# v16 + bias folded into the score fma in dilated edge tiles + GEMM K-loops: first iteration peeled with SrcC=0 instead of 128 accumulator-zeroing v_mov per tile
# baseline (speedup 1.0000x reference)
; #define PG8_STAGE(bufoff, gbase, voff) do { _Pragma("unroll") for (int _i = 0; _i < 2; ++_i) \
;         __builtin_amdgcn_global_load_lds((const unsigned*)((const char*)(gbase) + (voff)[_i]), (PG8_LAS unsigned*)(lds + (bufoff) + ldsw + _i * 8192), 16, 0, 0); } while (0)
; #define PG8_LDA(dst, b, h) do { _Pragma("unroll") for (int m = 0; m < 4; ++m) _Pragma("unroll") for (int k = 0; k < 2; ++k) dst[m][k] = *(const PG8_LAS bf16x8*)(lds + PG8_SA(b, h) + aoff + m * 2048 + k * 1024); } while (0)
; #define PG8_LDB(dst, b, h) do { _Pragma("unroll") for (int n = 0; n < 2; ++n) _Pragma("unroll") for (int k = 0; k < 2; ++k) dst[n][k] = *(const PG8_LAS bf16x8*)(lds + PG8_SB(b, h) + boff + n * 2048 + k * 1024); } while (0)
; #define PG8_MMA(ai, bj, At, Bt) do { __builtin_amdgcn_s_setprio(1); _Pragma("unroll") for (int m = 0; m < 4; ++m) _Pragma("unroll") for (int n = 0; n < 2; ++n) _Pragma("unroll") for (int k = 0; k < 2; ++k) \
;         acc[ai][bj][m][n] = __builtin_amdgcn_mfma_f32_16x16x32_bf16(Bt[n][k], At[m][k], acc[ai][bj][m][n], 0, 0, 0); __builtin_amdgcn_s_setprio(0); } while (0)
; #define PG8_WAIT_V(n) asm volatile("s_waitcnt vmcnt(" #n ")" ::: "memory")
; #define PG8_WAIT_L(n) asm volatile("s_waitcnt lgkmcnt(" #n ")" ::: "memory")
; #define PG8_BAR __builtin_amdgcn_s_barrier()
; #define PG8_SCHED __builtin_amdgcn_sched_barrier(0)
; template <class Epi, class Sched, bool ALIGN_EPI = false, bool SP2 = false>
; __device__ __forceinline__ void gemm_phase(PG8_LAS unsigned char* lds, const Gemm g, const Sched& S, const Epi& E) {
;     ...
;             PG8_LDB(B0, 0, 0); PG8_LDB(B1, 0, 1); PG8_SCHED; PG8_LDA(At, 0, 0); PG8_STAGE(PG8_SA(1, 1), a1 + hstep, voffA);
;             PG8_WAIT_V(8); PG8_WAIT_L(0); PG8_BAR; PG8_MMA(0, 0, At, B0); PG8_MMA(0, 1, At, B1); PG8_BAR; PG8_SCHED;
;             PG8_LDA(At, 0, 1); PG8_STAGE(PG8_SB(0, 0), b2, voffB); PG8_STAGE(PG8_SB(0, 1), b2 + hstep, voffB); PG8_STAGE(PG8_SA(0, 0), a2, voffA);
.LBB0_522:
	s_ashr_i32 s67, s66, 31
	s_lshl_b64 s[0:1], s[66:67], 19
	s_add_u32 s70, s13, s0
	s_addc_u32 s71, s80, s1
	s_and_b64 s[0:1], s[4:5], exec
	s_cselect_b32 s0, s71, s9
	s_cselect_b32 s1, s70, s8
	s_ashr_i32 s65, s64, 31
	s_lshl_b64 s[10:11], s[64:65], 19
	s_add_u32 s72, s14, s10
	s_addc_u32 s73, s15, s11
	s_and_b64 s[10:11], s[4:5], exec
	s_cselect_b32 s7, s73, s75
	s_cselect_b32 s10, s72, s74
	s_add_u32 s8, s8, 0x40080
	s_addc_u32 s9, s9, 0
	s_add_u32 s11, s74, 0x100
	v_mov_b32_e32 v0, 0
	s_addc_u32 s65, s75, 0
	s_mov_b32 s67, -2
	ds_read_b128 v[156:159], v171
	ds_read_b128 v[160:163], v171 offset:1024
	ds_read_b128 v[164:167], v171 offset:2048
	ds_read_b128 v[176:179], v171 offset:3072
	ds_read_b128 v[180:183], v172
	ds_read_b128 v[184:187], v172 offset:1024
	ds_read_b128 v[188:191], v172 offset:2048
	ds_read_b128 v[192:195], v172 offset:3072
	s_add_u32 s30, s8, 0xfffc0080
	s_addc_u32 s31, s9, -1
	s_cmp_eq_u32 s67, 12
	s_cselect_b32 s77, s0, s31
	s_cselect_b32 s76, s1, s30
	s_cselect_b32 s75, s7, s65
	s_cselect_b32 s74, s10, s11
	v_lshl_add_u64 v[168:169], s[8:9], 0, v[146:147]
	s_add_i32 m0, s69, 0xc000
	ds_read_b128 v[196:199], v173
	ds_read_b128 v[200:203], v173 offset:1024
	ds_read_b128 v[204:207], v173 offset:2048
	ds_read_b128 v[208:211], v173 offset:3072
	ds_read_b128 v[212:215], v173 offset:4096
	ds_read_b128 v[216:219], v173 offset:5120
	ds_read_b128 v[220:223], v173 offset:6144
	ds_read_b128 v[224:227], v173 offset:7168
	global_load_lds_dwordx4 v[168:169], off
	v_lshl_add_u64 v[168:169], s[8:9], 0, v[148:149]
	s_add_i32 m0, s69, 0xe000
	s_nop 0
	global_load_lds_dwordx4 v[168:169], off
	s_waitcnt vmcnt(8)
	s_waitcnt lgkmcnt(0)
	s_barrier
	s_setprio 1
	s_waitcnt lgkmcnt(0)
	v_mfma_f32_16x16x32_bf16 v[124:127], v[156:159], v[196:199], 0
	v_mfma_f32_16x16x32_bf16 v[120:123], v[164:167], v[196:199], 0
	v_mfma_f32_16x16x32_bf16 v[112:115], v[156:159], v[204:207], 0
	v_mfma_f32_16x16x32_bf16 v[104:107], v[164:167], v[204:207], 0
	v_mfma_f32_16x16x32_bf16 v[100:103], v[156:159], v[212:215], 0
	v_mfma_f32_16x16x32_bf16 v[92:95], v[164:167], v[212:215], 0
	v_mfma_f32_16x16x32_bf16 v[84:87], v[156:159], v[220:223], 0
	v_mfma_f32_16x16x32_bf16 v[76:79], v[164:167], v[220:223], 0
	v_mfma_f32_16x16x32_bf16 v[124:127], v[160:163], v[200:203], v[124:127]
	v_mfma_f32_16x16x32_bf16 v[120:123], v[176:179], v[200:203], v[120:123]
	v_mfma_f32_16x16x32_bf16 v[112:115], v[160:163], v[208:211], v[112:115]
	v_mfma_f32_16x16x32_bf16 v[104:107], v[176:179], v[208:211], v[104:107]
	v_mfma_f32_16x16x32_bf16 v[100:103], v[160:163], v[216:219], v[100:103]
	v_mfma_f32_16x16x32_bf16 v[92:95], v[176:179], v[216:219], v[92:95]
	v_mfma_f32_16x16x32_bf16 v[84:87], v[160:163], v[224:227], v[84:87]
	v_mfma_f32_16x16x32_bf16 v[76:79], v[176:179], v[224:227], v[76:79]
	s_setprio 0
	s_setprio 1
	v_mfma_f32_16x16x32_bf16 v[116:119], v[180:183], v[196:199], 0
	v_mfma_f32_16x16x32_bf16 v[108:111], v[188:191], v[196:199], 0
	v_mfma_f32_16x16x32_bf16 v[96:99], v[180:183], v[204:207], 0
	v_mfma_f32_16x16x32_bf16 v[88:91], v[188:191], v[204:207], 0
	v_mfma_f32_16x16x32_bf16 v[80:83], v[180:183], v[212:215], 0
	v_mfma_f32_16x16x32_bf16 v[72:75], v[188:191], v[212:215], 0
	v_mfma_f32_16x16x32_bf16 v[68:71], v[180:183], v[220:223], 0
	v_mfma_f32_16x16x32_bf16 v[64:67], v[188:191], v[220:223], 0
	v_mfma_f32_16x16x32_bf16 v[116:119], v[184:187], v[200:203], v[116:119]
	v_mfma_f32_16x16x32_bf16 v[108:111], v[192:195], v[200:203], v[108:111]
	v_mfma_f32_16x16x32_bf16 v[96:99], v[184:187], v[208:211], v[96:99]
	v_mfma_f32_16x16x32_bf16 v[88:91], v[192:195], v[208:211], v[88:91]
	v_mfma_f32_16x16x32_bf16 v[80:83], v[184:187], v[216:219], v[80:83]
	v_mfma_f32_16x16x32_bf16 v[72:75], v[192:195], v[216:219], v[72:75]
	v_mfma_f32_16x16x32_bf16 v[68:71], v[184:187], v[224:227], v[68:71]
	v_mfma_f32_16x16x32_bf16 v[64:67], v[192:195], v[224:227], v[64:67]
	s_setprio 0
	s_barrier
	s_add_i32 s30, s90, s81
	v_lshl_add_u64 v[168:169], s[74:75], 0, v[130:131]
	s_mov_b32 m0, s30
	ds_read_b128 v[196:199], v173 offset:16384
	ds_read_b128 v[200:203], v173 offset:17408
	ds_read_b128 v[204:207], v173 offset:18432
	ds_read_b128 v[208:211], v173 offset:19456
	ds_read_b128 v[212:215], v173 offset:20480
	ds_read_b128 v[216:219], v173 offset:21504
	ds_read_b128 v[220:223], v173 offset:22528
	ds_read_b128 v[224:227], v173 offset:23552
	global_load_lds_dwordx4 v[168:169], off
	s_add_i32 m0, s30, 0x2000
	s_add_u32 s30, s74, 0x40000
	v_lshl_add_u64 v[228:229], s[74:75], 0, v[134:135]
	s_addc_u32 s31, s75, 0
	s_add_i32 s94, s91, s81
	global_load_lds_dwordx4 v[228:229], off
	v_lshl_add_u64 v[230:231], s[30:31], 0, v[130:131]
	s_mov_b32 m0, s94
	v_lshl_add_u64 v[232:233], s[76:77], 0, v[132:133]
	global_load_lds_dwordx4 v[230:231], off
	v_lshl_add_u64 v[230:231], s[30:31], 0, v[134:135]
	s_add_i32 m0, s94, 0x2000
	s_nop 0
	global_load_lds_dwordx4 v[230:231], off
	v_lshl_add_u64 v[230:231], s[76:77], 0, v[128:129]
	s_mov_b32 m0, s69
	s_nop 0
	global_load_lds_dwordx4 v[230:231], off
	s_mov_b32 m0, s82
	s_nop 0
	global_load_lds_dwordx4 v[232:233], off
	s_waitcnt vmcnt(8)
	s_waitcnt lgkmcnt(0)
	s_barrier
; #define PG8_STAGE(bufoff, gbase, voff) do { _Pragma("unroll") for (int _i = 0; _i < 2; ++_i) \
;         __builtin_amdgcn_global_load_lds((const unsigned*)((const char*)(gbase) + (voff)[_i]), (PG8_LAS unsigned*)(lds + (bufoff) + ldsw + _i * 8192), 16, 0, 0); } while (0)
; #define PG8_LDA(dst, b, h) do { _Pragma("unroll") for (int m = 0; m < 4; ++m) _Pragma("unroll") for (int k = 0; k < 2; ++k) dst[m][k] = *(const PG8_LAS bf16x8*)(lds + PG8_SA(b, h) + aoff + m * 2048 + k * 1024); } while (0)
; #define PG8_LDB(dst, b, h) do { _Pragma("unroll") for (int n = 0; n < 2; ++n) _Pragma("unroll") for (int k = 0; k < 2; ++k) dst[n][k] = *(const PG8_LAS bf16x8*)(lds + PG8_SB(b, h) + boff + n * 2048 + k * 1024); } while (0)
; #define PG8_MMA(ai, bj, At, Bt) do { __builtin_amdgcn_s_setprio(1); _Pragma("unroll") for (int m = 0; m < 4; ++m) _Pragma("unroll") for (int n = 0; n < 2; ++n) _Pragma("unroll") for (int k = 0; k < 2; ++k) \
;         acc[ai][bj][m][n] = __builtin_amdgcn_mfma_f32_16x16x32_bf16(Bt[n][k], At[m][k], acc[ai][bj][m][n], 0, 0, 0); __builtin_amdgcn_s_setprio(0); } while (0)
; #define PG8_WAIT_V(n) asm volatile("s_waitcnt vmcnt(" #n ")" ::: "memory")
; #define PG8_WAIT_L(n) asm volatile("s_waitcnt lgkmcnt(" #n ")" ::: "memory")
; #define PG8_BAR __builtin_amdgcn_s_barrier()
; #define PG8_SCHED __builtin_amdgcn_sched_barrier(0)
; template <class Epi, class Sched, bool ALIGN_EPI = false, bool SP2 = false>
; __device__ __forceinline__ void gemm_phase(PG8_LAS unsigned char* lds, const Gemm g, const Sched& S, const Epi& E) {
;     ...
;             PG8_WAIT_V(8); PG8_WAIT_L(0); PG8_BAR; PG8_MMA(1, 0, At, B0); PG8_MMA(1, 1, At, B1); PG8_BAR; PG8_SCHED;
;             PG8_LDB(B0, 1, 0); PG8_LDB(B1, 1, 1); PG8_SCHED; PG8_LDA(At, 1, 0); PG8_STAGE(PG8_SA(0, 1), a2 + hstep, voffA);
;             PG8_WAIT_V(8); PG8_WAIT_L(0); PG8_BAR; PG8_MMA(0, 0, At, B0); PG8_MMA(0, 1, At, B1); PG8_BAR; PG8_SCHED;
	s_setprio 1
	s_waitcnt lgkmcnt(0)
	v_mfma_f32_16x16x32_bf16 v[60:63], v[156:159], v[196:199], 0
	v_mfma_f32_16x16x32_bf16 v[56:59], v[164:167], v[196:199], 0
	v_mfma_f32_16x16x32_bf16 v[48:51], v[156:159], v[204:207], 0
	v_mfma_f32_16x16x32_bf16 v[40:43], v[164:167], v[204:207], 0
	v_mfma_f32_16x16x32_bf16 v[36:39], v[156:159], v[212:215], 0
	v_mfma_f32_16x16x32_bf16 v[28:31], v[164:167], v[212:215], 0
	v_mfma_f32_16x16x32_bf16 v[20:23], v[156:159], v[220:223], 0
	v_mfma_f32_16x16x32_bf16 v[12:15], v[164:167], v[220:223], 0
	v_mfma_f32_16x16x32_bf16 v[60:63], v[160:163], v[200:203], v[60:63]
	v_mfma_f32_16x16x32_bf16 v[56:59], v[176:179], v[200:203], v[56:59]
	v_mfma_f32_16x16x32_bf16 v[48:51], v[160:163], v[208:211], v[48:51]
	v_mfma_f32_16x16x32_bf16 v[40:43], v[176:179], v[208:211], v[40:43]
	v_mfma_f32_16x16x32_bf16 v[36:39], v[160:163], v[216:219], v[36:39]
	v_mfma_f32_16x16x32_bf16 v[28:31], v[176:179], v[216:219], v[28:31]
	v_mfma_f32_16x16x32_bf16 v[20:23], v[160:163], v[224:227], v[20:23]
	v_mfma_f32_16x16x32_bf16 v[12:15], v[176:179], v[224:227], v[12:15]
	s_setprio 0
	s_setprio 1
	v_mfma_f32_16x16x32_bf16 v[52:55], v[180:183], v[196:199], 0
	v_mfma_f32_16x16x32_bf16 v[44:47], v[188:191], v[196:199], 0
	v_mfma_f32_16x16x32_bf16 v[32:35], v[180:183], v[204:207], 0
	v_mfma_f32_16x16x32_bf16 v[24:27], v[188:191], v[204:207], 0
	v_mfma_f32_16x16x32_bf16 v[16:19], v[180:183], v[212:215], 0
	v_mfma_f32_16x16x32_bf16 v[8:11], v[188:191], v[212:215], 0
	v_mfma_f32_16x16x32_bf16 v[4:7], v[180:183], v[220:223], 0
	v_mfma_f32_16x16x32_bf16 v[0:3], v[188:191], v[220:223], 0
	v_mfma_f32_16x16x32_bf16 v[52:55], v[184:187], v[200:203], v[52:55]
	v_mfma_f32_16x16x32_bf16 v[44:47], v[192:195], v[200:203], v[44:47]
	v_mfma_f32_16x16x32_bf16 v[32:35], v[184:187], v[208:211], v[32:35]
	v_mfma_f32_16x16x32_bf16 v[24:27], v[192:195], v[208:211], v[24:27]
	v_mfma_f32_16x16x32_bf16 v[16:19], v[184:187], v[216:219], v[16:19]
	v_mfma_f32_16x16x32_bf16 v[8:11], v[192:195], v[216:219], v[8:11]
	v_mfma_f32_16x16x32_bf16 v[4:7], v[184:187], v[224:227], v[4:7]
	v_mfma_f32_16x16x32_bf16 v[0:3], v[192:195], v[224:227], v[0:3]
	s_setprio 0
	s_barrier
	s_add_i32 s94, 0, 0x18000
	v_add_u32_e32 v136, s94, v170
	s_add_i32 s95, 0, 0x1c000
	ds_read_b128 v[156:159], v136
	ds_read_b128 v[160:163], v136 offset:1024
	ds_read_b128 v[164:167], v136 offset:2048
	ds_read_b128 v[176:179], v136 offset:3072
	v_add_u32_e32 v136, s95, v170
	ds_read_b128 v[180:183], v136
	ds_read_b128 v[184:187], v136 offset:1024
	ds_read_b128 v[188:191], v136 offset:2048
	ds_read_b128 v[192:195], v136 offset:3072
	s_add_u32 s30, s76, 0x40000
	s_addc_u32 s31, s77, 0
	s_mov_b32 m0, s83
	v_lshl_add_u64 v[234:235], s[30:31], 0, v[128:129]
	ds_read_b128 v[196:199], v173 offset:32768
	ds_read_b128 v[200:203], v173 offset:33792
	ds_read_b128 v[204:207], v173 offset:34816
	ds_read_b128 v[208:211], v173 offset:35840
	ds_read_b128 v[212:215], v173 offset:36864
	ds_read_b128 v[216:219], v173 offset:37888
	ds_read_b128 v[220:223], v173 offset:38912
	ds_read_b128 v[224:227], v173 offset:39936
	global_load_lds_dwordx4 v[234:235], off
	v_lshl_add_u64 v[234:235], s[30:31], 0, v[132:133]
	s_mov_b32 m0, s84
	s_nop 0
	global_load_lds_dwordx4 v[234:235], off
	s_waitcnt vmcnt(8)
	s_waitcnt lgkmcnt(0)
	s_barrier
	s_setprio 1
	s_waitcnt lgkmcnt(0)
	v_mfma_f32_16x16x32_bf16 v[124:127], v[156:159], v[196:199], v[124:127]
	v_mfma_f32_16x16x32_bf16 v[120:123], v[164:167], v[196:199], v[120:123]
	v_mfma_f32_16x16x32_bf16 v[112:115], v[156:159], v[204:207], v[112:115]
	v_mfma_f32_16x16x32_bf16 v[104:107], v[164:167], v[204:207], v[104:107]
	v_mfma_f32_16x16x32_bf16 v[100:103], v[156:159], v[212:215], v[100:103]
	v_mfma_f32_16x16x32_bf16 v[92:95], v[164:167], v[212:215], v[92:95]
	v_mfma_f32_16x16x32_bf16 v[84:87], v[156:159], v[220:223], v[84:87]
	v_mfma_f32_16x16x32_bf16 v[76:79], v[164:167], v[220:223], v[76:79]
	v_mfma_f32_16x16x32_bf16 v[124:127], v[160:163], v[200:203], v[124:127]
	v_mfma_f32_16x16x32_bf16 v[120:123], v[176:179], v[200:203], v[120:123]
	v_mfma_f32_16x16x32_bf16 v[112:115], v[160:163], v[208:211], v[112:115]
	v_mfma_f32_16x16x32_bf16 v[104:107], v[176:179], v[208:211], v[104:107]
	v_mfma_f32_16x16x32_bf16 v[100:103], v[160:163], v[216:219], v[100:103]
	v_mfma_f32_16x16x32_bf16 v[92:95], v[176:179], v[216:219], v[92:95]
	v_mfma_f32_16x16x32_bf16 v[84:87], v[160:163], v[224:227], v[84:87]
	v_mfma_f32_16x16x32_bf16 v[76:79], v[176:179], v[224:227], v[76:79]
	s_setprio 0
	s_setprio 1
	v_mfma_f32_16x16x32_bf16 v[116:119], v[180:183], v[196:199], v[116:119]
	v_mfma_f32_16x16x32_bf16 v[108:111], v[188:191], v[196:199], v[108:111]
	v_mfma_f32_16x16x32_bf16 v[96:99], v[180:183], v[204:207], v[96:99]
	v_mfma_f32_16x16x32_bf16 v[88:91], v[188:191], v[204:207], v[88:91]
	v_mfma_f32_16x16x32_bf16 v[80:83], v[180:183], v[212:215], v[80:83]
	v_mfma_f32_16x16x32_bf16 v[72:75], v[188:191], v[212:215], v[72:75]
	v_mfma_f32_16x16x32_bf16 v[68:71], v[180:183], v[220:223], v[68:71]
	v_mfma_f32_16x16x32_bf16 v[64:67], v[188:191], v[220:223], v[64:67]
	v_mfma_f32_16x16x32_bf16 v[116:119], v[184:187], v[200:203], v[116:119]
	v_mfma_f32_16x16x32_bf16 v[108:111], v[192:195], v[200:203], v[108:111]
	v_mfma_f32_16x16x32_bf16 v[96:99], v[184:187], v[208:211], v[96:99]
	v_mfma_f32_16x16x32_bf16 v[88:91], v[192:195], v[208:211], v[88:91]
	v_mfma_f32_16x16x32_bf16 v[80:83], v[184:187], v[216:219], v[80:83]
	v_mfma_f32_16x16x32_bf16 v[72:75], v[192:195], v[216:219], v[72:75]
	v_mfma_f32_16x16x32_bf16 v[68:71], v[184:187], v[224:227], v[68:71]
	v_mfma_f32_16x16x32_bf16 v[64:67], v[192:195], v[224:227], v[64:67]
	s_setprio 0
	s_barrier
; #define PG8_STAGE(bufoff, gbase, voff) do { _Pragma("unroll") for (int _i = 0; _i < 2; ++_i) \
;         __builtin_amdgcn_global_load_lds((const unsigned*)((const char*)(gbase) + (voff)[_i]), (PG8_LAS unsigned*)(lds + (bufoff) + ldsw + _i * 8192), 16, 0, 0); } while (0)
; #define PG8_LDA(dst, b, h) do { _Pragma("unroll") for (int m = 0; m < 4; ++m) _Pragma("unroll") for (int k = 0; k < 2; ++k) dst[m][k] = *(const PG8_LAS bf16x8*)(lds + PG8_SA(b, h) + aoff + m * 2048 + k * 1024); } while (0)
; #define PG8_MMA(ai, bj, At, Bt) do { __builtin_amdgcn_s_setprio(1); _Pragma("unroll") for (int m = 0; m < 4; ++m) _Pragma("unroll") for (int n = 0; n < 2; ++n) _Pragma("unroll") for (int k = 0; k < 2; ++k) \
;         acc[ai][bj][m][n] = __builtin_amdgcn_mfma_f32_16x16x32_bf16(Bt[n][k], At[m][k], acc[ai][bj][m][n], 0, 0, 0); __builtin_amdgcn_s_setprio(0); } while (0)
; #define PG8_WAIT_V(n) asm volatile("s_waitcnt vmcnt(" #n ")" ::: "memory")
; #define PG8_WAIT_L(n) asm volatile("s_waitcnt lgkmcnt(" #n ")" ::: "memory")
; #define PG8_BAR __builtin_amdgcn_s_barrier()
; #define PG8_SCHED __builtin_amdgcn_sched_barrier(0)
; template <class Epi, class Sched, bool ALIGN_EPI = false, bool SP2 = false>
; __device__ __forceinline__ void gemm_phase(PG8_LAS unsigned char* lds, const Gemm g, const Sched& S, const Epi& E) {
;     ...
;         for (int t = 0; t < nt; t += 2) {
;             const bool last = (t == nt - 2);
;     ...
;             PG8_LDA(At, 1, 1); PG8_STAGE(PG8_SB(1, 0), b3, voffB); PG8_STAGE(PG8_SB(1, 1), b3 + hstep, voffB); PG8_STAGE(PG8_SA(1, 0), a3, voffA);
;             PG8_WAIT_V(8); PG8_WAIT_L(0); PG8_BAR; PG8_MMA(1, 0, At, B0); PG8_MMA(1, 1, At, B1); PG8_BAR; PG8_SCHED;
	s_add_i32 s30, s94, s81
	v_lshl_add_u64 v[168:169], v[168:169], 0, s[46:47]
	s_mov_b32 m0, s30
	ds_read_b128 v[196:199], v173 offset:49152
	ds_read_b128 v[200:203], v173 offset:50176
	ds_read_b128 v[204:207], v173 offset:51200
	ds_read_b128 v[208:211], v173 offset:52224
	ds_read_b128 v[212:215], v173 offset:53248
	ds_read_b128 v[216:219], v173 offset:54272
	ds_read_b128 v[220:223], v173 offset:55296
	ds_read_b128 v[224:227], v173 offset:56320
	global_load_lds_dwordx4 v[168:169], off
	s_add_i32 m0, s30, 0x2000
	s_add_u32 s30, s74, 0x40080
	v_lshl_add_u64 v[168:169], v[228:229], 0, s[46:47]
	s_addc_u32 s31, s75, 0
	s_add_i32 s74, s95, s81
	global_load_lds_dwordx4 v[168:169], off
	v_lshl_add_u64 v[168:169], s[30:31], 0, v[130:131]
	s_mov_b32 m0, s74
	s_nop 0
	global_load_lds_dwordx4 v[168:169], off
	v_lshl_add_u64 v[168:169], s[30:31], 0, v[134:135]
	s_add_i32 m0, s74, 0x2000
	s_nop 0
	global_load_lds_dwordx4 v[168:169], off
	v_lshl_add_u64 v[168:169], v[230:231], 0, s[46:47]
	s_mov_b32 m0, s86
	s_nop 0
	global_load_lds_dwordx4 v[168:169], off
	v_lshl_add_u64 v[168:169], v[232:233], 0, s[46:47]
	s_mov_b32 m0, s87
	s_nop 0
	global_load_lds_dwordx4 v[168:169], off
	s_waitcnt vmcnt(8)
	s_waitcnt lgkmcnt(0)
	s_barrier
	s_setprio 1
	s_waitcnt lgkmcnt(0)
	v_mfma_f32_16x16x32_bf16 v[60:63], v[156:159], v[196:199], v[60:63]
	v_mfma_f32_16x16x32_bf16 v[56:59], v[164:167], v[196:199], v[56:59]
	v_mfma_f32_16x16x32_bf16 v[48:51], v[156:159], v[204:207], v[48:51]
	v_mfma_f32_16x16x32_bf16 v[40:43], v[164:167], v[204:207], v[40:43]
	v_mfma_f32_16x16x32_bf16 v[36:39], v[156:159], v[212:215], v[36:39]
	v_mfma_f32_16x16x32_bf16 v[28:31], v[164:167], v[212:215], v[28:31]
	v_mfma_f32_16x16x32_bf16 v[20:23], v[156:159], v[220:223], v[20:23]
	v_mfma_f32_16x16x32_bf16 v[12:15], v[164:167], v[220:223], v[12:15]
	v_mfma_f32_16x16x32_bf16 v[60:63], v[160:163], v[200:203], v[60:63]
	v_mfma_f32_16x16x32_bf16 v[56:59], v[176:179], v[200:203], v[56:59]
	v_mfma_f32_16x16x32_bf16 v[48:51], v[160:163], v[208:211], v[48:51]
	v_mfma_f32_16x16x32_bf16 v[40:43], v[176:179], v[208:211], v[40:43]
	v_mfma_f32_16x16x32_bf16 v[36:39], v[160:163], v[216:219], v[36:39]
	v_mfma_f32_16x16x32_bf16 v[28:31], v[176:179], v[216:219], v[28:31]
	v_mfma_f32_16x16x32_bf16 v[20:23], v[160:163], v[224:227], v[20:23]
	v_mfma_f32_16x16x32_bf16 v[12:15], v[176:179], v[224:227], v[12:15]
	s_setprio 0
	s_setprio 1
	v_mfma_f32_16x16x32_bf16 v[52:55], v[180:183], v[196:199], v[52:55]
	v_mfma_f32_16x16x32_bf16 v[44:47], v[188:191], v[196:199], v[44:47]
	v_mfma_f32_16x16x32_bf16 v[32:35], v[180:183], v[204:207], v[32:35]
	v_mfma_f32_16x16x32_bf16 v[24:27], v[188:191], v[204:207], v[24:27]
	v_mfma_f32_16x16x32_bf16 v[16:19], v[180:183], v[212:215], v[16:19]
	v_mfma_f32_16x16x32_bf16 v[8:11], v[188:191], v[212:215], v[8:11]
	v_mfma_f32_16x16x32_bf16 v[4:7], v[180:183], v[220:223], v[4:7]
	v_mfma_f32_16x16x32_bf16 v[0:3], v[188:191], v[220:223], v[0:3]
	v_mfma_f32_16x16x32_bf16 v[52:55], v[184:187], v[200:203], v[52:55]
	v_mfma_f32_16x16x32_bf16 v[44:47], v[192:195], v[200:203], v[44:47]
	v_mfma_f32_16x16x32_bf16 v[32:35], v[184:187], v[208:211], v[32:35]
	v_mfma_f32_16x16x32_bf16 v[24:27], v[192:195], v[208:211], v[24:27]
	v_mfma_f32_16x16x32_bf16 v[16:19], v[184:187], v[216:219], v[16:19]
	v_mfma_f32_16x16x32_bf16 v[8:11], v[192:195], v[216:219], v[8:11]
	v_mfma_f32_16x16x32_bf16 v[4:7], v[184:187], v[224:227], v[4:7]
	v_mfma_f32_16x16x32_bf16 v[0:3], v[192:195], v[224:227], v[0:3]
	s_setprio 0
	s_barrier
	s_add_i32 s67, s67, 2
	s_add_u32 s8, s8, 0x100
	s_addc_u32 s9, s9, 0
	s_add_u32 s11, s11, 0x100
	s_addc_u32 s65, s65, 0
	s_cmp_gt_u32 s67, 13
	s_cbranch_scc0 .LBB0_523
	s_branch .Lgx_g0

; #define PG8_BAR __builtin_amdgcn_s_barrier()
; template <class Epi, class Sched, bool ALIGN_EPI = false, bool SP2 = false>
; __device__ __forceinline__ void gemm_phase(PG8_LAS unsigned char* lds, const Gemm g, const Sched& S, const Epi& E) {
;     ...
;         if constexpr (ALIGN_EPI) { if (wr == 0) PG8_BAR; }
.Lgx_g0:
	s_and_b64 vcc, exec, s[48:49]
	s_cbranch_vccz .LBB0_526
	s_barrier

; #define PG8_STAGE(bufoff, gbase, voff) do { _Pragma("unroll") for (int _i = 0; _i < 2; ++_i) \
;         __builtin_amdgcn_global_load_lds((const unsigned*)((const char*)(gbase) + (voff)[_i]), (PG8_LAS unsigned*)(lds + (bufoff) + ldsw + _i * 8192), 16, 0, 0); } while (0)
; #define PG8_LDA(dst, b, h) do { _Pragma("unroll") for (int m = 0; m < 4; ++m) _Pragma("unroll") for (int k = 0; k < 2; ++k) dst[m][k] = *(const PG8_LAS bf16x8*)(lds + PG8_SA(b, h) + aoff + m * 2048 + k * 1024); } while (0)
; #define PG8_LDB(dst, b, h) do { _Pragma("unroll") for (int n = 0; n < 2; ++n) _Pragma("unroll") for (int k = 0; k < 2; ++k) dst[n][k] = *(const PG8_LAS bf16x8*)(lds + PG8_SB(b, h) + boff + n * 2048 + k * 1024); } while (0)
; #define PG8_MMA(ai, bj, At, Bt) do { __builtin_amdgcn_s_setprio(1); _Pragma("unroll") for (int m = 0; m < 4; ++m) _Pragma("unroll") for (int n = 0; n < 2; ++n) _Pragma("unroll") for (int k = 0; k < 2; ++k) \
;         acc[ai][bj][m][n] = __builtin_amdgcn_mfma_f32_16x16x32_bf16(Bt[n][k], At[m][k], acc[ai][bj][m][n], 0, 0, 0); __builtin_amdgcn_s_setprio(0); } while (0)
; #define PG8_WAIT_V(n) asm volatile("s_waitcnt vmcnt(" #n ")" ::: "memory")
; #define PG8_WAIT_L(n) asm volatile("s_waitcnt lgkmcnt(" #n ")" ::: "memory")
; #define PG8_BAR __builtin_amdgcn_s_barrier()
; #define PG8_SCHED __builtin_amdgcn_sched_barrier(0)
; template <class Epi, class Sched, bool ALIGN_EPI = false, bool SP2 = false>
; __device__ __forceinline__ void gemm_phase(PG8_LAS unsigned char* lds, const Gemm g, const Sched& S, const Epi& E) {
;     ...
;             const bool last = (t == nt - 2);
;             const char* a1 = cA + (size_t)(t + 1) * kstep;
;             const char* a2 = last ? nA : cA + (size_t)(t + 2) * kstep; const char* b2 = last ? nB : cB + (size_t)(t + 2) * kstep;
;             const char* a3 = a2 + kstep; const char* b3 = b2 + kstep;
;             if (last && has_next) S.a_ready(nxt);
;             if constexpr (SP2) {
;             PG8_LDB(B0, 0, 0); PG8_LDB(B1, 0, 1); PG8_SCHED; PG8_LDA(At, 0, 0); PG8_STAGE(PG8_SA(1, 1), a1 + hstep, voffA);
;             PG8_WAIT_V(8); PG8_WAIT_L(0); PG8_BAR; PG8_MMA(0, 0, At, B0); PG8_MMA(0, 1, At, B1); PG8_BAR; PG8_SCHED;
;             PG8_LDA(At, 0, 1); PG8_STAGE(PG8_SB(0, 0), b2, voffB); PG8_STAGE(PG8_SB(0, 1), b2 + hstep, voffB); PG8_STAGE(PG8_SA(0, 0), a2, voffA);
.LBB0_750:
	s_ashr_i32 s45, s44, 31
	s_lshl_b64 s[30:31], s[44:45], 19
	s_add_u32 s46, s62, s30
	s_addc_u32 s47, s63, s31
	s_and_b64 s[30:31], s[38:39], exec
	s_cselect_b32 s45, s47, s53
	s_cselect_b32 s77, s46, s52
	s_ashr_i32 s43, s42, 31
	s_lshl_b64 s[30:31], s[42:43], 19
	s_add_u32 s48, s10, s30
	s_addc_u32 s49, s11, s31
	s_and_b64 s[30:31], s[38:39], exec
	s_cselect_b32 s43, s49, s59
	s_cselect_b32 s80, s48, s58
	s_add_u32 s52, s52, 0x40080
	s_addc_u32 s53, s53, 0
	s_add_u32 s81, s58, 0x100
	v_mov_b32_e32 v0, 0
	s_addc_u32 s82, s59, 0
	s_mov_b32 s83, -2
	ds_read_b128 v[148:151], v145
	s_waitcnt lgkmcnt(0)
	ds_read_b128 v[152:155], v145 offset:1024
	ds_read_b128 v[156:159], v145 offset:2048
	ds_read_b128 v[160:163], v145 offset:3072
	ds_read_b128 v[164:167], v146
	ds_read_b128 v[168:171], v146 offset:1024
	ds_read_b128 v[172:175], v146 offset:2048
	ds_read_b128 v[176:179], v146 offset:3072
	s_add_u32 s30, s52, 0xfffc0080
	s_addc_u32 s31, s53, -1
	s_cmp_eq_u32 s83, 12
	s_cselect_b32 s61, s45, s31
	s_cselect_b32 s60, s77, s30
	s_cselect_b32 s59, s43, s82
	s_cselect_b32 s58, s80, s81
	v_lshl_add_u64 v[140:141], s[52:53], 0, v[136:137]
	s_add_i32 m0, s51, 0xc000
	ds_read_b128 v[180:183], v147
	ds_read_b128 v[184:187], v147 offset:1024
	ds_read_b128 v[188:191], v147 offset:2048
	ds_read_b128 v[192:195], v147 offset:3072
	ds_read_b128 v[196:199], v147 offset:4096
	ds_read_b128 v[200:203], v147 offset:5120
	ds_read_b128 v[204:207], v147 offset:6144
	ds_read_b128 v[208:211], v147 offset:7168
	global_load_lds_dwordx4 v[140:141], off
	v_lshl_add_u64 v[140:141], s[52:53], 0, v[138:139]
	s_add_i32 m0, s51, 0xe000
	s_nop 0
	global_load_lds_dwordx4 v[140:141], off
	s_waitcnt vmcnt(8)
	s_waitcnt lgkmcnt(0)
	s_barrier
	s_setprio 1
	s_waitcnt lgkmcnt(0)
	v_mfma_f32_16x16x32_bf16 v[124:127], v[148:151], v[180:183], 0
	v_mfma_f32_16x16x32_bf16 v[120:123], v[156:159], v[180:183], 0
	v_mfma_f32_16x16x32_bf16 v[116:119], v[148:151], v[188:191], 0
	v_mfma_f32_16x16x32_bf16 v[108:111], v[156:159], v[188:191], 0
	v_mfma_f32_16x16x32_bf16 v[100:103], v[148:151], v[196:199], 0
	v_mfma_f32_16x16x32_bf16 v[92:95], v[156:159], v[196:199], 0
	v_mfma_f32_16x16x32_bf16 v[84:87], v[148:151], v[204:207], 0
	v_mfma_f32_16x16x32_bf16 v[76:79], v[156:159], v[204:207], 0
	v_mfma_f32_16x16x32_bf16 v[124:127], v[152:155], v[184:187], v[124:127]
	v_mfma_f32_16x16x32_bf16 v[120:123], v[160:163], v[184:187], v[120:123]
	v_mfma_f32_16x16x32_bf16 v[116:119], v[152:155], v[192:195], v[116:119]
	v_mfma_f32_16x16x32_bf16 v[108:111], v[160:163], v[192:195], v[108:111]
	v_mfma_f32_16x16x32_bf16 v[100:103], v[152:155], v[200:203], v[100:103]
	v_mfma_f32_16x16x32_bf16 v[92:95], v[160:163], v[200:203], v[92:95]
	v_mfma_f32_16x16x32_bf16 v[84:87], v[152:155], v[208:211], v[84:87]
	v_mfma_f32_16x16x32_bf16 v[76:79], v[160:163], v[208:211], v[76:79]
	s_setprio 0
	s_setprio 1
	v_mfma_f32_16x16x32_bf16 v[112:115], v[164:167], v[180:183], 0
	v_mfma_f32_16x16x32_bf16 v[104:107], v[172:175], v[180:183], 0
	v_mfma_f32_16x16x32_bf16 v[96:99], v[164:167], v[188:191], 0
	v_mfma_f32_16x16x32_bf16 v[88:91], v[172:175], v[188:191], 0
	v_mfma_f32_16x16x32_bf16 v[80:83], v[164:167], v[196:199], 0
	v_mfma_f32_16x16x32_bf16 v[72:75], v[172:175], v[196:199], 0
	v_mfma_f32_16x16x32_bf16 v[68:71], v[164:167], v[204:207], 0
	v_mfma_f32_16x16x32_bf16 v[64:67], v[172:175], v[204:207], 0
	v_mfma_f32_16x16x32_bf16 v[112:115], v[168:171], v[184:187], v[112:115]
	v_mfma_f32_16x16x32_bf16 v[104:107], v[176:179], v[184:187], v[104:107]
	v_mfma_f32_16x16x32_bf16 v[96:99], v[168:171], v[192:195], v[96:99]
	v_mfma_f32_16x16x32_bf16 v[88:91], v[176:179], v[192:195], v[88:91]
	v_mfma_f32_16x16x32_bf16 v[80:83], v[168:171], v[200:203], v[80:83]
	v_mfma_f32_16x16x32_bf16 v[72:75], v[176:179], v[200:203], v[72:75]
	v_mfma_f32_16x16x32_bf16 v[68:71], v[168:171], v[208:211], v[68:71]
	v_mfma_f32_16x16x32_bf16 v[64:67], v[176:179], v[208:211], v[64:67]
	s_setprio 0
	s_barrier
	s_add_i32 s30, s70, s1
	v_lshl_add_u64 v[140:141], s[58:59], 0, v[130:131]
	s_mov_b32 m0, s30
	ds_read_b128 v[180:183], v147 offset:16384
	ds_read_b128 v[184:187], v147 offset:17408
	ds_read_b128 v[188:191], v147 offset:18432
	ds_read_b128 v[192:195], v147 offset:19456
	ds_read_b128 v[196:199], v147 offset:20480
	ds_read_b128 v[200:203], v147 offset:21504
	ds_read_b128 v[204:207], v147 offset:22528
	ds_read_b128 v[208:211], v147 offset:23552
	global_load_lds_dwordx4 v[140:141], off
	s_add_i32 m0, s30, 0x2000
	s_add_u32 s30, s58, 0x40000
	v_lshl_add_u64 v[212:213], s[58:59], 0, v[134:135]
	s_addc_u32 s31, s59, 0
	s_add_i32 s84, s71, s1
	global_load_lds_dwordx4 v[212:213], off
	v_lshl_add_u64 v[214:215], s[30:31], 0, v[130:131]
	s_mov_b32 m0, s84
	v_lshl_add_u64 v[216:217], s[60:61], 0, v[132:133]
	global_load_lds_dwordx4 v[214:215], off
	v_lshl_add_u64 v[214:215], s[30:31], 0, v[134:135]
	s_add_i32 m0, s84, 0x2000
	s_nop 0
	global_load_lds_dwordx4 v[214:215], off
	v_lshl_add_u64 v[214:215], s[60:61], 0, v[128:129]
	s_mov_b32 m0, s51
	s_nop 0
	global_load_lds_dwordx4 v[214:215], off
	s_mov_b32 m0, s64
	s_nop 0
	global_load_lds_dwordx4 v[216:217], off
	s_waitcnt vmcnt(8)
	s_waitcnt lgkmcnt(0)
	s_barrier
; #define PG8_STAGE(bufoff, gbase, voff) do { _Pragma("unroll") for (int _i = 0; _i < 2; ++_i) \
;         __builtin_amdgcn_global_load_lds((const unsigned*)((const char*)(gbase) + (voff)[_i]), (PG8_LAS unsigned*)(lds + (bufoff) + ldsw + _i * 8192), 16, 0, 0); } while (0)
; #define PG8_LDA(dst, b, h) do { _Pragma("unroll") for (int m = 0; m < 4; ++m) _Pragma("unroll") for (int k = 0; k < 2; ++k) dst[m][k] = *(const PG8_LAS bf16x8*)(lds + PG8_SA(b, h) + aoff + m * 2048 + k * 1024); } while (0)
; #define PG8_LDB(dst, b, h) do { _Pragma("unroll") for (int n = 0; n < 2; ++n) _Pragma("unroll") for (int k = 0; k < 2; ++k) dst[n][k] = *(const PG8_LAS bf16x8*)(lds + PG8_SB(b, h) + boff + n * 2048 + k * 1024); } while (0)
; #define PG8_MMA(ai, bj, At, Bt) do { __builtin_amdgcn_s_setprio(1); _Pragma("unroll") for (int m = 0; m < 4; ++m) _Pragma("unroll") for (int n = 0; n < 2; ++n) _Pragma("unroll") for (int k = 0; k < 2; ++k) \
;         acc[ai][bj][m][n] = __builtin_amdgcn_mfma_f32_16x16x32_bf16(Bt[n][k], At[m][k], acc[ai][bj][m][n], 0, 0, 0); __builtin_amdgcn_s_setprio(0); } while (0)
; #define PG8_WAIT_V(n) asm volatile("s_waitcnt vmcnt(" #n ")" ::: "memory")
; #define PG8_WAIT_L(n) asm volatile("s_waitcnt lgkmcnt(" #n ")" ::: "memory")
; #define PG8_BAR __builtin_amdgcn_s_barrier()
; #define PG8_SCHED __builtin_amdgcn_sched_barrier(0)
; template <class Epi, class Sched, bool ALIGN_EPI = false, bool SP2 = false>
; __device__ __forceinline__ void gemm_phase(PG8_LAS unsigned char* lds, const Gemm g, const Sched& S, const Epi& E) {
;     ...
;             PG8_WAIT_V(8); PG8_WAIT_L(0); PG8_BAR; PG8_MMA(1, 0, At, B0); PG8_MMA(1, 1, At, B1); PG8_BAR; PG8_SCHED;
;             PG8_LDB(B0, 1, 0); PG8_LDB(B1, 1, 1); PG8_SCHED; PG8_LDA(At, 1, 0); PG8_STAGE(PG8_SA(0, 1), a2 + hstep, voffA);
;             PG8_WAIT_V(8); PG8_WAIT_L(0); PG8_BAR; PG8_MMA(0, 0, At, B0); PG8_MMA(0, 1, At, B1); PG8_BAR; PG8_SCHED;
	s_setprio 1
	s_waitcnt lgkmcnt(0)
	v_mfma_f32_16x16x32_bf16 v[60:63], v[148:151], v[180:183], 0
	v_mfma_f32_16x16x32_bf16 v[56:59], v[156:159], v[180:183], 0
	v_mfma_f32_16x16x32_bf16 v[52:55], v[148:151], v[188:191], 0
	v_mfma_f32_16x16x32_bf16 v[44:47], v[156:159], v[188:191], 0
	v_mfma_f32_16x16x32_bf16 v[36:39], v[148:151], v[196:199], 0
	v_mfma_f32_16x16x32_bf16 v[28:31], v[156:159], v[196:199], 0
	v_mfma_f32_16x16x32_bf16 v[20:23], v[148:151], v[204:207], 0
	v_mfma_f32_16x16x32_bf16 v[12:15], v[156:159], v[204:207], 0
	v_mfma_f32_16x16x32_bf16 v[60:63], v[152:155], v[184:187], v[60:63]
	v_mfma_f32_16x16x32_bf16 v[56:59], v[160:163], v[184:187], v[56:59]
	v_mfma_f32_16x16x32_bf16 v[52:55], v[152:155], v[192:195], v[52:55]
	v_mfma_f32_16x16x32_bf16 v[44:47], v[160:163], v[192:195], v[44:47]
	v_mfma_f32_16x16x32_bf16 v[36:39], v[152:155], v[200:203], v[36:39]
	v_mfma_f32_16x16x32_bf16 v[28:31], v[160:163], v[200:203], v[28:31]
	v_mfma_f32_16x16x32_bf16 v[20:23], v[152:155], v[208:211], v[20:23]
	v_mfma_f32_16x16x32_bf16 v[12:15], v[160:163], v[208:211], v[12:15]
	s_setprio 0
	s_setprio 1
	v_mfma_f32_16x16x32_bf16 v[48:51], v[164:167], v[180:183], 0
	v_mfma_f32_16x16x32_bf16 v[40:43], v[172:175], v[180:183], 0
	v_mfma_f32_16x16x32_bf16 v[32:35], v[164:167], v[188:191], 0
	v_mfma_f32_16x16x32_bf16 v[24:27], v[172:175], v[188:191], 0
	v_mfma_f32_16x16x32_bf16 v[16:19], v[164:167], v[196:199], 0
	v_mfma_f32_16x16x32_bf16 v[8:11], v[172:175], v[196:199], 0
	v_mfma_f32_16x16x32_bf16 v[4:7], v[164:167], v[204:207], 0
	v_mfma_f32_16x16x32_bf16 v[0:3], v[172:175], v[204:207], 0
	v_mfma_f32_16x16x32_bf16 v[48:51], v[168:171], v[184:187], v[48:51]
	v_mfma_f32_16x16x32_bf16 v[40:43], v[176:179], v[184:187], v[40:43]
	v_mfma_f32_16x16x32_bf16 v[32:35], v[168:171], v[192:195], v[32:35]
	v_mfma_f32_16x16x32_bf16 v[24:27], v[176:179], v[192:195], v[24:27]
	v_mfma_f32_16x16x32_bf16 v[16:19], v[168:171], v[200:203], v[16:19]
	v_mfma_f32_16x16x32_bf16 v[8:11], v[176:179], v[200:203], v[8:11]
	v_mfma_f32_16x16x32_bf16 v[4:7], v[168:171], v[208:211], v[4:7]
	v_mfma_f32_16x16x32_bf16 v[0:3], v[176:179], v[208:211], v[0:3]
	s_setprio 0
	s_barrier
	s_add_i32 s84, 0, 0x18000
	s_add_i32 s85, 0, 0x1c000
	v_add_u32_e32 v160, s84, v143
	v_add_u32_e32 v176, s85, v143
	ds_read_b128 v[148:151], v160
	ds_read_b128 v[152:155], v160 offset:1024
	ds_read_b128 v[156:159], v160 offset:2048
	ds_read_b128 v[160:163], v160 offset:3072
	ds_read_b128 v[164:167], v176
	ds_read_b128 v[168:171], v176 offset:1024
	ds_read_b128 v[172:175], v176 offset:2048
	ds_read_b128 v[176:179], v176 offset:3072
	s_add_u32 s30, s60, 0x40000
	s_addc_u32 s31, s61, 0
	s_mov_b32 m0, s65
	v_lshl_add_u64 v[218:219], s[30:31], 0, v[128:129]
	ds_read_b128 v[180:183], v147 offset:32768
	ds_read_b128 v[184:187], v147 offset:33792
	ds_read_b128 v[188:191], v147 offset:34816
	ds_read_b128 v[192:195], v147 offset:35840
	ds_read_b128 v[196:199], v147 offset:36864
	ds_read_b128 v[200:203], v147 offset:37888
	ds_read_b128 v[204:207], v147 offset:38912
	ds_read_b128 v[208:211], v147 offset:39936
	global_load_lds_dwordx4 v[218:219], off
	v_lshl_add_u64 v[218:219], s[30:31], 0, v[132:133]
	s_mov_b32 m0, s66
	s_nop 0
	global_load_lds_dwordx4 v[218:219], off
	s_waitcnt vmcnt(8)
	s_waitcnt lgkmcnt(0)
	s_barrier
	s_setprio 1
	s_waitcnt lgkmcnt(0)
	v_mfma_f32_16x16x32_bf16 v[124:127], v[148:151], v[180:183], v[124:127]
	v_mfma_f32_16x16x32_bf16 v[120:123], v[156:159], v[180:183], v[120:123]
	v_mfma_f32_16x16x32_bf16 v[116:119], v[148:151], v[188:191], v[116:119]
	v_mfma_f32_16x16x32_bf16 v[108:111], v[156:159], v[188:191], v[108:111]
	v_mfma_f32_16x16x32_bf16 v[100:103], v[148:151], v[196:199], v[100:103]
	v_mfma_f32_16x16x32_bf16 v[92:95], v[156:159], v[196:199], v[92:95]
	v_mfma_f32_16x16x32_bf16 v[84:87], v[148:151], v[204:207], v[84:87]
	v_mfma_f32_16x16x32_bf16 v[76:79], v[156:159], v[204:207], v[76:79]
	v_mfma_f32_16x16x32_bf16 v[124:127], v[152:155], v[184:187], v[124:127]
	v_mfma_f32_16x16x32_bf16 v[120:123], v[160:163], v[184:187], v[120:123]
	v_mfma_f32_16x16x32_bf16 v[116:119], v[152:155], v[192:195], v[116:119]
	v_mfma_f32_16x16x32_bf16 v[108:111], v[160:163], v[192:195], v[108:111]
	v_mfma_f32_16x16x32_bf16 v[100:103], v[152:155], v[200:203], v[100:103]
	v_mfma_f32_16x16x32_bf16 v[92:95], v[160:163], v[200:203], v[92:95]
	v_mfma_f32_16x16x32_bf16 v[84:87], v[152:155], v[208:211], v[84:87]
	v_mfma_f32_16x16x32_bf16 v[76:79], v[160:163], v[208:211], v[76:79]
	s_setprio 0
	s_setprio 1
	v_mfma_f32_16x16x32_bf16 v[112:115], v[164:167], v[180:183], v[112:115]
	v_mfma_f32_16x16x32_bf16 v[104:107], v[172:175], v[180:183], v[104:107]
	v_mfma_f32_16x16x32_bf16 v[96:99], v[164:167], v[188:191], v[96:99]
	v_mfma_f32_16x16x32_bf16 v[88:91], v[172:175], v[188:191], v[88:91]
	v_mfma_f32_16x16x32_bf16 v[80:83], v[164:167], v[196:199], v[80:83]
	v_mfma_f32_16x16x32_bf16 v[72:75], v[172:175], v[196:199], v[72:75]
	v_mfma_f32_16x16x32_bf16 v[68:71], v[164:167], v[204:207], v[68:71]
	v_mfma_f32_16x16x32_bf16 v[64:67], v[172:175], v[204:207], v[64:67]
	v_mfma_f32_16x16x32_bf16 v[112:115], v[168:171], v[184:187], v[112:115]
	v_mfma_f32_16x16x32_bf16 v[104:107], v[176:179], v[184:187], v[104:107]
	v_mfma_f32_16x16x32_bf16 v[96:99], v[168:171], v[192:195], v[96:99]
	v_mfma_f32_16x16x32_bf16 v[88:91], v[176:179], v[192:195], v[88:91]
	v_mfma_f32_16x16x32_bf16 v[80:83], v[168:171], v[200:203], v[80:83]
	v_mfma_f32_16x16x32_bf16 v[72:75], v[176:179], v[200:203], v[72:75]
	v_mfma_f32_16x16x32_bf16 v[68:71], v[168:171], v[208:211], v[68:71]
	v_mfma_f32_16x16x32_bf16 v[64:67], v[176:179], v[208:211], v[64:67]
	s_setprio 0
	s_barrier
; #define PG8_STAGE(bufoff, gbase, voff) do { _Pragma("unroll") for (int _i = 0; _i < 2; ++_i) \
;         __builtin_amdgcn_global_load_lds((const unsigned*)((const char*)(gbase) + (voff)[_i]), (PG8_LAS unsigned*)(lds + (bufoff) + ldsw + _i * 8192), 16, 0, 0); } while (0)
; #define PG8_LDA(dst, b, h) do { _Pragma("unroll") for (int m = 0; m < 4; ++m) _Pragma("unroll") for (int k = 0; k < 2; ++k) dst[m][k] = *(const PG8_LAS bf16x8*)(lds + PG8_SA(b, h) + aoff + m * 2048 + k * 1024); } while (0)
; #define PG8_MMA(ai, bj, At, Bt) do { __builtin_amdgcn_s_setprio(1); _Pragma("unroll") for (int m = 0; m < 4; ++m) _Pragma("unroll") for (int n = 0; n < 2; ++n) _Pragma("unroll") for (int k = 0; k < 2; ++k) \
;         acc[ai][bj][m][n] = __builtin_amdgcn_mfma_f32_16x16x32_bf16(Bt[n][k], At[m][k], acc[ai][bj][m][n], 0, 0, 0); __builtin_amdgcn_s_setprio(0); } while (0)
; #define PG8_WAIT_V(n) asm volatile("s_waitcnt vmcnt(" #n ")" ::: "memory")
; #define PG8_WAIT_L(n) asm volatile("s_waitcnt lgkmcnt(" #n ")" ::: "memory")
; #define PG8_BAR __builtin_amdgcn_s_barrier()
; #define PG8_SCHED __builtin_amdgcn_sched_barrier(0)
; template <class Epi, class Sched, bool ALIGN_EPI = false, bool SP2 = false>
; __device__ __forceinline__ void gemm_phase(PG8_LAS unsigned char* lds, const Gemm g, const Sched& S, const Epi& E) {
;     ...
;         for (int t = 0; t < nt; t += 2) {
;             const bool last = (t == nt - 2);
;     ...
;             PG8_LDA(At, 1, 1); PG8_STAGE(PG8_SB(1, 0), b3, voffB); PG8_STAGE(PG8_SB(1, 1), b3 + hstep, voffB); PG8_STAGE(PG8_SA(1, 0), a3, voffA);
;             PG8_WAIT_V(8); PG8_WAIT_L(0); PG8_BAR; PG8_MMA(1, 0, At, B0); PG8_MMA(1, 1, At, B1); PG8_BAR; PG8_SCHED;
	s_add_i32 s30, s84, s1
	v_lshl_add_u64 v[140:141], v[140:141], 0, s[8:9]
	s_mov_b32 m0, s30
	ds_read_b128 v[180:183], v147 offset:49152
	ds_read_b128 v[184:187], v147 offset:50176
	ds_read_b128 v[188:191], v147 offset:51200
	ds_read_b128 v[192:195], v147 offset:52224
	ds_read_b128 v[196:199], v147 offset:53248
	ds_read_b128 v[200:203], v147 offset:54272
	ds_read_b128 v[204:207], v147 offset:55296
	ds_read_b128 v[208:211], v147 offset:56320
	global_load_lds_dwordx4 v[140:141], off
	s_add_i32 m0, s30, 0x2000
	s_add_u32 s30, s58, 0x40080
	v_lshl_add_u64 v[140:141], v[212:213], 0, s[8:9]
	s_addc_u32 s31, s59, 0
	s_add_i32 s58, s85, s1
	global_load_lds_dwordx4 v[140:141], off
	v_lshl_add_u64 v[140:141], s[30:31], 0, v[130:131]
	s_mov_b32 m0, s58
	s_nop 0
	global_load_lds_dwordx4 v[140:141], off
	v_lshl_add_u64 v[140:141], s[30:31], 0, v[134:135]
	s_add_i32 m0, s58, 0x2000
	s_nop 0
	global_load_lds_dwordx4 v[140:141], off
	v_lshl_add_u64 v[140:141], v[214:215], 0, s[8:9]
	s_mov_b32 m0, s68
	s_nop 0
	global_load_lds_dwordx4 v[140:141], off
	v_lshl_add_u64 v[140:141], v[216:217], 0, s[8:9]
	s_mov_b32 m0, s69
	s_nop 0
	global_load_lds_dwordx4 v[140:141], off
	s_waitcnt vmcnt(8)
	s_waitcnt lgkmcnt(0)
	s_barrier
	s_setprio 1
	s_waitcnt lgkmcnt(0)
	v_mfma_f32_16x16x32_bf16 v[60:63], v[148:151], v[180:183], v[60:63]
	v_mfma_f32_16x16x32_bf16 v[56:59], v[156:159], v[180:183], v[56:59]
	v_mfma_f32_16x16x32_bf16 v[52:55], v[148:151], v[188:191], v[52:55]
	v_mfma_f32_16x16x32_bf16 v[44:47], v[156:159], v[188:191], v[44:47]
	v_mfma_f32_16x16x32_bf16 v[36:39], v[148:151], v[196:199], v[36:39]
	v_mfma_f32_16x16x32_bf16 v[28:31], v[156:159], v[196:199], v[28:31]
	v_mfma_f32_16x16x32_bf16 v[20:23], v[148:151], v[204:207], v[20:23]
	v_mfma_f32_16x16x32_bf16 v[12:15], v[156:159], v[204:207], v[12:15]
	v_mfma_f32_16x16x32_bf16 v[60:63], v[152:155], v[184:187], v[60:63]
	v_mfma_f32_16x16x32_bf16 v[56:59], v[160:163], v[184:187], v[56:59]
	v_mfma_f32_16x16x32_bf16 v[52:55], v[152:155], v[192:195], v[52:55]
	v_mfma_f32_16x16x32_bf16 v[44:47], v[160:163], v[192:195], v[44:47]
	v_mfma_f32_16x16x32_bf16 v[36:39], v[152:155], v[200:203], v[36:39]
	v_mfma_f32_16x16x32_bf16 v[28:31], v[160:163], v[200:203], v[28:31]
	v_mfma_f32_16x16x32_bf16 v[20:23], v[152:155], v[208:211], v[20:23]
	v_mfma_f32_16x16x32_bf16 v[12:15], v[160:163], v[208:211], v[12:15]
	s_setprio 0
	s_setprio 1
	v_mfma_f32_16x16x32_bf16 v[48:51], v[164:167], v[180:183], v[48:51]
	v_mfma_f32_16x16x32_bf16 v[40:43], v[172:175], v[180:183], v[40:43]
	v_mfma_f32_16x16x32_bf16 v[32:35], v[164:167], v[188:191], v[32:35]
	v_mfma_f32_16x16x32_bf16 v[24:27], v[172:175], v[188:191], v[24:27]
	v_mfma_f32_16x16x32_bf16 v[16:19], v[164:167], v[196:199], v[16:19]
	v_mfma_f32_16x16x32_bf16 v[8:11], v[172:175], v[196:199], v[8:11]
	v_mfma_f32_16x16x32_bf16 v[4:7], v[164:167], v[204:207], v[4:7]
	v_mfma_f32_16x16x32_bf16 v[0:3], v[172:175], v[204:207], v[0:3]
	v_mfma_f32_16x16x32_bf16 v[48:51], v[168:171], v[184:187], v[48:51]
	v_mfma_f32_16x16x32_bf16 v[40:43], v[176:179], v[184:187], v[40:43]
	v_mfma_f32_16x16x32_bf16 v[32:35], v[168:171], v[192:195], v[32:35]
	v_mfma_f32_16x16x32_bf16 v[24:27], v[176:179], v[192:195], v[24:27]
	v_mfma_f32_16x16x32_bf16 v[16:19], v[168:171], v[200:203], v[16:19]
	v_mfma_f32_16x16x32_bf16 v[8:11], v[176:179], v[200:203], v[8:11]
	v_mfma_f32_16x16x32_bf16 v[4:7], v[168:171], v[208:211], v[4:7]
	v_mfma_f32_16x16x32_bf16 v[0:3], v[176:179], v[208:211], v[0:3]
	s_setprio 0
	s_barrier
	s_add_i32 s83, s83, 2
	s_add_u32 s52, s52, 0x100
	s_addc_u32 s53, s53, 0
	s_add_u32 s81, s81, 0x100
	s_addc_u32 s82, s82, 0
	s_cmp_gt_u32 s83, 13
	s_cbranch_scc0 .LBB0_751
	s_branch .Lgx_g1

; #define PG8_BAR __builtin_amdgcn_s_barrier()
; template <class Epi, class Sched, bool ALIGN_EPI = false, bool SP2 = false>
; __device__ __forceinline__ void gemm_phase(PG8_LAS unsigned char* lds, const Gemm g, const Sched& S, const Epi& E) {
;     ...
;         if constexpr (ALIGN_EPI) { if (wr == 0) PG8_BAR; }
.Lgx_g1:
	s_and_b64 vcc, exec, s[14:15]
	s_cbranch_vccz .LBB0_754
	s_barrier

; #define PG8_STAGE(bufoff, gbase, voff) do { _Pragma("unroll") for (int _i = 0; _i < 2; ++_i) \
;         __builtin_amdgcn_global_load_lds((const unsigned*)((const char*)(gbase) + (voff)[_i]), (PG8_LAS unsigned*)(lds + (bufoff) + ldsw + _i * 8192), 16, 0, 0); } while (0)
; #define PG8_LDA(dst, b, h) do { _Pragma("unroll") for (int m = 0; m < 4; ++m) _Pragma("unroll") for (int k = 0; k < 2; ++k) dst[m][k] = *(const PG8_LAS bf16x8*)(lds + PG8_SA(b, h) + aoff + m * 2048 + k * 1024); } while (0)
; #define PG8_LDB(dst, b, h) do { _Pragma("unroll") for (int n = 0; n < 2; ++n) _Pragma("unroll") for (int k = 0; k < 2; ++k) dst[n][k] = *(const PG8_LAS bf16x8*)(lds + PG8_SB(b, h) + boff + n * 2048 + k * 1024); } while (0)
; #define PG8_MMA(ai, bj, At, Bt) do { __builtin_amdgcn_s_setprio(1); _Pragma("unroll") for (int m = 0; m < 4; ++m) _Pragma("unroll") for (int n = 0; n < 2; ++n) _Pragma("unroll") for (int k = 0; k < 2; ++k) \
;         acc[ai][bj][m][n] = __builtin_amdgcn_mfma_f32_16x16x32_bf16(Bt[n][k], At[m][k], acc[ai][bj][m][n], 0, 0, 0); __builtin_amdgcn_s_setprio(0); } while (0)
; #define PG8_WAIT_V(n) asm volatile("s_waitcnt vmcnt(" #n ")" ::: "memory")
; #define PG8_WAIT_L(n) asm volatile("s_waitcnt lgkmcnt(" #n ")" ::: "memory")
; #define PG8_BAR __builtin_amdgcn_s_barrier()
; #define PG8_SCHED __builtin_amdgcn_sched_barrier(0)
; template <class Epi, class Sched, bool ALIGN_EPI = false, bool SP2 = false>
; __device__ __forceinline__ void gemm_phase(PG8_LAS unsigned char* lds, const Gemm g, const Sched& S, const Epi& E) {
;     ...
;             const bool last = (t == nt - 2);
;             const char* a1 = cA + (size_t)(t + 1) * kstep;
;             const char* a2 = last ? nA : cA + (size_t)(t + 2) * kstep; const char* b2 = last ? nB : cB + (size_t)(t + 2) * kstep;
;             const char* a3 = a2 + kstep; const char* b3 = b2 + kstep;
;             if (last && has_next) S.a_ready(nxt);
;             if constexpr (SP2) {
;             PG8_LDB(B0, 0, 0); PG8_LDB(B1, 0, 1); PG8_SCHED; PG8_LDA(At, 0, 0); PG8_STAGE(PG8_SA(1, 1), a1 + hstep, voffA);
;             PG8_WAIT_V(8); PG8_WAIT_L(0); PG8_BAR; PG8_MMA(0, 0, At, B0); PG8_MMA(0, 1, At, B1); PG8_BAR; PG8_SCHED;
;             PG8_LDA(At, 0, 1); PG8_STAGE(PG8_SB(0, 0), b2, voffB); PG8_STAGE(PG8_SB(0, 1), b2 + hstep, voffB); PG8_STAGE(PG8_SA(0, 0), a2, voffA);
.LBB0_823:
	s_add_u32 s67, s42, 0x100
	v_mov_b32_e32 v0, 0
	s_addc_u32 s70, s43, 0
	s_mov_b32 s71, -2
	ds_read_b128 v[144:147], v153
	ds_read_b128 v[158:161], v153 offset:1024
	ds_read_b128 v[162:165], v153 offset:2048
	ds_read_b128 v[166:169], v153 offset:3072
	ds_read_b128 v[170:173], v154
	ds_read_b128 v[174:177], v154 offset:1024
	ds_read_b128 v[178:181], v154 offset:2048
	ds_read_b128 v[182:185], v154 offset:3072
	s_add_u32 s42, s38, 0x100
	s_addc_u32 s43, s39, 0
	s_cmp_eq_u32 s71, 2
	s_cselect_b32 s47, s5, s43
	s_cselect_b32 s46, s4, s42
	s_cselect_b32 s45, s21, s70
	s_cselect_b32 s44, s20, s67
	v_lshl_add_u64 v[148:149], s[38:39], 0, v[136:137]
	s_add_i32 m0, s49, 0xc000
	ds_read_b128 v[186:189], v155
	ds_read_b128 v[190:193], v155 offset:1024
	ds_read_b128 v[194:197], v155 offset:2048
	ds_read_b128 v[198:201], v155 offset:3072
	ds_read_b128 v[202:205], v155 offset:4096
	ds_read_b128 v[206:209], v155 offset:5120
	ds_read_b128 v[210:213], v155 offset:6144
	ds_read_b128 v[214:217], v155 offset:7168
	global_load_lds_dwordx4 v[148:149], off
	v_lshl_add_u64 v[148:149], s[38:39], 0, v[138:139]
	s_add_i32 m0, s49, 0xe000
	s_nop 0
	global_load_lds_dwordx4 v[148:149], off
	s_waitcnt vmcnt(8)
	s_waitcnt lgkmcnt(0)
	s_barrier
	s_setprio 1
	s_waitcnt lgkmcnt(0)
	v_mfma_f32_16x16x32_bf16 v[124:127], v[144:147], v[186:189], 0
	v_mfma_f32_16x16x32_bf16 v[120:123], v[162:165], v[186:189], 0
	v_mfma_f32_16x16x32_bf16 v[108:111], v[144:147], v[194:197], 0
	v_mfma_f32_16x16x32_bf16 v[104:107], v[162:165], v[194:197], 0
	v_mfma_f32_16x16x32_bf16 v[92:95], v[144:147], v[202:205], 0
	v_mfma_f32_16x16x32_bf16 v[88:91], v[162:165], v[202:205], 0
	v_mfma_f32_16x16x32_bf16 v[76:79], v[144:147], v[210:213], 0
	v_mfma_f32_16x16x32_bf16 v[72:75], v[162:165], v[210:213], 0
	v_mfma_f32_16x16x32_bf16 v[124:127], v[158:161], v[190:193], v[124:127]
	v_mfma_f32_16x16x32_bf16 v[120:123], v[166:169], v[190:193], v[120:123]
	v_mfma_f32_16x16x32_bf16 v[108:111], v[158:161], v[198:201], v[108:111]
	v_mfma_f32_16x16x32_bf16 v[104:107], v[166:169], v[198:201], v[104:107]
	v_mfma_f32_16x16x32_bf16 v[92:95], v[158:161], v[206:209], v[92:95]
	v_mfma_f32_16x16x32_bf16 v[88:91], v[166:169], v[206:209], v[88:91]
	v_mfma_f32_16x16x32_bf16 v[76:79], v[158:161], v[214:217], v[76:79]
	v_mfma_f32_16x16x32_bf16 v[72:75], v[166:169], v[214:217], v[72:75]
	s_setprio 0
	s_setprio 1
	v_mfma_f32_16x16x32_bf16 v[116:119], v[170:173], v[186:189], 0
	v_mfma_f32_16x16x32_bf16 v[112:115], v[178:181], v[186:189], 0
	v_mfma_f32_16x16x32_bf16 v[100:103], v[170:173], v[194:197], 0
	v_mfma_f32_16x16x32_bf16 v[96:99], v[178:181], v[194:197], 0
	v_mfma_f32_16x16x32_bf16 v[84:87], v[170:173], v[202:205], 0
	v_mfma_f32_16x16x32_bf16 v[80:83], v[178:181], v[202:205], 0
	v_mfma_f32_16x16x32_bf16 v[68:71], v[170:173], v[210:213], 0
	v_mfma_f32_16x16x32_bf16 v[64:67], v[178:181], v[210:213], 0
	v_mfma_f32_16x16x32_bf16 v[116:119], v[174:177], v[190:193], v[116:119]
	v_mfma_f32_16x16x32_bf16 v[112:115], v[182:185], v[190:193], v[112:115]
	v_mfma_f32_16x16x32_bf16 v[100:103], v[174:177], v[198:201], v[100:103]
	v_mfma_f32_16x16x32_bf16 v[96:99], v[182:185], v[198:201], v[96:99]
	v_mfma_f32_16x16x32_bf16 v[84:87], v[174:177], v[206:209], v[84:87]
	v_mfma_f32_16x16x32_bf16 v[80:83], v[182:185], v[206:209], v[80:83]
	v_mfma_f32_16x16x32_bf16 v[68:71], v[174:177], v[214:217], v[68:71]
	v_mfma_f32_16x16x32_bf16 v[64:67], v[182:185], v[214:217], v[64:67]
	s_setprio 0
	s_barrier
	s_add_i32 s30, s60, s48
	v_lshl_add_u64 v[148:149], s[44:45], 0, v[132:133]
	s_mov_b32 m0, s30
	ds_read_b128 v[186:189], v155 offset:16384
	ds_read_b128 v[190:193], v155 offset:17408
	ds_read_b128 v[194:197], v155 offset:18432
	ds_read_b128 v[198:201], v155 offset:19456
	ds_read_b128 v[202:205], v155 offset:20480
	ds_read_b128 v[206:209], v155 offset:21504
	ds_read_b128 v[210:213], v155 offset:22528
	ds_read_b128 v[214:217], v155 offset:23552
	global_load_lds_dwordx4 v[148:149], off
	s_add_i32 m0, s30, 0x2000
	s_add_u32 s30, s44, 0x18000
	v_lshl_add_u64 v[218:219], s[44:45], 0, v[128:129]
	s_addc_u32 s31, s45, 0
	s_add_i32 s38, s61, s48
	global_load_lds_dwordx4 v[218:219], off
	v_lshl_add_u64 v[220:221], s[30:31], 0, v[132:133]
	s_mov_b32 m0, s38
	v_lshl_add_u64 v[222:223], s[46:47], 0, v[130:131]
	global_load_lds_dwordx4 v[220:221], off
	v_lshl_add_u64 v[220:221], s[30:31], 0, v[128:129]
	s_add_i32 m0, s38, 0x2000
	s_nop 0
	global_load_lds_dwordx4 v[220:221], off
	v_lshl_add_u64 v[220:221], s[46:47], 0, v[134:135]
	s_mov_b32 m0, s49
	s_nop 0
	global_load_lds_dwordx4 v[220:221], off
	s_mov_b32 m0, s50
	s_nop 0
	global_load_lds_dwordx4 v[222:223], off
	s_waitcnt vmcnt(8)
	s_waitcnt lgkmcnt(0)
	s_barrier
; #define PG8_STAGE(bufoff, gbase, voff) do { _Pragma("unroll") for (int _i = 0; _i < 2; ++_i) \
;         __builtin_amdgcn_global_load_lds((const unsigned*)((const char*)(gbase) + (voff)[_i]), (PG8_LAS unsigned*)(lds + (bufoff) + ldsw + _i * 8192), 16, 0, 0); } while (0)
; #define PG8_LDA(dst, b, h) do { _Pragma("unroll") for (int m = 0; m < 4; ++m) _Pragma("unroll") for (int k = 0; k < 2; ++k) dst[m][k] = *(const PG8_LAS bf16x8*)(lds + PG8_SA(b, h) + aoff + m * 2048 + k * 1024); } while (0)
; #define PG8_LDB(dst, b, h) do { _Pragma("unroll") for (int n = 0; n < 2; ++n) _Pragma("unroll") for (int k = 0; k < 2; ++k) dst[n][k] = *(const PG8_LAS bf16x8*)(lds + PG8_SB(b, h) + boff + n * 2048 + k * 1024); } while (0)
; #define PG8_MMA(ai, bj, At, Bt) do { __builtin_amdgcn_s_setprio(1); _Pragma("unroll") for (int m = 0; m < 4; ++m) _Pragma("unroll") for (int n = 0; n < 2; ++n) _Pragma("unroll") for (int k = 0; k < 2; ++k) \
;         acc[ai][bj][m][n] = __builtin_amdgcn_mfma_f32_16x16x32_bf16(Bt[n][k], At[m][k], acc[ai][bj][m][n], 0, 0, 0); __builtin_amdgcn_s_setprio(0); } while (0)
; #define PG8_WAIT_V(n) asm volatile("s_waitcnt vmcnt(" #n ")" ::: "memory")
; #define PG8_WAIT_L(n) asm volatile("s_waitcnt lgkmcnt(" #n ")" ::: "memory")
; #define PG8_BAR __builtin_amdgcn_s_barrier()
; #define PG8_SCHED __builtin_amdgcn_sched_barrier(0)
; template <class Epi, class Sched, bool ALIGN_EPI = false, bool SP2 = false>
; __device__ __forceinline__ void gemm_phase(PG8_LAS unsigned char* lds, const Gemm g, const Sched& S, const Epi& E) {
;     ...
;             PG8_WAIT_V(8); PG8_WAIT_L(0); PG8_BAR; PG8_MMA(1, 0, At, B0); PG8_MMA(1, 1, At, B1); PG8_BAR; PG8_SCHED;
;             PG8_LDB(B0, 1, 0); PG8_LDB(B1, 1, 1); PG8_SCHED; PG8_LDA(At, 1, 0); PG8_STAGE(PG8_SA(0, 1), a2 + hstep, voffA);
;             PG8_WAIT_V(8); PG8_WAIT_L(0); PG8_BAR; PG8_MMA(0, 0, At, B0); PG8_MMA(0, 1, At, B1); PG8_BAR; PG8_SCHED;
	s_setprio 1
	s_waitcnt lgkmcnt(0)
	v_mfma_f32_16x16x32_bf16 v[60:63], v[144:147], v[186:189], 0
	v_mfma_f32_16x16x32_bf16 v[56:59], v[162:165], v[186:189], 0
	v_mfma_f32_16x16x32_bf16 v[44:47], v[144:147], v[194:197], 0
	v_mfma_f32_16x16x32_bf16 v[40:43], v[162:165], v[194:197], 0
	v_mfma_f32_16x16x32_bf16 v[28:31], v[144:147], v[202:205], 0
	v_mfma_f32_16x16x32_bf16 v[24:27], v[162:165], v[202:205], 0
	v_mfma_f32_16x16x32_bf16 v[12:15], v[144:147], v[210:213], 0
	v_mfma_f32_16x16x32_bf16 v[8:11], v[162:165], v[210:213], 0
	v_mfma_f32_16x16x32_bf16 v[60:63], v[158:161], v[190:193], v[60:63]
	v_mfma_f32_16x16x32_bf16 v[56:59], v[166:169], v[190:193], v[56:59]
	v_mfma_f32_16x16x32_bf16 v[44:47], v[158:161], v[198:201], v[44:47]
	v_mfma_f32_16x16x32_bf16 v[40:43], v[166:169], v[198:201], v[40:43]
	v_mfma_f32_16x16x32_bf16 v[28:31], v[158:161], v[206:209], v[28:31]
	v_mfma_f32_16x16x32_bf16 v[24:27], v[166:169], v[206:209], v[24:27]
	v_mfma_f32_16x16x32_bf16 v[12:15], v[158:161], v[214:217], v[12:15]
	v_mfma_f32_16x16x32_bf16 v[8:11], v[166:169], v[214:217], v[8:11]
	s_setprio 0
	s_setprio 1
	v_mfma_f32_16x16x32_bf16 v[52:55], v[170:173], v[186:189], 0
	v_mfma_f32_16x16x32_bf16 v[48:51], v[178:181], v[186:189], 0
	v_mfma_f32_16x16x32_bf16 v[36:39], v[170:173], v[194:197], 0
	v_mfma_f32_16x16x32_bf16 v[32:35], v[178:181], v[194:197], 0
	v_mfma_f32_16x16x32_bf16 v[20:23], v[170:173], v[202:205], 0
	v_mfma_f32_16x16x32_bf16 v[16:19], v[178:181], v[202:205], 0
	v_mfma_f32_16x16x32_bf16 v[4:7], v[170:173], v[210:213], 0
	v_mfma_f32_16x16x32_bf16 v[0:3], v[178:181], v[210:213], 0
	v_mfma_f32_16x16x32_bf16 v[52:55], v[174:177], v[190:193], v[52:55]
	v_mfma_f32_16x16x32_bf16 v[48:51], v[182:185], v[190:193], v[48:51]
	v_mfma_f32_16x16x32_bf16 v[36:39], v[174:177], v[198:201], v[36:39]
	v_mfma_f32_16x16x32_bf16 v[32:35], v[182:185], v[198:201], v[32:35]
	v_mfma_f32_16x16x32_bf16 v[20:23], v[174:177], v[206:209], v[20:23]
	v_mfma_f32_16x16x32_bf16 v[16:19], v[182:185], v[206:209], v[16:19]
	v_mfma_f32_16x16x32_bf16 v[4:7], v[174:177], v[214:217], v[4:7]
	v_mfma_f32_16x16x32_bf16 v[0:3], v[182:185], v[214:217], v[0:3]
	s_setprio 0
	s_barrier
	s_add_i32 s38, 0, 0x18000
	v_add_u32_e32 v157, s38, v151
	s_add_i32 s39, 0, 0x1c000
	ds_read_b128 v[144:147], v157
	ds_read_b128 v[158:161], v157 offset:1024
	ds_read_b128 v[162:165], v157 offset:2048
	ds_read_b128 v[166:169], v157 offset:3072
	v_add_u32_e32 v157, s39, v151
	ds_read_b128 v[170:173], v157
	ds_read_b128 v[174:177], v157 offset:1024
	ds_read_b128 v[178:181], v157 offset:2048
	ds_read_b128 v[182:185], v157 offset:3072
	s_add_u32 s30, s46, 0x18000
	s_addc_u32 s31, s47, 0
	s_mov_b32 m0, s51
	v_lshl_add_u64 v[224:225], s[30:31], 0, v[134:135]
	ds_read_b128 v[186:189], v155 offset:32768
	ds_read_b128 v[190:193], v155 offset:33792
	ds_read_b128 v[194:197], v155 offset:34816
	ds_read_b128 v[198:201], v155 offset:35840
	ds_read_b128 v[202:205], v155 offset:36864
	ds_read_b128 v[206:209], v155 offset:37888
	ds_read_b128 v[210:213], v155 offset:38912
	ds_read_b128 v[214:217], v155 offset:39936
	global_load_lds_dwordx4 v[224:225], off
	v_lshl_add_u64 v[224:225], s[30:31], 0, v[130:131]
	s_mov_b32 m0, s52
	s_nop 0
	global_load_lds_dwordx4 v[224:225], off
	s_waitcnt vmcnt(8)
	s_waitcnt lgkmcnt(0)
	s_barrier
	s_setprio 1
	s_waitcnt lgkmcnt(0)
	v_mfma_f32_16x16x32_bf16 v[124:127], v[144:147], v[186:189], v[124:127]
	v_mfma_f32_16x16x32_bf16 v[120:123], v[162:165], v[186:189], v[120:123]
	v_mfma_f32_16x16x32_bf16 v[108:111], v[144:147], v[194:197], v[108:111]
	v_mfma_f32_16x16x32_bf16 v[104:107], v[162:165], v[194:197], v[104:107]
	v_mfma_f32_16x16x32_bf16 v[92:95], v[144:147], v[202:205], v[92:95]
	v_mfma_f32_16x16x32_bf16 v[88:91], v[162:165], v[202:205], v[88:91]
	v_mfma_f32_16x16x32_bf16 v[76:79], v[144:147], v[210:213], v[76:79]
	v_mfma_f32_16x16x32_bf16 v[72:75], v[162:165], v[210:213], v[72:75]
	v_mfma_f32_16x16x32_bf16 v[124:127], v[158:161], v[190:193], v[124:127]
	v_mfma_f32_16x16x32_bf16 v[120:123], v[166:169], v[190:193], v[120:123]
	v_mfma_f32_16x16x32_bf16 v[108:111], v[158:161], v[198:201], v[108:111]
	v_mfma_f32_16x16x32_bf16 v[104:107], v[166:169], v[198:201], v[104:107]
	v_mfma_f32_16x16x32_bf16 v[92:95], v[158:161], v[206:209], v[92:95]
	v_mfma_f32_16x16x32_bf16 v[88:91], v[166:169], v[206:209], v[88:91]
	v_mfma_f32_16x16x32_bf16 v[76:79], v[158:161], v[214:217], v[76:79]
	v_mfma_f32_16x16x32_bf16 v[72:75], v[166:169], v[214:217], v[72:75]
	s_setprio 0
	s_setprio 1
	v_mfma_f32_16x16x32_bf16 v[116:119], v[170:173], v[186:189], v[116:119]
	v_mfma_f32_16x16x32_bf16 v[112:115], v[178:181], v[186:189], v[112:115]
	v_mfma_f32_16x16x32_bf16 v[100:103], v[170:173], v[194:197], v[100:103]
	v_mfma_f32_16x16x32_bf16 v[96:99], v[178:181], v[194:197], v[96:99]
	v_mfma_f32_16x16x32_bf16 v[84:87], v[170:173], v[202:205], v[84:87]
	v_mfma_f32_16x16x32_bf16 v[80:83], v[178:181], v[202:205], v[80:83]
	v_mfma_f32_16x16x32_bf16 v[68:71], v[170:173], v[210:213], v[68:71]
	v_mfma_f32_16x16x32_bf16 v[64:67], v[178:181], v[210:213], v[64:67]
	v_mfma_f32_16x16x32_bf16 v[116:119], v[174:177], v[190:193], v[116:119]
	v_mfma_f32_16x16x32_bf16 v[112:115], v[182:185], v[190:193], v[112:115]
	v_mfma_f32_16x16x32_bf16 v[100:103], v[174:177], v[198:201], v[100:103]
	v_mfma_f32_16x16x32_bf16 v[96:99], v[182:185], v[198:201], v[96:99]
	v_mfma_f32_16x16x32_bf16 v[84:87], v[174:177], v[206:209], v[84:87]
	v_mfma_f32_16x16x32_bf16 v[80:83], v[182:185], v[206:209], v[80:83]
	v_mfma_f32_16x16x32_bf16 v[68:71], v[174:177], v[214:217], v[68:71]
	v_mfma_f32_16x16x32_bf16 v[64:67], v[182:185], v[214:217], v[64:67]
	s_setprio 0
	s_barrier
; #define PG8_STAGE(bufoff, gbase, voff) do { _Pragma("unroll") for (int _i = 0; _i < 2; ++_i) \
;         __builtin_amdgcn_global_load_lds((const unsigned*)((const char*)(gbase) + (voff)[_i]), (PG8_LAS unsigned*)(lds + (bufoff) + ldsw + _i * 8192), 16, 0, 0); } while (0)
; #define PG8_LDA(dst, b, h) do { _Pragma("unroll") for (int m = 0; m < 4; ++m) _Pragma("unroll") for (int k = 0; k < 2; ++k) dst[m][k] = *(const PG8_LAS bf16x8*)(lds + PG8_SA(b, h) + aoff + m * 2048 + k * 1024); } while (0)
; #define PG8_MMA(ai, bj, At, Bt) do { __builtin_amdgcn_s_setprio(1); _Pragma("unroll") for (int m = 0; m < 4; ++m) _Pragma("unroll") for (int n = 0; n < 2; ++n) _Pragma("unroll") for (int k = 0; k < 2; ++k) \
;         acc[ai][bj][m][n] = __builtin_amdgcn_mfma_f32_16x16x32_bf16(Bt[n][k], At[m][k], acc[ai][bj][m][n], 0, 0, 0); __builtin_amdgcn_s_setprio(0); } while (0)
; #define PG8_WAIT_V(n) asm volatile("s_waitcnt vmcnt(" #n ")" ::: "memory")
; #define PG8_WAIT_L(n) asm volatile("s_waitcnt lgkmcnt(" #n ")" ::: "memory")
; #define PG8_BAR __builtin_amdgcn_s_barrier()
; #define PG8_SCHED __builtin_amdgcn_sched_barrier(0)
; template <class Epi, class Sched, bool ALIGN_EPI = false, bool SP2 = false>
; __device__ __forceinline__ void gemm_phase(PG8_LAS unsigned char* lds, const Gemm g, const Sched& S, const Epi& E) {
;     ...
;         for (int t = 0; t < nt; t += 2) {
;             const bool last = (t == nt - 2);
;     ...
;             PG8_LDA(At, 1, 1); PG8_STAGE(PG8_SB(1, 0), b3, voffB); PG8_STAGE(PG8_SB(1, 1), b3 + hstep, voffB); PG8_STAGE(PG8_SA(1, 0), a3, voffA);
;             PG8_WAIT_V(8); PG8_WAIT_L(0); PG8_BAR; PG8_MMA(1, 0, At, B0); PG8_MMA(1, 1, At, B1); PG8_BAR; PG8_SCHED;
	s_add_i32 s30, s38, s48
	v_lshl_add_u64 v[148:149], v[148:149], 0, s[16:17]
	s_mov_b32 m0, s30
	ds_read_b128 v[186:189], v155 offset:49152
	ds_read_b128 v[190:193], v155 offset:50176
	ds_read_b128 v[194:197], v155 offset:51200
	ds_read_b128 v[198:201], v155 offset:52224
	ds_read_b128 v[202:205], v155 offset:53248
	ds_read_b128 v[206:209], v155 offset:54272
	ds_read_b128 v[210:213], v155 offset:55296
	ds_read_b128 v[214:217], v155 offset:56320
	global_load_lds_dwordx4 v[148:149], off
	s_add_i32 m0, s30, 0x2000
	s_add_u32 s30, s44, 0x18080
	v_lshl_add_u64 v[148:149], v[218:219], 0, s[16:17]
	s_addc_u32 s31, s45, 0
	s_add_i32 s38, s39, s48
	global_load_lds_dwordx4 v[148:149], off
	v_lshl_add_u64 v[148:149], s[30:31], 0, v[132:133]
	s_mov_b32 m0, s38
	s_nop 0
	global_load_lds_dwordx4 v[148:149], off
	v_lshl_add_u64 v[148:149], s[30:31], 0, v[128:129]
	s_add_i32 m0, s38, 0x2000
	s_nop 0
	global_load_lds_dwordx4 v[148:149], off
	v_lshl_add_u64 v[148:149], v[220:221], 0, s[16:17]
	s_mov_b32 m0, s58
	s_nop 0
	global_load_lds_dwordx4 v[148:149], off
	v_lshl_add_u64 v[148:149], v[222:223], 0, s[16:17]
	s_mov_b32 m0, s59
	s_nop 0
	global_load_lds_dwordx4 v[148:149], off
	s_waitcnt vmcnt(8)
	s_waitcnt lgkmcnt(0)
	s_barrier
	s_setprio 1
	s_waitcnt lgkmcnt(0)
	v_mfma_f32_16x16x32_bf16 v[60:63], v[144:147], v[186:189], v[60:63]
	v_mfma_f32_16x16x32_bf16 v[56:59], v[162:165], v[186:189], v[56:59]
	v_mfma_f32_16x16x32_bf16 v[44:47], v[144:147], v[194:197], v[44:47]
	v_mfma_f32_16x16x32_bf16 v[40:43], v[162:165], v[194:197], v[40:43]
	v_mfma_f32_16x16x32_bf16 v[28:31], v[144:147], v[202:205], v[28:31]
	v_mfma_f32_16x16x32_bf16 v[24:27], v[162:165], v[202:205], v[24:27]
	v_mfma_f32_16x16x32_bf16 v[12:15], v[144:147], v[210:213], v[12:15]
	v_mfma_f32_16x16x32_bf16 v[8:11], v[162:165], v[210:213], v[8:11]
	v_mfma_f32_16x16x32_bf16 v[60:63], v[158:161], v[190:193], v[60:63]
	v_mfma_f32_16x16x32_bf16 v[56:59], v[166:169], v[190:193], v[56:59]
	v_mfma_f32_16x16x32_bf16 v[44:47], v[158:161], v[198:201], v[44:47]
	v_mfma_f32_16x16x32_bf16 v[40:43], v[166:169], v[198:201], v[40:43]
	v_mfma_f32_16x16x32_bf16 v[28:31], v[158:161], v[206:209], v[28:31]
	v_mfma_f32_16x16x32_bf16 v[24:27], v[166:169], v[206:209], v[24:27]
	v_mfma_f32_16x16x32_bf16 v[12:15], v[158:161], v[214:217], v[12:15]
	v_mfma_f32_16x16x32_bf16 v[8:11], v[166:169], v[214:217], v[8:11]
	s_setprio 0
	s_setprio 1
	v_mfma_f32_16x16x32_bf16 v[52:55], v[170:173], v[186:189], v[52:55]
	v_mfma_f32_16x16x32_bf16 v[48:51], v[178:181], v[186:189], v[48:51]
	v_mfma_f32_16x16x32_bf16 v[36:39], v[170:173], v[194:197], v[36:39]
	v_mfma_f32_16x16x32_bf16 v[32:35], v[178:181], v[194:197], v[32:35]
	v_mfma_f32_16x16x32_bf16 v[20:23], v[170:173], v[202:205], v[20:23]
	v_mfma_f32_16x16x32_bf16 v[16:19], v[178:181], v[202:205], v[16:19]
	v_mfma_f32_16x16x32_bf16 v[4:7], v[170:173], v[210:213], v[4:7]
	v_mfma_f32_16x16x32_bf16 v[0:3], v[178:181], v[210:213], v[0:3]
	v_mfma_f32_16x16x32_bf16 v[52:55], v[174:177], v[190:193], v[52:55]
	v_mfma_f32_16x16x32_bf16 v[48:51], v[182:185], v[190:193], v[48:51]
	v_mfma_f32_16x16x32_bf16 v[36:39], v[174:177], v[198:201], v[36:39]
	v_mfma_f32_16x16x32_bf16 v[32:35], v[182:185], v[198:201], v[32:35]
	v_mfma_f32_16x16x32_bf16 v[20:23], v[174:177], v[206:209], v[20:23]
	v_mfma_f32_16x16x32_bf16 v[16:19], v[182:185], v[206:209], v[16:19]
	v_mfma_f32_16x16x32_bf16 v[4:7], v[174:177], v[214:217], v[4:7]
	v_mfma_f32_16x16x32_bf16 v[0:3], v[182:185], v[214:217], v[0:3]
	s_setprio 0
	s_barrier
	s_add_i32 s71, s71, 2
	s_add_u32 s67, s67, 0x100
	s_addc_u32 s70, s70, 0
	s_cmp_gt_u32 s71, 3
	s_mov_b64 s[38:39], s[42:43]
	s_cbranch_scc0 .LBB0_824
	s_branch .Lgx_g2

; #define PG8_BAR __builtin_amdgcn_s_barrier()
; template <class Epi, class Sched, bool ALIGN_EPI = false, bool SP2 = false>
; __device__ __forceinline__ void gemm_phase(PG8_LAS unsigned char* lds, const Gemm g, const Sched& S, const Epi& E) {
;     ...
;         if constexpr (ALIGN_EPI) { if (wr == 0) PG8_BAR; }
.Lgx_g2:
	s_and_b64 vcc, exec, s[18:19]
	s_cbranch_vccz .LBB0_827
	s_barrier

; #define PG8_STAGE(bufoff, gbase, voff) do { _Pragma("unroll") for (int _i = 0; _i < 2; ++_i) \
;         __builtin_amdgcn_global_load_lds((const unsigned*)((const char*)(gbase) + (voff)[_i]), (PG8_LAS unsigned*)(lds + (bufoff) + ldsw + _i * 8192), 16, 0, 0); } while (0)
; #define PG8_LDA(dst, b, h) do { _Pragma("unroll") for (int m = 0; m < 4; ++m) _Pragma("unroll") for (int k = 0; k < 2; ++k) dst[m][k] = *(const PG8_LAS bf16x8*)(lds + PG8_SA(b, h) + aoff + m * 2048 + k * 1024); } while (0)
; #define PG8_LDB(dst, b, h) do { _Pragma("unroll") for (int n = 0; n < 2; ++n) _Pragma("unroll") for (int k = 0; k < 2; ++k) dst[n][k] = *(const PG8_LAS bf16x8*)(lds + PG8_SB(b, h) + boff + n * 2048 + k * 1024); } while (0)
; #define PG8_MMA(ai, bj, At, Bt) do { __builtin_amdgcn_s_setprio(1); _Pragma("unroll") for (int m = 0; m < 4; ++m) _Pragma("unroll") for (int n = 0; n < 2; ++n) _Pragma("unroll") for (int k = 0; k < 2; ++k) \
;         acc[ai][bj][m][n] = __builtin_amdgcn_mfma_f32_16x16x32_bf16(Bt[n][k], At[m][k], acc[ai][bj][m][n], 0, 0, 0); __builtin_amdgcn_s_setprio(0); } while (0)
; #define PG8_WAIT_V(n) asm volatile("s_waitcnt vmcnt(" #n ")" ::: "memory")
; #define PG8_WAIT_L(n) asm volatile("s_waitcnt lgkmcnt(" #n ")" ::: "memory")
; #define PG8_BAR __builtin_amdgcn_s_barrier()
; #define PG8_SCHED __builtin_amdgcn_sched_barrier(0)
; template <class Epi, class Sched, bool ALIGN_EPI = false, bool SP2 = false>
; __device__ __forceinline__ void gemm_phase(PG8_LAS unsigned char* lds, const Gemm g, const Sched& S, const Epi& E) {
;     ...
;             const bool last = (t == nt - 2);
;             const char* a1 = cA + (size_t)(t + 1) * kstep;
;             const char* a2 = last ? nA : cA + (size_t)(t + 2) * kstep; const char* b2 = last ? nB : cB + (size_t)(t + 2) * kstep;
;             const char* a3 = a2 + kstep; const char* b3 = b2 + kstep;
;             if (last && has_next) S.a_ready(nxt);
;             if constexpr (SP2) {
;             PG8_LDB(B0, 0, 0); PG8_LDB(B1, 0, 1); PG8_SCHED; PG8_LDA(At, 0, 0); PG8_STAGE(PG8_SA(1, 1), a1 + hstep, voffA);
;             PG8_WAIT_V(8); PG8_WAIT_L(0); PG8_BAR; PG8_MMA(0, 0, At, B0); PG8_MMA(0, 1, At, B1); PG8_BAR; PG8_SCHED;
;             PG8_LDA(At, 0, 1); PG8_STAGE(PG8_SB(0, 0), b2, voffB); PG8_STAGE(PG8_SB(0, 1), b2 + hstep, voffB); PG8_STAGE(PG8_SA(0, 0), a2, voffA);
.LBB0_847:
	s_ashr_i32 s21, s20, 31
	s_lshl_b64 s[30:31], s[20:21], 17
	s_add_u32 s38, s70, s30
	s_addc_u32 s39, s71, s31
	s_and_b64 s[30:31], s[2:3], exec
	s_cselect_b32 s21, s39, s49
	s_cselect_b32 s83, s38, s48
	s_ashr_i32 s19, s18, 31
	s_lshl_b64 s[30:31], s[18:19], 17
	s_add_u32 s42, s10, s30
	s_addc_u32 s43, s11, s31
	s_and_b64 s[30:31], s[2:3], exec
	v_mov_b32_e32 v0, 0
	s_cselect_b32 s19, s43, s47
	s_cselect_b32 s84, s42, s46
	s_mov_b64 s[58:59], 0
	s_mov_b64 s[50:51], -1
	s_mov_b64 s[52:53], 0
	s_add_u32 s64, s48, s58
	s_addc_u32 s65, s49, s59
	s_add_u32 s60, s64, 0x100
	s_addc_u32 s61, s65, 0
	s_and_b64 s[30:31], s[52:53], exec
	s_cselect_b32 s61, s21, s61
	s_cselect_b32 s60, s83, s60
	s_add_u32 s30, s46, s58
	s_addc_u32 s31, s47, s59
	s_add_u32 s58, s30, 0x100
	s_addc_u32 s59, s31, 0
	s_and_b64 s[30:31], s[52:53], exec
	s_cselect_b32 s63, s19, s59
	s_cselect_b32 s62, s84, s58
	s_add_u32 s66, s64, 0x10080
	ds_read_b128 v[140:143], v147
	ds_read_b128 v[152:155], v147 offset:1024
	ds_read_b128 v[156:159], v147 offset:2048
	ds_read_b128 v[160:163], v147 offset:3072
	ds_read_b128 v[164:167], v148
	ds_read_b128 v[168:171], v148 offset:1024
	ds_read_b128 v[172:175], v148 offset:2048
	ds_read_b128 v[176:179], v148 offset:3072
	s_addc_u32 s67, s65, 0
	s_add_i32 s90, s80, s1
	s_add_i32 m0, s45, 0xc000
	s_add_i32 s93, s45, 0xe000
	s_add_i32 s87, s90, 0x2000
	s_add_u32 s64, s62, 0x10000
	s_addc_u32 s65, s63, 0
	s_add_i32 s89, s81, s1
	s_add_i32 s88, s89, 0x2000
	s_add_i32 s86, 0, 0x18000
	s_add_i32 s85, 0, 0x1c000
	s_add_u32 s58, s60, 0x10000
	s_addc_u32 s59, s61, 0
	s_add_i32 s31, s86, s1
	s_add_i32 s30, s31, 0x2000
	s_add_u32 s52, s62, 0x10080
	s_addc_u32 s53, s63, 0
	s_add_i32 s92, s85, s1
	s_add_i32 s91, s92, 0x2000
	v_lshl_add_u64 v[212:213], s[66:67], 0, v[128:129]
	ds_read_b128 v[180:183], v149
	ds_read_b128 v[184:187], v149 offset:1024
	ds_read_b128 v[188:191], v149 offset:2048
	ds_read_b128 v[192:195], v149 offset:3072
	ds_read_b128 v[196:199], v149 offset:4096
	ds_read_b128 v[200:203], v149 offset:5120
	ds_read_b128 v[204:207], v149 offset:6144
	ds_read_b128 v[208:211], v149 offset:7168
	global_load_lds_dwordx4 v[212:213], off
	v_lshl_add_u64 v[212:213], s[66:67], 0, v[132:133]
	s_mov_b32 m0, s93
	s_nop 0
	global_load_lds_dwordx4 v[212:213], off
	s_waitcnt vmcnt(8)
	s_waitcnt lgkmcnt(0)
	s_barrier
	s_setprio 1
	s_waitcnt lgkmcnt(0)
	v_mfma_f32_16x16x32_bf16 v[124:127], v[140:143], v[180:183], 0
	v_mfma_f32_16x16x32_bf16 v[120:123], v[156:159], v[180:183], 0
	v_mfma_f32_16x16x32_bf16 v[108:111], v[140:143], v[188:191], 0
	v_mfma_f32_16x16x32_bf16 v[104:107], v[156:159], v[188:191], 0
	v_mfma_f32_16x16x32_bf16 v[92:95], v[140:143], v[196:199], 0
	v_mfma_f32_16x16x32_bf16 v[88:91], v[156:159], v[196:199], 0
	v_mfma_f32_16x16x32_bf16 v[76:79], v[140:143], v[204:207], 0
	v_mfma_f32_16x16x32_bf16 v[72:75], v[156:159], v[204:207], 0
	v_mfma_f32_16x16x32_bf16 v[124:127], v[152:155], v[184:187], v[124:127]
	v_mfma_f32_16x16x32_bf16 v[120:123], v[160:163], v[184:187], v[120:123]
	v_mfma_f32_16x16x32_bf16 v[108:111], v[152:155], v[192:195], v[108:111]
	v_mfma_f32_16x16x32_bf16 v[104:107], v[160:163], v[192:195], v[104:107]
	v_mfma_f32_16x16x32_bf16 v[92:95], v[152:155], v[200:203], v[92:95]
	v_mfma_f32_16x16x32_bf16 v[88:91], v[160:163], v[200:203], v[88:91]
	v_mfma_f32_16x16x32_bf16 v[76:79], v[152:155], v[208:211], v[76:79]
	v_mfma_f32_16x16x32_bf16 v[72:75], v[160:163], v[208:211], v[72:75]
	s_setprio 0
	s_setprio 1
	v_mfma_f32_16x16x32_bf16 v[116:119], v[164:167], v[180:183], 0
	v_mfma_f32_16x16x32_bf16 v[112:115], v[172:175], v[180:183], 0
	v_mfma_f32_16x16x32_bf16 v[100:103], v[164:167], v[188:191], 0
	v_mfma_f32_16x16x32_bf16 v[96:99], v[172:175], v[188:191], 0
	v_mfma_f32_16x16x32_bf16 v[84:87], v[164:167], v[196:199], 0
	v_mfma_f32_16x16x32_bf16 v[80:83], v[172:175], v[196:199], 0
	v_mfma_f32_16x16x32_bf16 v[68:71], v[164:167], v[204:207], 0
	v_mfma_f32_16x16x32_bf16 v[64:67], v[172:175], v[204:207], 0
	v_mfma_f32_16x16x32_bf16 v[116:119], v[168:171], v[184:187], v[116:119]
	v_mfma_f32_16x16x32_bf16 v[112:115], v[176:179], v[184:187], v[112:115]
	v_mfma_f32_16x16x32_bf16 v[100:103], v[168:171], v[192:195], v[100:103]
	v_mfma_f32_16x16x32_bf16 v[96:99], v[176:179], v[192:195], v[96:99]
	v_mfma_f32_16x16x32_bf16 v[84:87], v[168:171], v[200:203], v[84:87]
	v_mfma_f32_16x16x32_bf16 v[80:83], v[176:179], v[200:203], v[80:83]
	v_mfma_f32_16x16x32_bf16 v[68:71], v[168:171], v[208:211], v[68:71]
	v_mfma_f32_16x16x32_bf16 v[64:67], v[176:179], v[208:211], v[64:67]
	s_setprio 0
	s_barrier
	s_mov_b32 m0, s90
	v_lshl_add_u64 v[212:213], s[62:63], 0, v[130:131]
	ds_read_b128 v[180:183], v149 offset:16384
	ds_read_b128 v[184:187], v149 offset:17408
	ds_read_b128 v[188:191], v149 offset:18432
	ds_read_b128 v[192:195], v149 offset:19456
	ds_read_b128 v[196:199], v149 offset:20480
	ds_read_b128 v[200:203], v149 offset:21504
	ds_read_b128 v[204:207], v149 offset:22528
	ds_read_b128 v[208:211], v149 offset:23552
	global_load_lds_dwordx4 v[212:213], off
	v_lshl_add_u64 v[214:215], s[62:63], 0, v[134:135]
	s_mov_b32 m0, s87
	v_lshl_add_u64 v[216:217], s[64:65], 0, v[130:131]
	global_load_lds_dwordx4 v[214:215], off
	s_mov_b32 m0, s89
	v_lshl_add_u64 v[218:219], s[60:61], 0, v[132:133]
	global_load_lds_dwordx4 v[216:217], off
	v_lshl_add_u64 v[216:217], s[64:65], 0, v[134:135]
	s_mov_b32 m0, s88
	s_nop 0
	global_load_lds_dwordx4 v[216:217], off
	v_lshl_add_u64 v[216:217], s[60:61], 0, v[128:129]
	s_mov_b32 m0, s45
	s_nop 0
	global_load_lds_dwordx4 v[216:217], off
	s_mov_b32 m0, s72
	s_nop 0
	global_load_lds_dwordx4 v[218:219], off
	s_waitcnt vmcnt(8)
	s_waitcnt lgkmcnt(0)
	s_barrier
; #define PG8_STAGE(bufoff, gbase, voff) do { _Pragma("unroll") for (int _i = 0; _i < 2; ++_i) \
;         __builtin_amdgcn_global_load_lds((const unsigned*)((const char*)(gbase) + (voff)[_i]), (PG8_LAS unsigned*)(lds + (bufoff) + ldsw + _i * 8192), 16, 0, 0); } while (0)
; #define PG8_LDA(dst, b, h) do { _Pragma("unroll") for (int m = 0; m < 4; ++m) _Pragma("unroll") for (int k = 0; k < 2; ++k) dst[m][k] = *(const PG8_LAS bf16x8*)(lds + PG8_SA(b, h) + aoff + m * 2048 + k * 1024); } while (0)
; #define PG8_LDB(dst, b, h) do { _Pragma("unroll") for (int n = 0; n < 2; ++n) _Pragma("unroll") for (int k = 0; k < 2; ++k) dst[n][k] = *(const PG8_LAS bf16x8*)(lds + PG8_SB(b, h) + boff + n * 2048 + k * 1024); } while (0)
; #define PG8_MMA(ai, bj, At, Bt) do { __builtin_amdgcn_s_setprio(1); _Pragma("unroll") for (int m = 0; m < 4; ++m) _Pragma("unroll") for (int n = 0; n < 2; ++n) _Pragma("unroll") for (int k = 0; k < 2; ++k) \
;         acc[ai][bj][m][n] = __builtin_amdgcn_mfma_f32_16x16x32_bf16(Bt[n][k], At[m][k], acc[ai][bj][m][n], 0, 0, 0); __builtin_amdgcn_s_setprio(0); } while (0)
; #define PG8_WAIT_V(n) asm volatile("s_waitcnt vmcnt(" #n ")" ::: "memory")
; #define PG8_WAIT_L(n) asm volatile("s_waitcnt lgkmcnt(" #n ")" ::: "memory")
; #define PG8_BAR __builtin_amdgcn_s_barrier()
; #define PG8_SCHED __builtin_amdgcn_sched_barrier(0)
; template <class Epi, class Sched, bool ALIGN_EPI = false, bool SP2 = false>
; __device__ __forceinline__ void gemm_phase(PG8_LAS unsigned char* lds, const Gemm g, const Sched& S, const Epi& E) {
;     ...
;             PG8_WAIT_V(8); PG8_WAIT_L(0); PG8_BAR; PG8_MMA(1, 0, At, B0); PG8_MMA(1, 1, At, B1); PG8_BAR; PG8_SCHED;
;             PG8_LDB(B0, 1, 0); PG8_LDB(B1, 1, 1); PG8_SCHED; PG8_LDA(At, 1, 0); PG8_STAGE(PG8_SA(0, 1), a2 + hstep, voffA);
;             PG8_WAIT_V(8); PG8_WAIT_L(0); PG8_BAR; PG8_MMA(0, 0, At, B0); PG8_MMA(0, 1, At, B1); PG8_BAR; PG8_SCHED;
	s_setprio 1
	s_waitcnt lgkmcnt(0)
	v_mfma_f32_16x16x32_bf16 v[60:63], v[140:143], v[180:183], 0
	v_mfma_f32_16x16x32_bf16 v[56:59], v[156:159], v[180:183], 0
	v_mfma_f32_16x16x32_bf16 v[44:47], v[140:143], v[188:191], 0
	v_mfma_f32_16x16x32_bf16 v[40:43], v[156:159], v[188:191], 0
	v_mfma_f32_16x16x32_bf16 v[28:31], v[140:143], v[196:199], 0
	v_mfma_f32_16x16x32_bf16 v[24:27], v[156:159], v[196:199], 0
	v_mfma_f32_16x16x32_bf16 v[12:15], v[140:143], v[204:207], 0
	v_mfma_f32_16x16x32_bf16 v[8:11], v[156:159], v[204:207], 0
	v_mfma_f32_16x16x32_bf16 v[60:63], v[152:155], v[184:187], v[60:63]
	v_mfma_f32_16x16x32_bf16 v[56:59], v[160:163], v[184:187], v[56:59]
	v_mfma_f32_16x16x32_bf16 v[44:47], v[152:155], v[192:195], v[44:47]
	v_mfma_f32_16x16x32_bf16 v[40:43], v[160:163], v[192:195], v[40:43]
	v_mfma_f32_16x16x32_bf16 v[28:31], v[152:155], v[200:203], v[28:31]
	v_mfma_f32_16x16x32_bf16 v[24:27], v[160:163], v[200:203], v[24:27]
	v_mfma_f32_16x16x32_bf16 v[12:15], v[152:155], v[208:211], v[12:15]
	v_mfma_f32_16x16x32_bf16 v[8:11], v[160:163], v[208:211], v[8:11]
	s_setprio 0
	s_setprio 1
	v_mfma_f32_16x16x32_bf16 v[52:55], v[164:167], v[180:183], 0
	v_mfma_f32_16x16x32_bf16 v[48:51], v[172:175], v[180:183], 0
	v_mfma_f32_16x16x32_bf16 v[36:39], v[164:167], v[188:191], 0
	v_mfma_f32_16x16x32_bf16 v[32:35], v[172:175], v[188:191], 0
	v_mfma_f32_16x16x32_bf16 v[20:23], v[164:167], v[196:199], 0
	v_mfma_f32_16x16x32_bf16 v[16:19], v[172:175], v[196:199], 0
	v_mfma_f32_16x16x32_bf16 v[4:7], v[164:167], v[204:207], 0
	v_mfma_f32_16x16x32_bf16 v[0:3], v[172:175], v[204:207], 0
	v_mfma_f32_16x16x32_bf16 v[52:55], v[168:171], v[184:187], v[52:55]
	v_mfma_f32_16x16x32_bf16 v[48:51], v[176:179], v[184:187], v[48:51]
	v_mfma_f32_16x16x32_bf16 v[36:39], v[168:171], v[192:195], v[36:39]
	v_mfma_f32_16x16x32_bf16 v[32:35], v[176:179], v[192:195], v[32:35]
	v_mfma_f32_16x16x32_bf16 v[20:23], v[168:171], v[200:203], v[20:23]
	v_mfma_f32_16x16x32_bf16 v[16:19], v[176:179], v[200:203], v[16:19]
	v_mfma_f32_16x16x32_bf16 v[4:7], v[168:171], v[208:211], v[4:7]
	v_mfma_f32_16x16x32_bf16 v[0:3], v[176:179], v[208:211], v[0:3]
	s_setprio 0
	s_barrier
	v_add_u32_e32 v151, s86, v145
	ds_read_b128 v[140:143], v151
	ds_read_b128 v[152:155], v151 offset:1024
	ds_read_b128 v[156:159], v151 offset:2048
	ds_read_b128 v[160:163], v151 offset:3072
	v_add_u32_e32 v151, s85, v145
	ds_read_b128 v[164:167], v151
	ds_read_b128 v[168:171], v151 offset:1024
	ds_read_b128 v[172:175], v151 offset:2048
	ds_read_b128 v[176:179], v151 offset:3072
	s_mov_b32 m0, s73
	v_lshl_add_u64 v[220:221], s[58:59], 0, v[128:129]
	ds_read_b128 v[180:183], v149 offset:32768
	ds_read_b128 v[184:187], v149 offset:33792
	ds_read_b128 v[188:191], v149 offset:34816
	ds_read_b128 v[192:195], v149 offset:35840
	ds_read_b128 v[196:199], v149 offset:36864
	ds_read_b128 v[200:203], v149 offset:37888
	ds_read_b128 v[204:207], v149 offset:38912
	ds_read_b128 v[208:211], v149 offset:39936
	global_load_lds_dwordx4 v[220:221], off
	v_lshl_add_u64 v[220:221], s[58:59], 0, v[132:133]
	s_mov_b32 m0, s74
	s_nop 0
	global_load_lds_dwordx4 v[220:221], off
	s_waitcnt vmcnt(8)
	s_waitcnt lgkmcnt(0)
	s_barrier
	s_setprio 1
	s_waitcnt lgkmcnt(0)
	v_mfma_f32_16x16x32_bf16 v[124:127], v[140:143], v[180:183], v[124:127]
	v_mfma_f32_16x16x32_bf16 v[120:123], v[156:159], v[180:183], v[120:123]
	v_mfma_f32_16x16x32_bf16 v[108:111], v[140:143], v[188:191], v[108:111]
	v_mfma_f32_16x16x32_bf16 v[104:107], v[156:159], v[188:191], v[104:107]
	v_mfma_f32_16x16x32_bf16 v[92:95], v[140:143], v[196:199], v[92:95]
	v_mfma_f32_16x16x32_bf16 v[88:91], v[156:159], v[196:199], v[88:91]
	v_mfma_f32_16x16x32_bf16 v[76:79], v[140:143], v[204:207], v[76:79]
	v_mfma_f32_16x16x32_bf16 v[72:75], v[156:159], v[204:207], v[72:75]
	v_mfma_f32_16x16x32_bf16 v[124:127], v[152:155], v[184:187], v[124:127]
	v_mfma_f32_16x16x32_bf16 v[120:123], v[160:163], v[184:187], v[120:123]
	v_mfma_f32_16x16x32_bf16 v[108:111], v[152:155], v[192:195], v[108:111]
	v_mfma_f32_16x16x32_bf16 v[104:107], v[160:163], v[192:195], v[104:107]
	v_mfma_f32_16x16x32_bf16 v[92:95], v[152:155], v[200:203], v[92:95]
	v_mfma_f32_16x16x32_bf16 v[88:91], v[160:163], v[200:203], v[88:91]
	v_mfma_f32_16x16x32_bf16 v[76:79], v[152:155], v[208:211], v[76:79]
	v_mfma_f32_16x16x32_bf16 v[72:75], v[160:163], v[208:211], v[72:75]
	s_setprio 0
	s_setprio 1
	v_mfma_f32_16x16x32_bf16 v[116:119], v[164:167], v[180:183], v[116:119]
	v_mfma_f32_16x16x32_bf16 v[112:115], v[172:175], v[180:183], v[112:115]
	v_mfma_f32_16x16x32_bf16 v[100:103], v[164:167], v[188:191], v[100:103]
	v_mfma_f32_16x16x32_bf16 v[96:99], v[172:175], v[188:191], v[96:99]
	v_mfma_f32_16x16x32_bf16 v[84:87], v[164:167], v[196:199], v[84:87]
	v_mfma_f32_16x16x32_bf16 v[80:83], v[172:175], v[196:199], v[80:83]
	v_mfma_f32_16x16x32_bf16 v[68:71], v[164:167], v[204:207], v[68:71]
	v_mfma_f32_16x16x32_bf16 v[64:67], v[172:175], v[204:207], v[64:67]
	v_mfma_f32_16x16x32_bf16 v[116:119], v[168:171], v[184:187], v[116:119]
	v_mfma_f32_16x16x32_bf16 v[112:115], v[176:179], v[184:187], v[112:115]
	v_mfma_f32_16x16x32_bf16 v[100:103], v[168:171], v[192:195], v[100:103]
	v_mfma_f32_16x16x32_bf16 v[96:99], v[176:179], v[192:195], v[96:99]
	v_mfma_f32_16x16x32_bf16 v[84:87], v[168:171], v[200:203], v[84:87]
	v_mfma_f32_16x16x32_bf16 v[80:83], v[176:179], v[200:203], v[80:83]
	v_mfma_f32_16x16x32_bf16 v[68:71], v[168:171], v[208:211], v[68:71]
	v_mfma_f32_16x16x32_bf16 v[64:67], v[176:179], v[208:211], v[64:67]
	s_setprio 0
	s_barrier
; #define PG8_STAGE(bufoff, gbase, voff) do { _Pragma("unroll") for (int _i = 0; _i < 2; ++_i) \
;         __builtin_amdgcn_global_load_lds((const unsigned*)((const char*)(gbase) + (voff)[_i]), (PG8_LAS unsigned*)(lds + (bufoff) + ldsw + _i * 8192), 16, 0, 0); } while (0)
; #define PG8_LDA(dst, b, h) do { _Pragma("unroll") for (int m = 0; m < 4; ++m) _Pragma("unroll") for (int k = 0; k < 2; ++k) dst[m][k] = *(const PG8_LAS bf16x8*)(lds + PG8_SA(b, h) + aoff + m * 2048 + k * 1024); } while (0)
; #define PG8_MMA(ai, bj, At, Bt) do { __builtin_amdgcn_s_setprio(1); _Pragma("unroll") for (int m = 0; m < 4; ++m) _Pragma("unroll") for (int n = 0; n < 2; ++n) _Pragma("unroll") for (int k = 0; k < 2; ++k) \
;         acc[ai][bj][m][n] = __builtin_amdgcn_mfma_f32_16x16x32_bf16(Bt[n][k], At[m][k], acc[ai][bj][m][n], 0, 0, 0); __builtin_amdgcn_s_setprio(0); } while (0)
; #define PG8_WAIT_V(n) asm volatile("s_waitcnt vmcnt(" #n ")" ::: "memory")
; #define PG8_WAIT_L(n) asm volatile("s_waitcnt lgkmcnt(" #n ")" ::: "memory")
; #define PG8_BAR __builtin_amdgcn_s_barrier()
; #define PG8_SCHED __builtin_amdgcn_sched_barrier(0)
; template <class Epi, class Sched, bool ALIGN_EPI = false, bool SP2 = false>
; __device__ __forceinline__ void gemm_phase(PG8_LAS unsigned char* lds, const Gemm g, const Sched& S, const Epi& E) {
;     ...
;         for (int t = 0; t < nt; t += 2) {
;             const bool last = (t == nt - 2);
;     ...
;             PG8_LDA(At, 1, 1); PG8_STAGE(PG8_SB(1, 0), b3, voffB); PG8_STAGE(PG8_SB(1, 1), b3 + hstep, voffB); PG8_STAGE(PG8_SA(1, 0), a3, voffA);
;             PG8_WAIT_V(8); PG8_WAIT_L(0); PG8_BAR; PG8_MMA(1, 0, At, B0); PG8_MMA(1, 1, At, B1); PG8_BAR; PG8_SCHED;
	s_mov_b32 m0, s31
	v_lshl_add_u64 v[212:213], v[212:213], 0, s[14:15]
	ds_read_b128 v[180:183], v149 offset:49152
	ds_read_b128 v[184:187], v149 offset:50176
	ds_read_b128 v[188:191], v149 offset:51200
	ds_read_b128 v[192:195], v149 offset:52224
	ds_read_b128 v[196:199], v149 offset:53248
	ds_read_b128 v[200:203], v149 offset:54272
	ds_read_b128 v[204:207], v149 offset:55296
	ds_read_b128 v[208:211], v149 offset:56320
	global_load_lds_dwordx4 v[212:213], off
	v_lshl_add_u64 v[212:213], v[214:215], 0, s[14:15]
	s_mov_b32 m0, s30
	s_nop 0
	global_load_lds_dwordx4 v[212:213], off
	v_lshl_add_u64 v[212:213], s[52:53], 0, v[130:131]
	s_mov_b32 m0, s92
	s_nop 0
	global_load_lds_dwordx4 v[212:213], off
	v_lshl_add_u64 v[212:213], s[52:53], 0, v[134:135]
	s_mov_b32 m0, s91
	s_nop 0
	global_load_lds_dwordx4 v[212:213], off
	v_lshl_add_u64 v[212:213], v[216:217], 0, s[14:15]
	s_mov_b32 m0, s76
	s_nop 0
	global_load_lds_dwordx4 v[212:213], off
	v_lshl_add_u64 v[212:213], v[218:219], 0, s[14:15]
	s_mov_b32 m0, s77
	s_nop 0
	global_load_lds_dwordx4 v[212:213], off
	s_waitcnt vmcnt(8)
	s_waitcnt lgkmcnt(0)
	s_barrier
	s_setprio 1
	s_waitcnt lgkmcnt(0)
	v_mfma_f32_16x16x32_bf16 v[60:63], v[140:143], v[180:183], v[60:63]
	v_mfma_f32_16x16x32_bf16 v[56:59], v[156:159], v[180:183], v[56:59]
	v_mfma_f32_16x16x32_bf16 v[44:47], v[140:143], v[188:191], v[44:47]
	v_mfma_f32_16x16x32_bf16 v[40:43], v[156:159], v[188:191], v[40:43]
	v_mfma_f32_16x16x32_bf16 v[28:31], v[140:143], v[196:199], v[28:31]
	v_mfma_f32_16x16x32_bf16 v[24:27], v[156:159], v[196:199], v[24:27]
	v_mfma_f32_16x16x32_bf16 v[12:15], v[140:143], v[204:207], v[12:15]
	v_mfma_f32_16x16x32_bf16 v[8:11], v[156:159], v[204:207], v[8:11]
	v_mfma_f32_16x16x32_bf16 v[60:63], v[152:155], v[184:187], v[60:63]
	v_mfma_f32_16x16x32_bf16 v[56:59], v[160:163], v[184:187], v[56:59]
	v_mfma_f32_16x16x32_bf16 v[44:47], v[152:155], v[192:195], v[44:47]
	v_mfma_f32_16x16x32_bf16 v[40:43], v[160:163], v[192:195], v[40:43]
	v_mfma_f32_16x16x32_bf16 v[28:31], v[152:155], v[200:203], v[28:31]
	v_mfma_f32_16x16x32_bf16 v[24:27], v[160:163], v[200:203], v[24:27]
	v_mfma_f32_16x16x32_bf16 v[12:15], v[152:155], v[208:211], v[12:15]
	v_mfma_f32_16x16x32_bf16 v[8:11], v[160:163], v[208:211], v[8:11]
	s_setprio 0
	s_setprio 1
	v_mfma_f32_16x16x32_bf16 v[52:55], v[164:167], v[180:183], v[52:55]
	v_mfma_f32_16x16x32_bf16 v[48:51], v[172:175], v[180:183], v[48:51]
	v_mfma_f32_16x16x32_bf16 v[36:39], v[164:167], v[188:191], v[36:39]
	v_mfma_f32_16x16x32_bf16 v[32:35], v[172:175], v[188:191], v[32:35]
	v_mfma_f32_16x16x32_bf16 v[20:23], v[164:167], v[196:199], v[20:23]
	v_mfma_f32_16x16x32_bf16 v[16:19], v[172:175], v[196:199], v[16:19]
	v_mfma_f32_16x16x32_bf16 v[4:7], v[164:167], v[204:207], v[4:7]
	v_mfma_f32_16x16x32_bf16 v[0:3], v[172:175], v[204:207], v[0:3]
	v_mfma_f32_16x16x32_bf16 v[52:55], v[168:171], v[184:187], v[52:55]
	v_mfma_f32_16x16x32_bf16 v[48:51], v[176:179], v[184:187], v[48:51]
	v_mfma_f32_16x16x32_bf16 v[36:39], v[168:171], v[192:195], v[36:39]
	v_mfma_f32_16x16x32_bf16 v[32:35], v[176:179], v[192:195], v[32:35]
	v_mfma_f32_16x16x32_bf16 v[20:23], v[168:171], v[200:203], v[20:23]
	v_mfma_f32_16x16x32_bf16 v[16:19], v[176:179], v[200:203], v[16:19]
	v_mfma_f32_16x16x32_bf16 v[4:7], v[168:171], v[208:211], v[4:7]
	v_mfma_f32_16x16x32_bf16 v[0:3], v[176:179], v[208:211], v[0:3]
	s_setprio 0
	s_barrier
	s_andn2_b64 vcc, exec, s[50:51]
	s_mov_b64 s[52:53], -1
	s_mov_b64 s[50:51], 0
	s_mov_b64 s[58:59], 0x100
	s_cbranch_vccz .LBB0_848
	s_branch .Lgx_g3

; #define PG8_BAR __builtin_amdgcn_s_barrier()
; template <class Epi, class Sched, bool ALIGN_EPI = false, bool SP2 = false>
; __device__ __forceinline__ void gemm_phase(PG8_LAS unsigned char* lds, const Gemm g, const Sched& S, const Epi& E) {
;     ...
;         if constexpr (ALIGN_EPI) { if (wr == 0) PG8_BAR; }
.Lgx_g3:
	s_and_b64 vcc, exec, s[16:17]
	s_cbranch_vccz .LBB0_851
	s_barrier

; __device__ __forceinline__ int opaque_tid() { int t = threadIdx.x; asm volatile("" : "+v"(t)); return t; }
; #define SBAR() __builtin_amdgcn_sched_barrier(0)
; DI int v_st64(int k, int c) { const int kk = (k & ~0xC) | ((k & 4) << 1) | ((k & 8) >> 1); return ((kk >> 3) * 2 + (c >> 5)) * 512 + ((kk & 7) * 32 + (c & 31)) * 2; }
; DI void unit(const bf16* __restrict__ QKV, const int* __restrict__ pos, bf16* __restrict__ OA, float* __restrict__ LSE,
;              int b, int h, int d, int r, int qb, float slope, char* lds) {
;   const int tid = opaque_tid(), wid = tid >> 6, lane = tid & 63, r32 = lane & 31, hi = lane >> 5;
;   const int L = SEQ / d, u0 = qb * 256;
;   char* K_lds = lds + OFF_K; char* V_lds = lds + OFF_V; int* posk = (int*)(lds + OFF_POS); float* ws = (float*)(lds + OFF_WS) + wid * 64;
;   const bf16* base = QKV + (size_t)(b * 8 + h) * SEQ * 64;
;   constexpr size_t PLANE = (size_t)NB * 8 * SEQ * 64 * 2;
;   auto stage = [&](const int i0) {
;     bf16x8 kreg[3], vreg[3];
; #pragma unroll
;     for (int i = 0; i < 3; ++i) { const int idx = tid + (i0 + i) * 512, row = idx >> 3, ch = idx & 7, v = u0 - 64 + row; const bool ok = (v >= 0) && (v < L);
;       const unsigned go = (unsigned)((r + d * (ok ? v : 0)) * 64 + ch * 8) * 2u;
;       kreg[i] = *(const bf16x8*)((const char*)base + PLANE + go); vreg[i] = *(const bf16x8*)((const char*)base + 2 * PLANE + go);
;       if (!ok) { kreg[i] = bf16x8{}; vreg[i] = bf16x8{}; } }
; #pragma unroll
;     for (int i = 0; i < 3; ++i) { const int idx = tid + (i0 + i) * 512, row = idx >> 3, ch = idx & 7;
;       *(bf16x8*)(K_lds + PSWZ(row, ch * 16)) = kreg[i]; *(bf16x8*)(V_lds + v_st64(row, ch * 8)) = vreg[i]; }
;   };
;   stage(0); SBAR(); stage(3); SBAR();
;   float pkv = 3.0e8f; if (tid < 384) { const int v = u0 - 64 + tid; if (v >= 0 && v < L) pkv = (float)pos[b * SEQ + r + d * v]; }
;   const int uq = u0 + wid * 32 + r32, tq = r + d * uq;
;   bf16x8 qr[4];
; #pragma unroll
;   for (int d0 = 0; d0 < 4; ++d0) qr[d0] = *(const bf16x8*)((const char*)base + (unsigned)(tq * 64 + d0 * 16 + hi * 8) * 2u);
;   const int pq = pos[b * SEQ + tq];
;   if (tid < 384) ((float*)posk)[tid] = pkv;
;   __syncthreads();
.LBB0_864:
	s_and_b32 s48, s47, 7
	s_bfe_u32 s30, s47, 0x30007
	s_ff1_i32_b32 s3, s8
	s_lshr_b32 s49, 0x1000, s3
	s_mov_b32 s77, s3
	s_lshl_b32 s31, s2, 8
	s_lshl_b32 s2, s48, 19
	s_lshl_b32 s3, s30, 22
	s_or_b32 s2, s3, s2
	s_add_u32 s16, s10, s2
	v_mov_b32_e32 v4, v242
	s_addc_u32 s17, s11, 0
	s_sub_i32 s50, s31, 64
	s_add_u32 s18, s16, 0x2000000
	s_addc_u32 s19, s17, 0
	s_add_u32 s20, s16, 0x4000000
	s_addc_u32 s21, s17, 0
	s_lshl_b32 s94, s30, 12
	s_or_b32 s94, s15, s94
	v_ashrrev_i32_e32 v6, 6, v4
	v_lshlrev_b32_e32 v102, 5, v6
	v_and_b32_e32 v100, 31, v4
	v_add_u32_e32 v0, s31, v102
	v_or_b32_e32 v0, v0, v100
	v_bfe_u32 v101, v4, 5, 1
	v_lshlrev_b32_e32 v0, s77, v0
	v_add_u32_e32 v7, s15, v0
	v_lshlrev_b32_e32 v92, 4, v101
	v_lshl_or_b32 v8, v7, 7, v92
	v_lshl_add_u32 v94, s30, 12, v7
	global_load_dwordx4 v[0:3], v8, s[16:17]
	global_load_dwordx4 v[88:91], v8, s[16:17] offset:32
	global_load_dwordx4 v[84:87], v8, s[16:17] offset:64
	global_load_dwordx4 v[80:83], v8, s[16:17] offset:96
	v_ashrrev_i32_e32 v95, 31, v94
	v_lshl_add_u64 v[8:9], v[94:95], 2, s[40:41]
	global_load_dword v103, v[8:9], off
	v_add_u32_e32 v214, s50, v234
	s_add_i32 s95, s50, 64
	v_add_u32_e32 v215, s95, v234
	s_add_i32 s95, s50, 128
	v_add_u32_e32 v216, s95, v234
	s_add_i32 s95, s50, 192
	v_add_u32_e32 v217, s95, v234
	s_add_i32 s95, s50, 256
	v_add_u32_e32 v218, s95, v234
	s_add_i32 s95, s50, 320
	v_add_u32_e32 v219, s95, v234
	v_add_u32_e32 v220, s50, v4
	v_cmp_gt_u32_e64 s[80:81], s49, v214
	v_cmp_gt_u32_e64 s[82:83], s49, v215
	v_cmp_gt_u32_e64 s[84:85], s49, v216
	v_cmp_gt_u32_e64 s[86:87], s49, v217
	v_cmp_gt_u32_e64 s[88:89], s49, v218
	v_cmp_gt_u32_e64 s[90:91], s49, v219
	v_cmp_gt_u32_e64 s[92:93], s49, v220
	v_cmp_gt_i32_e32 vcc, s42, v4
	v_cndmask_b32_e64 v214, 0, v214, s[80:81]
	v_cndmask_b32_e64 v215, 0, v215, s[82:83]
	v_cndmask_b32_e64 v216, 0, v216, s[84:85]
	v_cndmask_b32_e64 v217, 0, v217, s[86:87]
	v_cndmask_b32_e64 v218, 0, v218, s[88:89]
	v_cndmask_b32_e64 v219, 0, v219, s[90:91]
	s_and_b64 s[92:93], s[92:93], vcc
	v_lshlrev_b32_e32 v214, s77, v214
	v_lshlrev_b32_e32 v215, s77, v215
	v_lshlrev_b32_e32 v216, s77, v216
	v_lshlrev_b32_e32 v217, s77, v217
	v_lshlrev_b32_e32 v218, s77, v218
	v_lshlrev_b32_e32 v219, s77, v219
	v_cndmask_b32_e64 v220, 0, v220, s[92:93]
	v_add_u32_e32 v214, s15, v214
	v_add_u32_e32 v215, s15, v215
	v_add_u32_e32 v216, s15, v216
	v_add_u32_e32 v217, s15, v217
	v_add_u32_e32 v218, s15, v218
	v_add_u32_e32 v219, s15, v219
	v_lshlrev_b32_e32 v220, s77, v220
	v_lshl_or_b32 v214, v214, 7, v235
	v_lshl_or_b32 v215, v215, 7, v235
	v_lshl_or_b32 v216, v216, 7, v235
	v_lshl_or_b32 v217, v217, 7, v235
	v_lshl_or_b32 v218, v218, 7, v235
	v_lshl_or_b32 v219, v219, 7, v235
	v_add_lshl_u32 v220, v220, s94, 2
	global_load_dwordx4 v[164:167], v214, s[18:19]
	global_load_dwordx4 v[168:171], v214, s[20:21]
	global_load_dwordx4 v[172:175], v215, s[18:19]
	global_load_dwordx4 v[176:179], v215, s[20:21]
	global_load_dwordx4 v[180:183], v216, s[18:19]
	global_load_dwordx4 v[184:187], v216, s[20:21]
	global_load_dwordx4 v[188:191], v217, s[18:19]
	global_load_dwordx4 v[192:195], v217, s[20:21]
	global_load_dwordx4 v[196:199], v218, s[18:19]
	global_load_dwordx4 v[200:203], v218, s[20:21]
	global_load_dwordx4 v[204:207], v219, s[18:19]
	global_load_dwordx4 v[208:211], v219, s[20:21]
	global_load_dword v213, v220, s[40:41]
	s_waitcnt vmcnt(11)
	ds_write_b128 v222, v[164:167]
	ds_write_b128 v223, v[168:171]
	s_waitcnt vmcnt(9)
	ds_write_b128 v222, v[172:175] offset:8192
	ds_write_b128 v223, v[176:179] offset:8192
	s_waitcnt vmcnt(7)
	ds_write_b128 v222, v[180:183] offset:16384
	ds_write_b128 v223, v[184:187] offset:16384
	s_waitcnt vmcnt(5)
	ds_write_b128 v222, v[188:191] offset:24576
	ds_write_b128 v223, v[192:195] offset:24576
	s_waitcnt vmcnt(3)
	ds_write_b128 v222, v[196:199] offset:32768
	ds_write_b128 v223, v[200:203] offset:32768
	s_waitcnt vmcnt(1)
	ds_write_b128 v222, v[204:207] offset:40960
	ds_write_b128 v223, v[208:211] offset:40960
	s_waitcnt vmcnt(0)
	v_cmp_gt_i32_e32 vcc, s42, v4
	v_cvt_f32_i32_e32 v213, v213
	v_mov_b32_e32 v5, 0x4d8f0d18
	v_cndmask_b32_e64 v5, v5, v213, s[92:93]
	s_and_saveexec_b64 s[2:3], vcc
	v_lshl_add_u32 v7, v4, 2, 0
	v_add_u32_e32 v7, 0x18000, v7
	ds_write_b32 v7, v5
	s_or_b64 exec, exec, s[2:3]
	v_lshlrev_b32_e32 v5, 3, v4
	v_lshlrev_b32_e32 v99, 12, v6
	v_bitop3_b32 v7, v92, v5, s39 bitop3:0x78
	v_lshl_or_b32 v14, v100, 7, v99
	v_add3_u32 v15, 0, v7, v14
	s_waitcnt lgkmcnt(0)
	s_barrier
; #define SBAR() __builtin_amdgcn_sched_barrier(0)
; DI void unit(const bf16* __restrict__ QKV, const int* __restrict__ pos, bf16* __restrict__ OA, float* __restrict__ LSE,
;              int b, int h, int d, int r, int qb, float slope, char* lds) {
;     ...
;   f32x16 p[5];
; #pragma unroll
;   for (int ta = 0; ta < 5; ++ta) { p[ta] = f32x16{};
; #pragma unroll
;     for (int d0 = 0; d0 < 4; ++d0) { const bf16x8 a = *(const bf16x8*)(K_lds + PSWZ(wid * 32 + ta * 32 + r32, (d0 * 16 + hi * 8) * 2));
;       p[ta] = __builtin_amdgcn_mfma_f32_32x32x16_bf16(a, qr[d0], p[ta], 0, 0, 0); }
;     SBAR(); }
;   const float C = 0.125f * 1.4426950408889634f, sl2 = slope * 1.4426950408889634f;
;   const float* pbase = (const float*)posk + wid * 32 + 4 * hi; const float pqf = (float)pq;
;   float mx = -1e30f;
; #pragma unroll
;   for (int ta = 0; ta < 5; ++ta) {
; #pragma unroll
;     for (int g = 0; g < 4; ++g) { const f32x4 pk4 = *(const f32x4*)(pbase + ta * 32 + 8 * g);
; #pragma unroll
;       for (int j = 0; j < 4; ++j) { const int rr = 4 * g + j, kr = j + 8 * g + 4 * hi;
;         float sc = fmaf(__builtin_fabsf(pqf - pk4[j]), -sl2, p[ta][rr] * C);
;         if (ta == 0) sc = (kr >= r32) ? sc : -1e30f;
;         if (ta == 4) sc = (kr <= r32) ? sc : -1e30f;
;         p[ta][rr] = sc; mx = fmaxf(mx, sc); } }
	ds_read_b128 v[6:9], v15
	v_and_b32_e32 v5, 0x70, v5
	v_bitop3_b32 v10, v92, v5, 32 bitop3:0x36
	v_add3_u32 v104, 0, v10, v14
	ds_read_b128 v[10:13], v104
	s_waitcnt vmcnt(4) lgkmcnt(1)
	v_mfma_f32_32x32x16_bf16 v[64:79], v[6:9], v[0:3], 0
	v_bitop3_b32 v6, v92, v5, 64 bitop3:0x36
	v_add3_u32 v108, 0, v6, v14
	ds_read_b128 v[6:9], v108
	v_bitop3_b32 v5, v92, v5, s44 bitop3:0x36
	v_add3_u32 v109, 0, v5, v14
	s_add_i32 s2, s48, 1
	v_cvt_f32_ubyte0_e32 v16, s2
	s_waitcnt vmcnt(3) lgkmcnt(1)
	v_mfma_f32_32x32x16_bf16 v[64:79], v[10:13], v[88:91], v[64:79]
	ds_read_b128 v[10:13], v109
	v_cmp_lt_f32_e32 vcc, s43, v16
	s_and_b64 s[2:3], vcc, exec
	s_cselect_b32 s2, 0xffffffc0, 0
	v_cndmask_b32_e32 v17, 0, v96, vcc
	v_sub_f32_e32 v5, v17, v16
	v_exp_f32_e32 v5, v5
	s_waitcnt vmcnt(2) lgkmcnt(1)
	v_mfma_f32_32x32x16_bf16 v[64:79], v[6:9], v[84:87], v[64:79]
	s_ashr_i32 s15, s14, 31
	v_and_b32_e32 v98, 63, v4
	v_ldexp_f32 v110, v5, s2
	s_waitcnt vmcnt(1) lgkmcnt(0)
	v_mfma_f32_32x32x16_bf16 v[64:79], v[10:13], v[80:83], v[64:79]
	ds_read_b128 v[4:7], v15 offset:4096
	ds_read_b128 v[8:11], v104 offset:4096
	s_waitcnt lgkmcnt(1)
	v_mfma_f32_32x32x16_bf16 v[48:63], v[4:7], v[0:3], 0
	s_waitcnt lgkmcnt(0)
	v_mfma_f32_32x32x16_bf16 v[48:63], v[8:11], v[88:91], v[48:63]
	ds_read_b128 v[4:7], v108 offset:4096
	ds_read_b128 v[8:11], v109 offset:4096
	s_waitcnt lgkmcnt(1)
	v_mfma_f32_32x32x16_bf16 v[48:63], v[4:7], v[84:87], v[48:63]
	s_waitcnt lgkmcnt(0)
	v_mfma_f32_32x32x16_bf16 v[48:63], v[8:11], v[80:83], v[48:63]
	ds_read_b128 v[4:7], v15 offset:8192
	ds_read_b128 v[8:11], v104 offset:8192
	s_waitcnt lgkmcnt(1)
	v_mfma_f32_32x32x16_bf16 v[32:47], v[4:7], v[0:3], 0
	s_waitcnt lgkmcnt(0)
	v_mfma_f32_32x32x16_bf16 v[32:47], v[8:11], v[88:91], v[32:47]
	ds_read_b128 v[4:7], v108 offset:8192
	ds_read_b128 v[8:11], v109 offset:8192
	s_waitcnt lgkmcnt(1)
	v_mfma_f32_32x32x16_bf16 v[32:47], v[4:7], v[84:87], v[32:47]
	s_waitcnt lgkmcnt(0)
	v_mfma_f32_32x32x16_bf16 v[32:47], v[8:11], v[80:83], v[32:47]
	ds_read_b128 v[4:7], v15 offset:12288
	ds_read_b128 v[8:11], v104 offset:12288
	s_waitcnt lgkmcnt(1)
	v_mfma_f32_32x32x16_bf16 v[16:31], v[4:7], v[0:3], 0
	s_waitcnt lgkmcnt(0)
	v_mfma_f32_32x32x16_bf16 v[16:31], v[8:11], v[88:91], v[16:31]
	ds_read_b128 v[4:7], v108 offset:12288
	ds_read_b128 v[8:11], v109 offset:12288
	s_waitcnt lgkmcnt(1)
	v_mfma_f32_32x32x16_bf16 v[16:31], v[4:7], v[84:87], v[16:31]
	s_waitcnt lgkmcnt(0)
	v_mfma_f32_32x32x16_bf16 v[16:31], v[8:11], v[80:83], v[16:31]
	ds_read_b128 v[4:7], v15 offset:16384
	ds_read_b128 v[104:107], v104 offset:16384
	s_waitcnt lgkmcnt(1)
	v_mfma_f32_32x32x16_bf16 v[0:15], v[4:7], v[0:3], 0
	s_waitcnt lgkmcnt(0)
	v_mfma_f32_32x32x16_bf16 v[0:15], v[104:107], v[88:91], v[0:15]
	ds_read_b128 v[88:91], v108 offset:16384
	ds_read_b128 v[104:107], v109 offset:16384
	s_waitcnt lgkmcnt(1)
	v_mfma_f32_32x32x16_bf16 v[0:15], v[88:91], v[84:87], v[0:15]
	s_waitcnt lgkmcnt(0)
	v_mfma_f32_32x32x16_bf16 v[0:15], v[104:107], v[80:83], v[0:15]
	v_lshlrev_b32_e32 v80, 2, v102
	v_add3_u32 v88, s46, v80, v92
	ds_read_b128 v[80:83], v88
	ds_read_b128 v[84:87], v88 offset:32
	s_waitcnt vmcnt(0)
	v_cvt_f32_i32_e32 v89, v103
	v_lshlrev_b32_e32 v90, 2, v101
	v_mul_f32_e32 v91, 0xbfb8aa3b, v110
	v_fma_f32 v64, v64, s76, v134
	s_waitcnt lgkmcnt(1)
	v_sub_f32_e32 v80, v89, v80
	v_fma_f32 v80, |v80|, v91, v64
	v_sub_f32_e32 v81, v89, v81
	v_fma_f32 v65, v65, s76, v135
	v_fma_f32 v81, |v81|, v91, v65
	v_fma_f32 v66, v66, s76, v136
	v_sub_f32_e32 v65, v89, v82
	v_fma_f32 v82, |v65|, v91, v66
	v_fma_f32 v66, v67, s76, v137
	v_sub_f32_e32 v65, v89, v83
	v_fma_f32 v83, |v65|, v91, v66
	v_fma_f32 v66, v68, s76, v138
	s_waitcnt lgkmcnt(0)
	v_sub_f32_e32 v65, v89, v84
	v_fma_f32 v84, |v65|, v91, v66
	v_fma_f32 v66, v69, s76, v139
	v_sub_f32_e32 v65, v89, v85
	v_max3_f32 v64, v80, s45, v81
	v_fma_f32 v85, |v65|, v91, v66
	v_max3_f32 v64, v64, v82, v83
	v_max3_f32 v68, v64, v84, v85
	v_sub_f32_e32 v64, v89, v86
	v_fma_f32 v65, v70, s76, v140
	v_fma_f32 v86, |v64|, v91, v65
	v_fma_f32 v65, v71, s76, v141
	v_sub_f32_e32 v64, v89, v87
	v_fma_f32 v87, |v64|, v91, v65
	ds_read_b128 v[64:67], v88 offset:64
	v_fma_f32 v72, v72, s76, v142
	v_max3_f32 v107, v68, v86, v87
	ds_read_b128 v[68:71], v88 offset:96
	s_waitcnt lgkmcnt(1)
	v_sub_f32_e32 v64, v89, v64
	v_fma_f32 v72, |v64|, v91, v72
	v_sub_f32_e32 v64, v89, v65
	v_fma_f32 v65, v73, s76, v143
	v_fma_f32 v73, |v64|, v91, v65
	v_sub_f32_e32 v65, v89, v66
	v_fma_f32 v66, v74, s76, v144
	v_max3_f32 v64, v107, v72, v73
	v_fma_f32 v74, |v65|, v91, v66
	v_fma_f32 v66, v75, s76, v145
	v_sub_f32_e32 v65, v89, v67
	v_fma_f32 v75, |v65|, v91, v66
	v_fma_f32 v66, v76, s76, v148
	s_waitcnt lgkmcnt(0)
	v_sub_f32_e32 v65, v89, v68
	v_fma_f32 v76, |v65|, v91, v66
	v_fma_f32 v66, v77, s76, v149
	v_sub_f32_e32 v65, v89, v69
	v_fma_f32 v77, |v65|, v91, v66
	v_fma_f32 v66, v78, s76, v150
	v_sub_f32_e32 v65, v89, v70
	v_fma_f32 v78, |v65|, v91, v66
	v_fma_f32 v66, v79, s76, v152
	v_max3_f32 v64, v64, v74, v75
	v_sub_f32_e32 v65, v89, v71
	v_fma_f32 v79, |v65|, v91, v66
	v_max3_f32 v64, v64, v76, v77
	s_nop 0
	v_max3_f32 v115, v64, v78, v79
	ds_read_b128 v[64:67], v88 offset:128
	ds_read_b128 v[68:71], v88 offset:160
	v_mul_f32_e32 v49, s76, v49
	v_mul_f32_e32 v50, s76, v50
	v_mul_f32_e32 v48, s76, v48
	s_waitcnt lgkmcnt(1)
	v_sub_f32_e32 v65, v89, v65
	v_fma_f32 v65, |v65|, v91, v49
	v_sub_f32_e32 v49, v89, v66
	v_sub_f32_e32 v64, v89, v64
	v_fma_f32 v66, |v49|, v91, v50
	v_sub_f32_e32 v49, v89, v67
	v_mul_f32_e32 v50, s76, v51
	v_fma_f32 v64, |v64|, v91, v48
	v_fma_f32 v67, |v49|, v91, v50
	s_waitcnt lgkmcnt(0)
; DI void unit(const bf16* __restrict__ QKV, const int* __restrict__ pos, bf16* __restrict__ OA, float* __restrict__ LSE,
;              int b, int h, int d, int r, int qb, float slope, char* lds) {
;     ...
;   for (int ta = 0; ta < 5; ++ta) {
; #pragma unroll
;     for (int g = 0; g < 4; ++g) { const f32x4 pk4 = *(const f32x4*)(pbase + ta * 32 + 8 * g);
; #pragma unroll
;       for (int j = 0; j < 4; ++j) { const int rr = 4 * g + j, kr = j + 8 * g + 4 * hi;
;         float sc = fmaf(__builtin_fabsf(pqf - pk4[j]), -sl2, p[ta][rr] * C);
;         if (ta == 0) sc = (kr >= r32) ? sc : -1e30f;
;         if (ta == 4) sc = (kr <= r32) ? sc : -1e30f;
;         p[ta][rr] = sc; mx = fmaxf(mx, sc); } }
	v_sub_f32_e32 v49, v89, v68
	v_mul_f32_e32 v50, s76, v52
	v_max3_f32 v48, v115, v64, v65
	v_fma_f32 v68, |v49|, v91, v50
	v_sub_f32_e32 v49, v89, v69
	v_mul_f32_e32 v50, s76, v53
	v_max3_f32 v48, v48, v66, v67
	v_fma_f32 v69, |v49|, v91, v50
	v_max3_f32 v52, v48, v68, v69
	v_sub_f32_e32 v48, v89, v70
	v_mul_f32_e32 v49, s76, v54
	v_fma_f32 v70, |v48|, v91, v49
	ds_read_b128 v[48:51], v88 offset:192
	v_sub_f32_e32 v53, v89, v71
	v_mul_f32_e32 v54, s76, v55
	v_fma_f32 v71, |v53|, v91, v54
	v_max3_f32 v115, v52, v70, v71
	ds_read_b128 v[52:55], v88 offset:224
	s_waitcnt lgkmcnt(1)
	v_sub_f32_e32 v48, v89, v48
	v_mul_f32_e32 v56, s76, v56
	v_fma_f32 v56, |v48|, v91, v56
	v_sub_f32_e32 v48, v89, v49
	v_mul_f32_e32 v49, s76, v57
	v_fma_f32 v57, |v48|, v91, v49
	v_sub_f32_e32 v49, v89, v50
	v_mul_f32_e32 v50, s76, v58
	v_fma_f32 v58, |v49|, v91, v50
	v_sub_f32_e32 v49, v89, v51
	v_mul_f32_e32 v50, s76, v59
	v_fma_f32 v59, |v49|, v91, v50
	s_waitcnt lgkmcnt(0)
	v_sub_f32_e32 v49, v89, v52
	v_mul_f32_e32 v50, s76, v60
	v_fma_f32 v60, |v49|, v91, v50
	v_sub_f32_e32 v49, v89, v53
	v_mul_f32_e32 v50, s76, v61
	v_max3_f32 v48, v115, v56, v57
	v_fma_f32 v61, |v49|, v91, v50
	v_sub_f32_e32 v49, v89, v54
	v_mul_f32_e32 v50, s76, v62
	v_max3_f32 v48, v48, v58, v59
	v_fma_f32 v62, |v49|, v91, v50
	v_sub_f32_e32 v49, v89, v55
	v_mul_f32_e32 v50, s76, v63
	v_max3_f32 v48, v48, v60, v61
	v_fma_f32 v63, |v49|, v91, v50
	v_max3_f32 v115, v48, v62, v63
	ds_read_b128 v[48:51], v88 offset:256
	ds_read_b128 v[52:55], v88 offset:288
	v_mul_f32_e32 v33, s76, v33
	v_mul_f32_e32 v34, s76, v34
	v_mul_f32_e32 v32, s76, v32
	s_waitcnt lgkmcnt(1)
	v_sub_f32_e32 v49, v89, v49
	v_fma_f32 v49, |v49|, v91, v33
	v_sub_f32_e32 v33, v89, v50
	v_sub_f32_e32 v48, v89, v48
	v_fma_f32 v50, |v33|, v91, v34
	v_sub_f32_e32 v33, v89, v51
	v_mul_f32_e32 v34, s76, v35
	v_fma_f32 v48, |v48|, v91, v32
	v_fma_f32 v51, |v33|, v91, v34
	s_waitcnt lgkmcnt(0)
	v_sub_f32_e32 v33, v89, v52
	v_mul_f32_e32 v34, s76, v36
	v_max3_f32 v32, v115, v48, v49
	v_fma_f32 v52, |v33|, v91, v34
	v_sub_f32_e32 v33, v89, v53
	v_mul_f32_e32 v34, s76, v37
	v_max3_f32 v32, v32, v50, v51
	v_fma_f32 v53, |v33|, v91, v34
	v_max3_f32 v36, v32, v52, v53
	v_sub_f32_e32 v32, v89, v54
	v_mul_f32_e32 v33, s76, v38
	v_fma_f32 v54, |v32|, v91, v33
	ds_read_b128 v[32:35], v88 offset:320
	v_sub_f32_e32 v37, v89, v55
	v_mul_f32_e32 v38, s76, v39
	v_fma_f32 v55, |v37|, v91, v38
	v_max3_f32 v115, v36, v54, v55
	ds_read_b128 v[36:39], v88 offset:352
	s_waitcnt lgkmcnt(1)
	v_sub_f32_e32 v32, v89, v32
	v_mul_f32_e32 v40, s76, v40
	v_fma_f32 v40, |v32|, v91, v40
	v_sub_f32_e32 v32, v89, v33
	v_mul_f32_e32 v33, s76, v41
	v_fma_f32 v41, |v32|, v91, v33
	v_sub_f32_e32 v33, v89, v34
	v_mul_f32_e32 v34, s76, v42
	v_fma_f32 v42, |v33|, v91, v34
	v_sub_f32_e32 v33, v89, v35
	v_mul_f32_e32 v34, s76, v43
	v_fma_f32 v43, |v33|, v91, v34
	s_waitcnt lgkmcnt(0)
	v_sub_f32_e32 v33, v89, v36
	v_mul_f32_e32 v34, s76, v44
	v_fma_f32 v44, |v33|, v91, v34
	v_sub_f32_e32 v33, v89, v37
	v_mul_f32_e32 v34, s76, v45
	v_max3_f32 v32, v115, v40, v41
	v_fma_f32 v45, |v33|, v91, v34
	v_sub_f32_e32 v33, v89, v38
	v_mul_f32_e32 v34, s76, v46
	v_max3_f32 v32, v32, v42, v43
	v_fma_f32 v46, |v33|, v91, v34
	v_sub_f32_e32 v33, v89, v39
	v_mul_f32_e32 v34, s76, v47
	v_max3_f32 v32, v32, v44, v45
	v_fma_f32 v47, |v33|, v91, v34
	v_max3_f32 v115, v32, v46, v47
	ds_read_b128 v[32:35], v88 offset:384
	ds_read_b128 v[36:39], v88 offset:416
	v_mul_f32_e32 v17, s76, v17
	v_mul_f32_e32 v18, s76, v18
	v_mul_f32_e32 v16, s76, v16
	s_waitcnt lgkmcnt(1)
	v_sub_f32_e32 v33, v89, v33
	v_fma_f32 v33, |v33|, v91, v17
	v_sub_f32_e32 v17, v89, v34
	v_sub_f32_e32 v32, v89, v32
	v_fma_f32 v34, |v17|, v91, v18
	v_sub_f32_e32 v17, v89, v35
	v_mul_f32_e32 v18, s76, v19
	v_fma_f32 v116, |v32|, v91, v16
	v_fma_f32 v35, |v17|, v91, v18
	s_waitcnt lgkmcnt(0)
	v_sub_f32_e32 v17, v89, v36
	v_mul_f32_e32 v18, s76, v20
	v_max3_f32 v16, v115, v116, v33
	v_fma_f32 v36, |v17|, v91, v18
	v_sub_f32_e32 v17, v89, v37
	v_mul_f32_e32 v18, s76, v21
	v_max3_f32 v16, v16, v34, v35
	v_fma_f32 v37, |v17|, v91, v18
	v_max3_f32 v20, v16, v36, v37
	v_sub_f32_e32 v16, v89, v38
	v_mul_f32_e32 v17, s76, v22
	v_fma_f32 v38, |v16|, v91, v17
	ds_read_b128 v[16:19], v88 offset:448
	v_sub_f32_e32 v21, v89, v39
	v_mul_f32_e32 v22, s76, v23
	v_fma_f32 v39, |v21|, v91, v22
	v_max3_f32 v32, v20, v38, v39
	ds_read_b128 v[20:23], v88 offset:480
	s_waitcnt lgkmcnt(1)
	v_sub_f32_e32 v16, v89, v16
	v_mul_f32_e32 v24, s76, v24
	v_fma_f32 v24, |v16|, v91, v24
	v_sub_f32_e32 v16, v89, v17
	v_mul_f32_e32 v17, s76, v25
	v_fma_f32 v25, |v16|, v91, v17
	v_sub_f32_e32 v17, v89, v18
	v_mul_f32_e32 v18, s76, v26
	v_fma_f32 v26, |v17|, v91, v18
	v_sub_f32_e32 v17, v89, v19
	v_mul_f32_e32 v18, s76, v27
	v_fma_f32 v27, |v17|, v91, v18
	s_waitcnt lgkmcnt(0)
	v_sub_f32_e32 v17, v89, v20
	v_mul_f32_e32 v18, s76, v28
	v_fma_f32 v28, |v17|, v91, v18
	v_sub_f32_e32 v17, v89, v21
	v_mul_f32_e32 v18, s76, v29
	v_max3_f32 v16, v32, v24, v25
	v_fma_f32 v29, |v17|, v91, v18
	v_sub_f32_e32 v17, v89, v22
	v_mul_f32_e32 v18, s76, v30
	v_max3_f32 v16, v16, v26, v27
	v_fma_f32 v30, |v17|, v91, v18
	v_sub_f32_e32 v17, v89, v23
	v_mul_f32_e32 v18, s76, v31
	v_max3_f32 v16, v16, v28, v29
	v_fma_f32 v31, |v17|, v91, v18
	v_max3_f32 v32, v16, v30, v31
	ds_read_b128 v[16:19], v88 offset:512
	ds_read_b128 v[20:23], v88 offset:544
	v_fma_f32 v0, v0, s76, v153
	v_fma_f32 v2, v2, s76, v155
	s_waitcnt lgkmcnt(1)
; #define SBAR() __builtin_amdgcn_sched_barrier(0)
; DI void unit(const bf16* __restrict__ QKV, const int* __restrict__ pos, bf16* __restrict__ OA, float* __restrict__ LSE,
;              int b, int h, int d, int r, int qb, float slope, char* lds) {
;     ...
;   for (int ta = 0; ta < 5; ++ta) {
; #pragma unroll
;     for (int g = 0; g < 4; ++g) { const f32x4 pk4 = *(const f32x4*)(pbase + ta * 32 + 8 * g);
; #pragma unroll
;       for (int j = 0; j < 4; ++j) { const int rr = 4 * g + j, kr = j + 8 * g + 4 * hi;
;         float sc = fmaf(__builtin_fabsf(pqf - pk4[j]), -sl2, p[ta][rr] * C);
;         if (ta == 0) sc = (kr >= r32) ? sc : -1e30f;
;         if (ta == 4) sc = (kr <= r32) ? sc : -1e30f;
;         p[ta][rr] = sc; mx = fmaxf(mx, sc); } }
;     SBAR(); }
;   { auto x = __builtin_amdgcn_permlane32_swap(__float_as_uint(mx), __float_as_uint(mx), false, false); mx = fmaxf(__uint_as_float(x[0]), __uint_as_float(x[1])); }
;   float ls = 0.f;
; #pragma unroll
;   for (int ta = 0; ta < 5; ++ta)
; #pragma unroll
;     for (int rr = 0; rr < 16; ++rr) { p[ta][rr] = __builtin_amdgcn_exp2f(p[ta][rr] - mx); ls += p[ta][rr]; if (rr == 15) SBAR(); }
;   { auto x = __builtin_amdgcn_permlane32_swap(__float_as_uint(ls), __float_as_uint(ls), false, false); ls = __uint_as_float(x[0]) + __uint_as_float(x[1]); }
	v_sub_f32_e32 v16, v89, v16
	v_fma_f32 v16, |v16|, v91, v0
	v_sub_f32_e32 v17, v89, v17
	v_fma_f32 v0, v1, s76, v154
	v_fma_f32 v17, |v17|, v91, v0
	v_sub_f32_e32 v1, v89, v18
	v_fma_f32 v18, |v1|, v91, v2
	v_fma_f32 v2, v3, s76, v156
	v_max3_f32 v0, v32, v16, v17
	v_sub_f32_e32 v1, v89, v19
	v_fma_f32 v19, |v1|, v91, v2
	v_fma_f32 v2, v4, s76, v157
	v_fma_f32 v8, v8, s76, v163
	s_waitcnt lgkmcnt(0)
	v_sub_f32_e32 v1, v89, v20
	v_fma_f32 v20, |v1|, v91, v2
	v_fma_f32 v2, v5, s76, v158
	v_max3_f32 v0, v0, v18, v19
	v_sub_f32_e32 v1, v89, v21
	v_fma_f32 v21, |v1|, v91, v2
	s_nop 1
	v_max3_f32 v4, v0, v20, v21
	v_sub_f32_e32 v0, v89, v22
	v_fma_f32 v1, v6, s76, v159
	v_fma_f32 v22, |v0|, v91, v1
	v_fma_f32 v1, v7, s76, v162
	s_nop 0
	v_sub_f32_e32 v0, v89, v23
	v_fma_f32 v23, |v0|, v91, v1
	ds_read_b128 v[0:3], v88 offset:576
	s_nop 1
	v_max3_f32 v32, v4, v22, v23
	ds_read_b128 v[4:7], v88 offset:608
	s_waitcnt lgkmcnt(1)
	v_sub_f32_e32 v0, v89, v0
	v_fma_f32 v0, |v0|, v91, v8
	v_sub_f32_e32 v1, v89, v1
	v_fma_f32 v8, v9, s76, v227
	v_fma_f32 v1, |v1|, v91, v8
	v_sub_f32_e32 v2, v89, v2
	v_fma_f32 v9, v10, s76, v228
	v_fma_f32 v2, |v2|, v91, v9
	v_sub_f32_e32 v3, v89, v3
	v_fma_f32 v9, v11, s76, v229
	v_fma_f32 v3, |v3|, v91, v9
	s_waitcnt lgkmcnt(0)
	v_sub_f32_e32 v4, v89, v4
	v_fma_f32 v9, v12, s76, v230
	v_fma_f32 v4, |v4|, v91, v9
	v_sub_f32_e32 v5, v89, v5
	v_fma_f32 v9, v13, s76, v231
	v_fma_f32 v5, |v5|, v91, v9
	v_sub_f32_e32 v6, v89, v6
	v_fma_f32 v9, v14, s76, v232
	v_max3_f32 v8, v32, v0, v1
	v_fma_f32 v6, |v6|, v91, v9
	v_sub_f32_e32 v7, v89, v7
	v_fma_f32 v9, v15, s76, v233
	v_max3_f32 v8, v8, v2, v3
	v_fma_f32 v7, |v7|, v91, v9
	v_max3_f32 v8, v8, v4, v5
	s_nop 0
	v_max3_f32 v8, v8, v6, v7
	v_mov_b32_e32 v9, v8
	s_nop 1
	v_permlane32_swap_b32_e32 v8, v9
	v_max_f32_e32 v9, v9, v9
	v_max_f32_e32 v8, v8, v8
	v_max_f32_e32 v32, v8, v9
	v_sub_f32_e32 v8, v80, v32
	v_exp_f32_e32 v8, v8
	v_sub_f32_e32 v9, v81, v32
	v_exp_f32_e32 v9, v9
	v_sub_f32_e32 v10, v82, v32
	v_exp_f32_e32 v10, v10
	v_sub_f32_e32 v11, v83, v32
	v_exp_f32_e32 v11, v11
	v_sub_f32_e32 v12, v84, v32
	v_exp_f32_e32 v12, v12
	v_sub_f32_e32 v13, v85, v32
	v_add_f32_e32 v80, 0, v8
	v_exp_f32_e32 v13, v13
	v_sub_f32_e32 v14, v86, v32
	v_add_f32_e32 v80, v9, v80
	v_exp_f32_e32 v14, v14
	v_sub_f32_e32 v15, v87, v32
	v_add_f32_e32 v80, v10, v80
	v_exp_f32_e32 v15, v15
	v_sub_f32_e32 v72, v72, v32
	v_add_f32_e32 v80, v11, v80
	v_exp_f32_e32 v72, v72
	v_sub_f32_e32 v73, v73, v32
	v_add_f32_e32 v80, v12, v80
	v_exp_f32_e32 v73, v73
	v_sub_f32_e32 v74, v74, v32
	v_add_f32_e32 v80, v13, v80
	v_exp_f32_e32 v74, v74
	v_sub_f32_e32 v75, v75, v32
	v_add_f32_e32 v80, v14, v80
	v_exp_f32_e32 v75, v75
	v_sub_f32_e32 v76, v76, v32
	v_add_f32_e32 v80, v15, v80
	v_exp_f32_e32 v76, v76
	v_sub_f32_e32 v77, v77, v32
	v_add_f32_e32 v80, v72, v80
	v_exp_f32_e32 v77, v77
	v_sub_f32_e32 v78, v78, v32
	v_add_f32_e32 v80, v73, v80
	v_exp_f32_e32 v78, v78
	v_add_f32_e32 v80, v74, v80
	v_sub_f32_e32 v79, v79, v32
	v_add_f32_e32 v80, v75, v80
	v_exp_f32_e32 v79, v79
	v_add_f32_e32 v80, v76, v80
	v_add_f32_e32 v80, v77, v80
	v_add_f32_e32 v80, v78, v80
	v_add_f32_e32 v80, v79, v80
	v_sub_f32_e32 v64, v64, v32
	v_exp_f32_e32 v64, v64
	v_sub_f32_e32 v65, v65, v32
	v_exp_f32_e32 v65, v65
	v_sub_f32_e32 v66, v66, v32
	v_exp_f32_e32 v66, v66
	v_sub_f32_e32 v67, v67, v32
	v_exp_f32_e32 v67, v67
	v_sub_f32_e32 v68, v68, v32
	v_exp_f32_e32 v68, v68
	v_sub_f32_e32 v69, v69, v32
	v_add_f32_e32 v80, v64, v80
	v_exp_f32_e32 v69, v69
	v_sub_f32_e32 v70, v70, v32
	v_add_f32_e32 v80, v65, v80
	v_exp_f32_e32 v70, v70
	v_sub_f32_e32 v71, v71, v32
	v_add_f32_e32 v80, v66, v80
	v_exp_f32_e32 v71, v71
	v_sub_f32_e32 v56, v56, v32
	v_add_f32_e32 v80, v67, v80
	v_exp_f32_e32 v56, v56
	v_sub_f32_e32 v57, v57, v32
	v_add_f32_e32 v80, v68, v80
	v_exp_f32_e32 v57, v57
	v_sub_f32_e32 v58, v58, v32
	v_add_f32_e32 v80, v69, v80
	v_exp_f32_e32 v58, v58
	v_sub_f32_e32 v59, v59, v32
	v_add_f32_e32 v80, v70, v80
	v_exp_f32_e32 v59, v59
	v_sub_f32_e32 v60, v60, v32
	v_add_f32_e32 v80, v71, v80
	v_exp_f32_e32 v60, v60
	v_sub_f32_e32 v61, v61, v32
	v_add_f32_e32 v80, v56, v80
	v_exp_f32_e32 v61, v61
	v_sub_f32_e32 v62, v62, v32
	v_add_f32_e32 v80, v57, v80
	v_exp_f32_e32 v62, v62
	v_add_f32_e32 v80, v58, v80
	v_sub_f32_e32 v63, v63, v32
	v_add_f32_e32 v80, v59, v80
	v_exp_f32_e32 v63, v63
	v_add_f32_e32 v80, v60, v80
	v_add_f32_e32 v80, v61, v80
	v_add_f32_e32 v80, v62, v80
	v_add_f32_e32 v80, v63, v80
	v_sub_f32_e32 v40, v40, v32
	v_exp_f32_e32 v87, v40
	v_sub_f32_e32 v40, v41, v32
	v_sub_f32_e32 v48, v48, v32
	v_exp_f32_e32 v88, v40
	v_sub_f32_e32 v40, v42, v32
	v_exp_f32_e32 v81, v48
	v_sub_f32_e32 v48, v49, v32
	v_exp_f32_e32 v89, v40
	v_sub_f32_e32 v40, v43, v32
	v_exp_f32_e32 v82, v48
	v_sub_f32_e32 v48, v50, v32
	v_exp_f32_e32 v90, v40
	v_sub_f32_e32 v40, v44, v32
	v_exp_f32_e32 v83, v48
	v_sub_f32_e32 v48, v51, v32
	v_exp_f32_e32 v91, v40
	v_sub_f32_e32 v40, v45, v32
	v_exp_f32_e32 v84, v48
	v_sub_f32_e32 v48, v52, v32
	v_exp_f32_e32 v100, v40
	v_sub_f32_e32 v40, v46, v32
	v_exp_f32_e32 v85, v48
	v_sub_f32_e32 v48, v53, v32
	v_exp_f32_e32 v101, v40
	v_add_f32_e32 v40, v81, v80
	v_exp_f32_e32 v86, v48
	v_sub_f32_e32 v48, v54, v32
	v_add_f32_e32 v40, v82, v40
	v_exp_f32_e32 v54, v48
	v_sub_f32_e32 v48, v55, v32
	v_add_f32_e32 v40, v83, v40
	v_exp_f32_e32 v55, v48
	v_add_f32_e32 v40, v84, v40
	v_add_f32_e32 v40, v85, v40
	v_add_f32_e32 v40, v86, v40
	v_add_f32_e32 v40, v54, v40
	v_add_f32_e32 v40, v55, v40
	v_add_f32_e32 v40, v87, v40
	v_add_f32_e32 v40, v88, v40
	v_add_f32_e32 v40, v89, v40
	v_sub_f32_e32 v41, v47, v32
; #define SBAR() __builtin_amdgcn_sched_barrier(0)
; DI int v_rd_base(int lane) { return ((lane & 3) << 3) | (((lane >> 2) & 3) << 6) | (((lane >> 4) & 1) << 5) | (((lane >> 5) & 1) << 8); }
; DI s16x4 vtr(const char* p) { return __builtin_bit_cast(s16x4, __builtin_amdgcn_ds_read_tr16_b64_v4i16((LAS v4i16_t*)(uintptr_t)p)); }
; DI void unit(const bf16* __restrict__ QKV, const int* __restrict__ pos, bf16* __restrict__ OA, float* __restrict__ LSE,
;              int b, int h, int d, int r, int qb, float slope, char* lds) {
;     ...
;   float ls = 0.f;
; #pragma unroll
;   for (int ta = 0; ta < 5; ++ta)
; #pragma unroll
;     for (int rr = 0; rr < 16; ++rr) { p[ta][rr] = __builtin_amdgcn_exp2f(p[ta][rr] - mx); ls += p[ta][rr]; if (rr == 15) SBAR(); }
;   { auto x = __builtin_amdgcn_permlane32_swap(__float_as_uint(ls), __float_as_uint(ls), false, false); ls = __uint_as_float(x[0]) + __uint_as_float(x[1]); }
;   f32x16 o[2] = {};
;   const char* vb = V_lds + att::v_rd_base(lane) + wid * 2 * 2048;
; #pragma unroll
;   for (int ta = 0; ta < 5; ++ta) {
;     bf16x8 pa0, pa1; PK4(p[ta], 0, pa0); PK4(p[ta], 8, pa1);
; #pragma unroll
;     for (int d0 = 0; d0 < 2; ++d0) {
;       const s16x4 l0 = vtr(vb + (2 * ta) * 2048 + d0 * 512), h0 = vtr(vb + (2 * ta) * 2048 + 1024 + d0 * 512);
;       const s16x4 l1 = vtr(vb + (2 * ta + 1) * 2048 + d0 * 512), h1 = vtr(vb + (2 * ta + 1) * 2048 + 1024 + d0 * 512);
;       o[d0] = __builtin_amdgcn_mfma_f32_32x32x16_bf16((bf16x8){l0[0], l0[1], l0[2], l0[3], h0[0], h0[1], h0[2], h0[3]}, pa0, o[d0], 0, 0, 0);
;       o[d0] = __builtin_amdgcn_mfma_f32_32x32x16_bf16((bf16x8){l1[0], l1[1], l1[2], l1[3], h1[0], h1[1], h1[2], h1[3]}, pa1, o[d0], 0, 0, 0);
;     }
	v_add_f32_e32 v40, v90, v40
	v_exp_f32_e32 v80, v41
	v_add_f32_e32 v40, v91, v40
	v_add_f32_e32 v40, v100, v40
	v_add_f32_e32 v40, v101, v40
	v_add_f32_e32 v40, v80, v40
	v_sub_f32_e32 v24, v24, v32
	v_exp_f32_e32 v109, v24
	v_sub_f32_e32 v24, v25, v32
	v_sub_f32_e32 v41, v116, v32
	v_exp_f32_e32 v110, v24
	v_sub_f32_e32 v24, v26, v32
	v_exp_f32_e32 v102, v41
	v_sub_f32_e32 v33, v33, v32
	v_exp_f32_e32 v111, v24
	v_sub_f32_e32 v24, v27, v32
	v_exp_f32_e32 v33, v33
	v_sub_f32_e32 v34, v34, v32
	v_exp_f32_e32 v112, v24
	v_sub_f32_e32 v24, v28, v32
	v_exp_f32_e32 v103, v34
	v_sub_f32_e32 v34, v35, v32
	v_exp_f32_e32 v113, v24
	v_sub_f32_e32 v24, v29, v32
	v_exp_f32_e32 v104, v34
	v_sub_f32_e32 v34, v36, v32
	v_exp_f32_e32 v114, v24
	v_sub_f32_e32 v24, v30, v32
	v_exp_f32_e32 v105, v34
	v_sub_f32_e32 v34, v37, v32
	v_exp_f32_e32 v115, v24
	v_add_f32_e32 v24, v102, v40
	v_exp_f32_e32 v106, v34
	v_sub_f32_e32 v34, v38, v32
	v_add_f32_e32 v24, v33, v24
	v_exp_f32_e32 v107, v34
	v_sub_f32_e32 v34, v39, v32
	v_add_f32_e32 v24, v103, v24
	v_exp_f32_e32 v108, v34
	v_add_f32_e32 v24, v104, v24
	v_add_f32_e32 v24, v105, v24
	v_add_f32_e32 v24, v106, v24
	v_add_f32_e32 v24, v107, v24
	v_add_f32_e32 v24, v108, v24
	v_add_f32_e32 v24, v109, v24
	v_add_f32_e32 v24, v110, v24
	v_add_f32_e32 v24, v111, v24
	v_sub_f32_e32 v25, v31, v32
	v_add_f32_e32 v24, v112, v24
	v_exp_f32_e32 v116, v25
	v_add_f32_e32 v24, v113, v24
	v_add_f32_e32 v24, v114, v24
	v_add_f32_e32 v24, v115, v24
	v_add_f32_e32 v24, v116, v24
	v_sub_f32_e32 v0, v0, v32
	v_exp_f32_e32 v125, v0
	v_sub_f32_e32 v0, v1, v32
	v_sub_f32_e32 v16, v16, v32
	v_exp_f32_e32 v126, v0
	v_sub_f32_e32 v0, v2, v32
	v_exp_f32_e32 v117, v16
	v_sub_f32_e32 v16, v17, v32
	v_exp_f32_e32 v127, v0
	v_sub_f32_e32 v0, v3, v32
	v_exp_f32_e32 v118, v16
	v_sub_f32_e32 v16, v18, v32
	v_exp_f32_e32 v128, v0
	v_sub_f32_e32 v0, v4, v32
	v_exp_f32_e32 v119, v16
	v_sub_f32_e32 v16, v19, v32
	v_exp_f32_e32 v129, v0
	v_sub_f32_e32 v0, v5, v32
	v_exp_f32_e32 v120, v16
	v_sub_f32_e32 v16, v20, v32
	v_exp_f32_e32 v130, v0
	v_sub_f32_e32 v0, v6, v32
	v_exp_f32_e32 v121, v16
	v_sub_f32_e32 v16, v21, v32
	v_exp_f32_e32 v131, v0
	v_add_f32_e32 v0, v117, v24
	v_exp_f32_e32 v122, v16
	v_sub_f32_e32 v16, v22, v32
	v_add_f32_e32 v0, v118, v0
	v_exp_f32_e32 v123, v16
	v_sub_f32_e32 v16, v23, v32
	v_add_f32_e32 v0, v119, v0
	v_exp_f32_e32 v124, v16
	v_add_f32_e32 v0, v120, v0
	v_add_f32_e32 v0, v121, v0
	v_add_f32_e32 v0, v122, v0
	v_add_f32_e32 v0, v123, v0
	v_add_f32_e32 v0, v124, v0
	v_add_f32_e32 v0, v125, v0
	v_add_f32_e32 v0, v126, v0
	v_add_f32_e32 v0, v127, v0
	v_sub_f32_e32 v1, v7, v32
	v_add_f32_e32 v0, v128, v0
	v_exp_f32_e32 v132, v1
	v_add_f32_e32 v0, v129, v0
	v_add_f32_e32 v0, v130, v0
	v_add_f32_e32 v0, v131, v0
	v_add_f32_e32 v133, v132, v0
	v_lshlrev_b32_e32 v0, 3, v98
	v_and_b32_e32 v1, 24, v0
	v_lshlrev_b32_e32 v2, 4, v98
	v_lshlrev_b32_e32 v3, 1, v98
	v_and_b32_e32 v2, 0xc0, v2
	v_and_b32_e32 v3, 32, v3
	v_add_u32_e32 v1, 0, v1
	v_and_b32_e32 v0, 0x100, v0
	v_add3_u32 v1, v1, v2, v3
	v_add3_u32 v99, v1, v0, v99
	v_cvt_pk_bf16_f32 v0, v8, v9
	v_cvt_pk_bf16_f32 v1, v10, v11
	v_cvt_pk_bf16_f32 v2, v12, v13
	v_cvt_pk_bf16_f32 v3, v14, v15
	v_cvt_pk_bf16_f32 v34, v72, v73
	v_cvt_pk_bf16_f32 v35, v74, v75
	v_cvt_pk_bf16_f32 v36, v76, v77
	v_cvt_pk_bf16_f32 v37, v78, v79
	ds_read_b64_tr_b16 v[4:5], v99 offset:49152
	ds_read_b64_tr_b16 v[6:7], v99 offset:50176
	v_permlane32_swap_b32_e32 v0, v2
	v_permlane32_swap_b32_e32 v1, v3
	ds_read_b64_tr_b16 v[10:11], v99 offset:50688
	ds_read_b64_tr_b16 v[8:9], v99 offset:49664
	s_waitcnt lgkmcnt(2)
	v_mfma_f32_32x32x16_bf16 v[16:31], v[4:7], v[0:3], 0
	ds_read_b64_tr_b16 v[4:5], v99 offset:51200
	ds_read_b64_tr_b16 v[6:7], v99 offset:52224
	v_permlane32_swap_b32_e32 v34, v36
	v_permlane32_swap_b32_e32 v35, v37
	ds_read_b64_tr_b16 v[40:41], v99 offset:52736
	ds_read_b64_tr_b16 v[38:39], v99 offset:51712
	v_mov_b32_e32 v72, v133
	s_waitcnt lgkmcnt(2)
	v_mfma_f32_32x32x16_bf16 v[16:31], v[4:7], v[34:37], v[16:31]
	v_permlane32_swap_b32_e32 v133, v72
	v_add_u32_e32 v73, 0xc000, v99
	v_mfma_f32_32x32x16_bf16 v[0:15], v[8:11], v[0:3], 0
	s_waitcnt lgkmcnt(0)
	v_mfma_f32_32x32x16_bf16 v[0:15], v[38:41], v[34:37], v[0:15]
	v_cvt_pk_bf16_f32 v34, v64, v65
	v_cvt_pk_bf16_f32 v35, v66, v67
	v_cvt_pk_bf16_f32 v36, v68, v69
	v_cvt_pk_bf16_f32 v37, v70, v71
	v_cvt_pk_bf16_f32 v38, v56, v57
	v_cvt_pk_bf16_f32 v39, v58, v59
	v_cvt_pk_bf16_f32 v40, v60, v61
	v_cvt_pk_bf16_f32 v41, v62, v63
	ds_read_b64_tr_b16 v[42:43], v99 offset:53248
	ds_read_b64_tr_b16 v[44:45], v99 offset:54272
	ds_read_b64_tr_b16 v[48:49], v99 offset:54784
	ds_read_b64_tr_b16 v[46:47], v99 offset:53760
	v_permlane32_swap_b32_e32 v34, v36
	v_permlane32_swap_b32_e32 v35, v37
	v_permlane32_swap_b32_e32 v38, v40
	s_waitcnt lgkmcnt(2)
; #define SBAR() __builtin_amdgcn_sched_barrier(0)
; DI s16x4 vtr(const char* p) { return __builtin_bit_cast(s16x4, __builtin_amdgcn_ds_read_tr16_b64_v4i16((LAS v4i16_t*)(uintptr_t)p)); }
; DI void unit(const bf16* __restrict__ QKV, const int* __restrict__ pos, bf16* __restrict__ OA, float* __restrict__ LSE,
;              int b, int h, int d, int r, int qb, float slope, char* lds) {
;     ...
;   for (int ta = 0; ta < 5; ++ta) {
;     bf16x8 pa0, pa1; PK4(p[ta], 0, pa0); PK4(p[ta], 8, pa1);
; #pragma unroll
;     for (int d0 = 0; d0 < 2; ++d0) {
;       const s16x4 l0 = vtr(vb + (2 * ta) * 2048 + d0 * 512), h0 = vtr(vb + (2 * ta) * 2048 + 1024 + d0 * 512);
;       const s16x4 l1 = vtr(vb + (2 * ta + 1) * 2048 + d0 * 512), h1 = vtr(vb + (2 * ta + 1) * 2048 + 1024 + d0 * 512);
;       o[d0] = __builtin_amdgcn_mfma_f32_32x32x16_bf16((bf16x8){l0[0], l0[1], l0[2], l0[3], h0[0], h0[1], h0[2], h0[3]}, pa0, o[d0], 0, 0, 0);
;       o[d0] = __builtin_amdgcn_mfma_f32_32x32x16_bf16((bf16x8){l1[0], l1[1], l1[2], l1[3], h1[0], h1[1], h1[2], h1[3]}, pa1, o[d0], 0, 0, 0);
;     }
;     SBAR();
;   }
;   if (hi == 0) LSE[(size_t)(b * SEQ + tq) * 8 + h] = (mx + __builtin_amdgcn_logf(ls)) * 0.6931471805599453f;
	v_mfma_f32_32x32x16_bf16 v[16:31], v[42:45], v[34:37], v[16:31]
	ds_read_b64_tr_b16 v[42:43], v99 offset:55296
	ds_read_b64_tr_b16 v[44:45], v99 offset:56320
	ds_read_b64_tr_b16 v[52:53], v99 offset:56832
	ds_read_b64_tr_b16 v[50:51], v99 offset:55808
	v_permlane32_swap_b32_e32 v39, v41
	s_waitcnt lgkmcnt(4)
	v_mfma_f32_32x32x16_bf16 v[0:15], v[46:49], v[34:37], v[0:15]
	s_waitcnt lgkmcnt(2)
	v_mfma_f32_32x32x16_bf16 v[16:31], v[42:45], v[38:41], v[16:31]
	s_waitcnt lgkmcnt(0)
	v_mfma_f32_32x32x16_bf16 v[0:15], v[50:53], v[38:41], v[0:15]
	v_cvt_pk_bf16_f32 v34, v81, v82
	v_cvt_pk_bf16_f32 v35, v83, v84
	v_cvt_pk_bf16_f32 v36, v85, v86
	v_cvt_pk_bf16_f32 v37, v54, v55
	v_cvt_pk_bf16_f32 v38, v87, v88
	v_cvt_pk_bf16_f32 v39, v89, v90
	v_cvt_pk_bf16_f32 v40, v91, v100
	v_cvt_pk_bf16_f32 v41, v101, v80
	ds_read_b64_tr_b16 v[42:43], v99 offset:57344
	ds_read_b64_tr_b16 v[44:45], v99 offset:58368
	ds_read_b64_tr_b16 v[48:49], v99 offset:58880
	ds_read_b64_tr_b16 v[46:47], v99 offset:57856
	v_permlane32_swap_b32_e32 v34, v36
	v_permlane32_swap_b32_e32 v35, v37
	v_permlane32_swap_b32_e32 v38, v40
	s_waitcnt lgkmcnt(2)
	v_mfma_f32_32x32x16_bf16 v[16:31], v[42:45], v[34:37], v[16:31]
	ds_read_b64_tr_b16 v[42:43], v99 offset:59392
	ds_read_b64_tr_b16 v[44:45], v99 offset:60416
	ds_read_b64_tr_b16 v[52:53], v99 offset:60928
	ds_read_b64_tr_b16 v[50:51], v99 offset:59904
	v_permlane32_swap_b32_e32 v39, v41
	s_waitcnt lgkmcnt(4)
	v_mfma_f32_32x32x16_bf16 v[0:15], v[46:49], v[34:37], v[0:15]
	s_waitcnt lgkmcnt(2)
	v_mfma_f32_32x32x16_bf16 v[16:31], v[42:45], v[38:41], v[16:31]
	s_waitcnt lgkmcnt(0)
	v_mfma_f32_32x32x16_bf16 v[0:15], v[50:53], v[38:41], v[0:15]
	v_cvt_pk_bf16_f32 v34, v102, v33
	v_cvt_pk_bf16_f32 v35, v103, v104
	v_cvt_pk_bf16_f32 v36, v105, v106
	v_cvt_pk_bf16_f32 v37, v107, v108
	v_cvt_pk_bf16_f32 v38, v109, v110
	v_cvt_pk_bf16_f32 v39, v111, v112
	v_cvt_pk_bf16_f32 v40, v113, v114
	v_cvt_pk_bf16_f32 v41, v115, v116
	ds_read_b64_tr_b16 v[42:43], v99 offset:61440
	ds_read_b64_tr_b16 v[44:45], v99 offset:62464
	ds_read_b64_tr_b16 v[48:49], v99 offset:62976
	ds_read_b64_tr_b16 v[46:47], v99 offset:61952
	v_permlane32_swap_b32_e32 v34, v36
	v_permlane32_swap_b32_e32 v35, v37
	v_permlane32_swap_b32_e32 v38, v40
	s_waitcnt lgkmcnt(2)
	v_mfma_f32_32x32x16_bf16 v[16:31], v[42:45], v[34:37], v[16:31]
	ds_read_b64_tr_b16 v[42:43], v99 offset:63488
	ds_read_b64_tr_b16 v[44:45], v99 offset:64512
	ds_read_b64_tr_b16 v[52:53], v99 offset:65024
	ds_read_b64_tr_b16 v[50:51], v99 offset:64000
	v_permlane32_swap_b32_e32 v39, v41
	s_waitcnt lgkmcnt(4)
	v_mfma_f32_32x32x16_bf16 v[0:15], v[46:49], v[34:37], v[0:15]
	s_waitcnt lgkmcnt(2)
	v_mfma_f32_32x32x16_bf16 v[16:31], v[42:45], v[38:41], v[16:31]
	s_waitcnt lgkmcnt(0)
	v_mfma_f32_32x32x16_bf16 v[0:15], v[50:53], v[38:41], v[0:15]
	v_cvt_pk_bf16_f32 v34, v117, v118
	v_cvt_pk_bf16_f32 v35, v119, v120
	v_cvt_pk_bf16_f32 v36, v121, v122
	v_cvt_pk_bf16_f32 v37, v123, v124
	v_cvt_pk_bf16_f32 v38, v125, v126
	v_cvt_pk_bf16_f32 v39, v127, v128
	v_cvt_pk_bf16_f32 v40, v129, v130
	v_cvt_pk_bf16_f32 v41, v131, v132
	ds_read_b64_tr_b16 v[42:43], v73 offset:16384
	ds_read_b64_tr_b16 v[44:45], v73 offset:17408
	ds_read_b64_tr_b16 v[48:49], v73 offset:17920
	ds_read_b64_tr_b16 v[46:47], v73 offset:16896
	v_permlane32_swap_b32_e32 v34, v36
	v_permlane32_swap_b32_e32 v35, v37
	v_permlane32_swap_b32_e32 v38, v40
	s_waitcnt lgkmcnt(2)
	v_mfma_f32_32x32x16_bf16 v[16:31], v[42:45], v[34:37], v[16:31]
	ds_read_b64_tr_b16 v[42:43], v73 offset:18432
	ds_read_b64_tr_b16 v[44:45], v73 offset:19456
	ds_read_b64_tr_b16 v[52:53], v73 offset:19968
	ds_read_b64_tr_b16 v[50:51], v73 offset:18944
	v_permlane32_swap_b32_e32 v39, v41
	s_waitcnt lgkmcnt(4)
	v_mfma_f32_32x32x16_bf16 v[0:15], v[46:49], v[34:37], v[0:15]
	s_waitcnt lgkmcnt(2)
	v_mfma_f32_32x32x16_bf16 v[16:31], v[42:45], v[38:41], v[16:31]
	s_waitcnt lgkmcnt(0)
	v_mfma_f32_32x32x16_bf16 v[0:15], v[50:53], v[38:41], v[0:15]
	v_add_f32_e32 v33, v133, v72
	v_cmp_gt_u32_e32 vcc, 32, v98
	s_and_saveexec_b64 s[2:3], vcc
	s_cbranch_execz .LBB0_857
	v_log_f32_e32 v34, v33
	s_lshl_b64 s[4:5], s[14:15], 20
	s_add_u32 s4, s13, s4
	s_addc_u32 s5, s38, s5
	v_add_f32_e32 v32, v32, v34
	v_lshlrev_b64 v[34:35], 5, v[94:95]
	v_lshl_add_u64 v[34:35], s[4:5], 0, v[34:35]
	s_lshl_b32 s8, s48, 2
	v_mul_f32_e32 v32, 0x3f317218, v32
	v_lshl_add_u64 v[34:35], v[34:35], 0, s[8:9]
	global_store_dword v[34:35], v32, off
	s_branch .LBB0_857

; #define PG8_STAGE(bufoff, gbase, voff) do { _Pragma("unroll") for (int _i = 0; _i < 2; ++_i) \
;         __builtin_amdgcn_global_load_lds((const unsigned*)((const char*)(gbase) + (voff)[_i]), (PG8_LAS unsigned*)(lds + (bufoff) + ldsw + _i * 8192), 16, 0, 0); } while (0)
; #define PG8_LDA(dst, b, h) do { _Pragma("unroll") for (int m = 0; m < 4; ++m) _Pragma("unroll") for (int k = 0; k < 2; ++k) dst[m][k] = *(const PG8_LAS bf16x8*)(lds + PG8_SA(b, h) + aoff + m * 2048 + k * 1024); } while (0)
; #define PG8_LDB(dst, b, h) do { _Pragma("unroll") for (int n = 0; n < 2; ++n) _Pragma("unroll") for (int k = 0; k < 2; ++k) dst[n][k] = *(const PG8_LAS bf16x8*)(lds + PG8_SB(b, h) + boff + n * 2048 + k * 1024); } while (0)
; #define PG8_MMA(ai, bj, At, Bt) do { __builtin_amdgcn_s_setprio(1); _Pragma("unroll") for (int m = 0; m < 4; ++m) _Pragma("unroll") for (int n = 0; n < 2; ++n) _Pragma("unroll") for (int k = 0; k < 2; ++k) \
;         acc[ai][bj][m][n] = __builtin_amdgcn_mfma_f32_16x16x32_bf16(Bt[n][k], At[m][k], acc[ai][bj][m][n], 0, 0, 0); __builtin_amdgcn_s_setprio(0); } while (0)
; #define PG8_WAIT_V(n) asm volatile("s_waitcnt vmcnt(" #n ")" ::: "memory")
; #define PG8_WAIT_L(n) asm volatile("s_waitcnt lgkmcnt(" #n ")" ::: "memory")
; #define PG8_BAR __builtin_amdgcn_s_barrier()
; #define PG8_SCHED __builtin_amdgcn_sched_barrier(0)
; template <class Epi, class Sched, bool ALIGN_EPI = false, bool SP2 = false>
; __device__ __forceinline__ void gemm_phase(PG8_LAS unsigned char* lds, const Gemm g, const Sched& S, const Epi& E) {
;     ...
;             const bool last = (t == nt - 2);
;             const char* a1 = cA + (size_t)(t + 1) * kstep;
;             const char* a2 = last ? nA : cA + (size_t)(t + 2) * kstep; const char* b2 = last ? nB : cB + (size_t)(t + 2) * kstep;
;             const char* a3 = a2 + kstep; const char* b3 = b2 + kstep;
;             if (last && has_next) S.a_ready(nxt);
;             if constexpr (SP2) {
;             PG8_LDB(B0, 0, 0); PG8_LDB(B1, 0, 1); PG8_SCHED; PG8_LDA(At, 0, 0); PG8_STAGE(PG8_SA(1, 1), a1 + hstep, voffA);
;             PG8_WAIT_V(8); PG8_WAIT_L(0); PG8_BAR; PG8_MMA(0, 0, At, B0); PG8_MMA(0, 1, At, B1); PG8_BAR; PG8_SCHED;
;             PG8_LDA(At, 0, 1); PG8_STAGE(PG8_SB(0, 0), b2, voffB); PG8_STAGE(PG8_SB(0, 1), b2 + hstep, voffB); PG8_STAGE(PG8_SA(0, 0), a2, voffA);
.LBB0_1061:
	s_ashr_i32 s41, s40, 31
	s_lshl_b64 s[30:31], s[40:41], 19
	s_add_u32 s42, s10, s30
	s_addc_u32 s43, s11, s31
	s_and_b64 s[30:31], s[6:7], exec
	s_cselect_b32 s41, s43, s51
	s_cselect_b32 s47, s42, s50
	s_ashr_i32 s39, s38, 31
	s_lshl_b64 s[30:31], s[38:39], 19
	s_add_u32 s44, s0, s30
	s_addc_u32 s45, s1, s31
	s_and_b64 s[30:31], s[6:7], exec
	s_cselect_b32 s39, s45, s53
	s_cselect_b32 s65, s44, s52
	s_add_u32 s50, s50, 0x40080
	s_addc_u32 s51, s51, 0
	s_add_u32 s66, s52, 0x100
	v_mov_b32_e32 v0, 0
	s_addc_u32 s67, s53, 0
	s_mov_b32 s68, -2
	s_waitcnt lgkmcnt(0)
	ds_read_b128 v[128:131], v207
	ds_read_b128 v[132:135], v207 offset:1024
	ds_read_b128 v[136:139], v207 offset:2048
	ds_read_b128 v[140:143], v207 offset:3072
	ds_read_b128 v[144:147], v208
	ds_read_b128 v[148:151], v208 offset:1024
	ds_read_b128 v[152:155], v208 offset:2048
	ds_read_b128 v[156:159], v208 offset:3072
	s_add_u32 s30, s50, 0xfffc0080
	s_addc_u32 s31, s51, -1
	s_cmp_eq_u32 s68, 12
	s_cselect_b32 s55, s41, s31
	s_cselect_b32 s54, s47, s30
	s_cselect_b32 s53, s39, s67
	s_cselect_b32 s52, s65, s66
	v_lshl_add_u64 v[216:217], s[50:51], 0, v[184:185]
	s_add_i32 m0, s49, 0xc000
	ds_read_b128 v[160:163], v209
	ds_read_b128 v[164:167], v209 offset:1024
	ds_read_b128 v[168:171], v209 offset:2048
	ds_read_b128 v[172:175], v209 offset:3072
	ds_read_b128 v[192:195], v209 offset:4096
	ds_read_b128 v[196:199], v209 offset:5120
	ds_read_b128 v[200:203], v209 offset:6144
	ds_read_b128 v[212:215], v209 offset:7168
	global_load_lds_dwordx4 v[216:217], off
	v_lshl_add_u64 v[216:217], s[50:51], 0, v[186:187]
	s_add_i32 m0, s49, 0xe000
	s_nop 0
	global_load_lds_dwordx4 v[216:217], off
	s_waitcnt vmcnt(8)
	s_waitcnt lgkmcnt(0)
	s_barrier
	s_setprio 1
	s_waitcnt lgkmcnt(0)
	v_mfma_f32_16x16x32_bf16 v[124:127], v[128:131], v[160:163], 0
	v_mfma_f32_16x16x32_bf16 v[120:123], v[136:139], v[160:163], 0
	v_mfma_f32_16x16x32_bf16 v[108:111], v[128:131], v[168:171], 0
	v_mfma_f32_16x16x32_bf16 v[104:107], v[136:139], v[168:171], 0
	v_mfma_f32_16x16x32_bf16 v[92:95], v[128:131], v[192:195], 0
	v_mfma_f32_16x16x32_bf16 v[88:91], v[136:139], v[192:195], 0
	v_mfma_f32_16x16x32_bf16 v[76:79], v[128:131], v[200:203], 0
	v_mfma_f32_16x16x32_bf16 v[72:75], v[136:139], v[200:203], 0
	v_mfma_f32_16x16x32_bf16 v[124:127], v[132:135], v[164:167], v[124:127]
	v_mfma_f32_16x16x32_bf16 v[120:123], v[140:143], v[164:167], v[120:123]
	v_mfma_f32_16x16x32_bf16 v[108:111], v[132:135], v[172:175], v[108:111]
	v_mfma_f32_16x16x32_bf16 v[104:107], v[140:143], v[172:175], v[104:107]
	v_mfma_f32_16x16x32_bf16 v[92:95], v[132:135], v[196:199], v[92:95]
	v_mfma_f32_16x16x32_bf16 v[88:91], v[140:143], v[196:199], v[88:91]
	v_mfma_f32_16x16x32_bf16 v[76:79], v[132:135], v[212:215], v[76:79]
	v_mfma_f32_16x16x32_bf16 v[72:75], v[140:143], v[212:215], v[72:75]
	s_setprio 0
	s_setprio 1
	v_mfma_f32_16x16x32_bf16 v[116:119], v[144:147], v[160:163], 0
	v_mfma_f32_16x16x32_bf16 v[112:115], v[152:155], v[160:163], 0
	v_mfma_f32_16x16x32_bf16 v[100:103], v[144:147], v[168:171], 0
	v_mfma_f32_16x16x32_bf16 v[96:99], v[152:155], v[168:171], 0
	v_mfma_f32_16x16x32_bf16 v[84:87], v[144:147], v[192:195], 0
	v_mfma_f32_16x16x32_bf16 v[80:83], v[152:155], v[192:195], 0
	v_mfma_f32_16x16x32_bf16 v[68:71], v[144:147], v[200:203], 0
	v_mfma_f32_16x16x32_bf16 v[64:67], v[152:155], v[200:203], 0
	v_mfma_f32_16x16x32_bf16 v[116:119], v[148:151], v[164:167], v[116:119]
	v_mfma_f32_16x16x32_bf16 v[112:115], v[156:159], v[164:167], v[112:115]
	v_mfma_f32_16x16x32_bf16 v[100:103], v[148:151], v[172:175], v[100:103]
	v_mfma_f32_16x16x32_bf16 v[96:99], v[156:159], v[172:175], v[96:99]
	v_mfma_f32_16x16x32_bf16 v[84:87], v[148:151], v[196:199], v[84:87]
	v_mfma_f32_16x16x32_bf16 v[80:83], v[156:159], v[196:199], v[80:83]
	v_mfma_f32_16x16x32_bf16 v[68:71], v[148:151], v[212:215], v[68:71]
	v_mfma_f32_16x16x32_bf16 v[64:67], v[156:159], v[212:215], v[64:67]
	s_setprio 0
	s_barrier
	s_add_i32 s30, s63, s56
	v_lshl_add_u64 v[216:217], s[52:53], 0, v[178:179]
	s_mov_b32 m0, s30
	ds_read_b128 v[160:163], v209 offset:16384
	ds_read_b128 v[164:167], v209 offset:17408
	ds_read_b128 v[168:171], v209 offset:18432
	ds_read_b128 v[172:175], v209 offset:19456
	ds_read_b128 v[192:195], v209 offset:20480
	ds_read_b128 v[196:199], v209 offset:21504
	ds_read_b128 v[200:203], v209 offset:22528
	ds_read_b128 v[212:215], v209 offset:23552
	global_load_lds_dwordx4 v[216:217], off
	s_add_i32 m0, s30, 0x2000
	s_add_u32 s30, s52, 0x40000
	v_lshl_add_u64 v[218:219], s[52:53], 0, v[182:183]
	s_addc_u32 s31, s53, 0
	s_add_i32 s69, s64, s56
	global_load_lds_dwordx4 v[218:219], off
	v_lshl_add_u64 v[220:221], s[30:31], 0, v[178:179]
	s_mov_b32 m0, s69
	v_lshl_add_u64 v[222:223], s[54:55], 0, v[180:181]
	global_load_lds_dwordx4 v[220:221], off
	v_lshl_add_u64 v[220:221], s[30:31], 0, v[182:183]
	s_add_i32 m0, s69, 0x2000
	s_nop 0
	global_load_lds_dwordx4 v[220:221], off
	v_lshl_add_u64 v[220:221], s[54:55], 0, v[176:177]
	s_mov_b32 m0, s49
	s_nop 0
	global_load_lds_dwordx4 v[220:221], off
	s_mov_b32 m0, s57
	s_nop 0
	global_load_lds_dwordx4 v[222:223], off
	s_waitcnt vmcnt(8)
	s_waitcnt lgkmcnt(0)
	s_barrier
; #define PG8_STAGE(bufoff, gbase, voff) do { _Pragma("unroll") for (int _i = 0; _i < 2; ++_i) \
;         __builtin_amdgcn_global_load_lds((const unsigned*)((const char*)(gbase) + (voff)[_i]), (PG8_LAS unsigned*)(lds + (bufoff) + ldsw + _i * 8192), 16, 0, 0); } while (0)
; #define PG8_LDA(dst, b, h) do { _Pragma("unroll") for (int m = 0; m < 4; ++m) _Pragma("unroll") for (int k = 0; k < 2; ++k) dst[m][k] = *(const PG8_LAS bf16x8*)(lds + PG8_SA(b, h) + aoff + m * 2048 + k * 1024); } while (0)
; #define PG8_LDB(dst, b, h) do { _Pragma("unroll") for (int n = 0; n < 2; ++n) _Pragma("unroll") for (int k = 0; k < 2; ++k) dst[n][k] = *(const PG8_LAS bf16x8*)(lds + PG8_SB(b, h) + boff + n * 2048 + k * 1024); } while (0)
; #define PG8_MMA(ai, bj, At, Bt) do { __builtin_amdgcn_s_setprio(1); _Pragma("unroll") for (int m = 0; m < 4; ++m) _Pragma("unroll") for (int n = 0; n < 2; ++n) _Pragma("unroll") for (int k = 0; k < 2; ++k) \
;         acc[ai][bj][m][n] = __builtin_amdgcn_mfma_f32_16x16x32_bf16(Bt[n][k], At[m][k], acc[ai][bj][m][n], 0, 0, 0); __builtin_amdgcn_s_setprio(0); } while (0)
; #define PG8_WAIT_V(n) asm volatile("s_waitcnt vmcnt(" #n ")" ::: "memory")
; #define PG8_WAIT_L(n) asm volatile("s_waitcnt lgkmcnt(" #n ")" ::: "memory")
; #define PG8_BAR __builtin_amdgcn_s_barrier()
; #define PG8_SCHED __builtin_amdgcn_sched_barrier(0)
; template <class Epi, class Sched, bool ALIGN_EPI = false, bool SP2 = false>
; __device__ __forceinline__ void gemm_phase(PG8_LAS unsigned char* lds, const Gemm g, const Sched& S, const Epi& E) {
;     ...
;             PG8_WAIT_V(8); PG8_WAIT_L(0); PG8_BAR; PG8_MMA(1, 0, At, B0); PG8_MMA(1, 1, At, B1); PG8_BAR; PG8_SCHED;
;             PG8_LDB(B0, 1, 0); PG8_LDB(B1, 1, 1); PG8_SCHED; PG8_LDA(At, 1, 0); PG8_STAGE(PG8_SA(0, 1), a2 + hstep, voffA);
;             PG8_WAIT_V(8); PG8_WAIT_L(0); PG8_BAR; PG8_MMA(0, 0, At, B0); PG8_MMA(0, 1, At, B1); PG8_BAR; PG8_SCHED;
	s_setprio 1
	s_waitcnt lgkmcnt(0)
	v_mfma_f32_16x16x32_bf16 v[60:63], v[128:131], v[160:163], 0
	v_mfma_f32_16x16x32_bf16 v[56:59], v[136:139], v[160:163], 0
	v_mfma_f32_16x16x32_bf16 v[44:47], v[128:131], v[168:171], 0
	v_mfma_f32_16x16x32_bf16 v[40:43], v[136:139], v[168:171], 0
	v_mfma_f32_16x16x32_bf16 v[28:31], v[128:131], v[192:195], 0
	v_mfma_f32_16x16x32_bf16 v[24:27], v[136:139], v[192:195], 0
	v_mfma_f32_16x16x32_bf16 v[12:15], v[128:131], v[200:203], 0
	v_mfma_f32_16x16x32_bf16 v[8:11], v[136:139], v[200:203], 0
	v_mfma_f32_16x16x32_bf16 v[60:63], v[132:135], v[164:167], v[60:63]
	v_mfma_f32_16x16x32_bf16 v[56:59], v[140:143], v[164:167], v[56:59]
	v_mfma_f32_16x16x32_bf16 v[44:47], v[132:135], v[172:175], v[44:47]
	v_mfma_f32_16x16x32_bf16 v[40:43], v[140:143], v[172:175], v[40:43]
	v_mfma_f32_16x16x32_bf16 v[28:31], v[132:135], v[196:199], v[28:31]
	v_mfma_f32_16x16x32_bf16 v[24:27], v[140:143], v[196:199], v[24:27]
	v_mfma_f32_16x16x32_bf16 v[12:15], v[132:135], v[212:215], v[12:15]
	v_mfma_f32_16x16x32_bf16 v[8:11], v[140:143], v[212:215], v[8:11]
	s_setprio 0
	s_setprio 1
	v_mfma_f32_16x16x32_bf16 v[52:55], v[144:147], v[160:163], 0
	v_mfma_f32_16x16x32_bf16 v[48:51], v[152:155], v[160:163], 0
	v_mfma_f32_16x16x32_bf16 v[36:39], v[144:147], v[168:171], 0
	v_mfma_f32_16x16x32_bf16 v[32:35], v[152:155], v[168:171], 0
	v_mfma_f32_16x16x32_bf16 v[20:23], v[144:147], v[192:195], 0
	v_mfma_f32_16x16x32_bf16 v[16:19], v[152:155], v[192:195], 0
	v_mfma_f32_16x16x32_bf16 v[4:7], v[144:147], v[200:203], 0
	v_mfma_f32_16x16x32_bf16 v[0:3], v[152:155], v[200:203], 0
	v_mfma_f32_16x16x32_bf16 v[52:55], v[148:151], v[164:167], v[52:55]
	v_mfma_f32_16x16x32_bf16 v[48:51], v[156:159], v[164:167], v[48:51]
	v_mfma_f32_16x16x32_bf16 v[36:39], v[148:151], v[172:175], v[36:39]
	v_mfma_f32_16x16x32_bf16 v[32:35], v[156:159], v[172:175], v[32:35]
	v_mfma_f32_16x16x32_bf16 v[20:23], v[148:151], v[196:199], v[20:23]
	v_mfma_f32_16x16x32_bf16 v[16:19], v[156:159], v[196:199], v[16:19]
	v_mfma_f32_16x16x32_bf16 v[4:7], v[148:151], v[212:215], v[4:7]
	v_mfma_f32_16x16x32_bf16 v[0:3], v[156:159], v[212:215], v[0:3]
	s_setprio 0
	s_barrier
	s_add_i32 s69, 0, 0x18000
	s_add_i32 s70, 0, 0x1c000
	v_add_u32_e32 v140, s69, v205
	v_add_u32_e32 v156, s70, v205
	ds_read_b128 v[128:131], v140
	ds_read_b128 v[132:135], v140 offset:1024
	ds_read_b128 v[136:139], v140 offset:2048
	ds_read_b128 v[140:143], v140 offset:3072
	ds_read_b128 v[144:147], v156
	ds_read_b128 v[148:151], v156 offset:1024
	ds_read_b128 v[152:155], v156 offset:2048
	ds_read_b128 v[156:159], v156 offset:3072
	s_add_u32 s30, s54, 0x40000
	s_addc_u32 s31, s55, 0
	s_mov_b32 m0, s58
	v_lshl_add_u64 v[224:225], s[30:31], 0, v[176:177]
	ds_read_b128 v[160:163], v209 offset:32768
	ds_read_b128 v[164:167], v209 offset:33792
	ds_read_b128 v[168:171], v209 offset:34816
	ds_read_b128 v[172:175], v209 offset:35840
	ds_read_b128 v[192:195], v209 offset:36864
	ds_read_b128 v[196:199], v209 offset:37888
	ds_read_b128 v[200:203], v209 offset:38912
	ds_read_b128 v[212:215], v209 offset:39936
	global_load_lds_dwordx4 v[224:225], off
	v_lshl_add_u64 v[224:225], s[30:31], 0, v[180:181]
	s_mov_b32 m0, s59
	s_nop 0
	global_load_lds_dwordx4 v[224:225], off
	s_waitcnt vmcnt(8)
	s_waitcnt lgkmcnt(0)
	s_barrier
	s_setprio 1
	s_waitcnt lgkmcnt(0)
	v_mfma_f32_16x16x32_bf16 v[124:127], v[128:131], v[160:163], v[124:127]
	v_mfma_f32_16x16x32_bf16 v[120:123], v[136:139], v[160:163], v[120:123]
	v_mfma_f32_16x16x32_bf16 v[108:111], v[128:131], v[168:171], v[108:111]
	v_mfma_f32_16x16x32_bf16 v[104:107], v[136:139], v[168:171], v[104:107]
	v_mfma_f32_16x16x32_bf16 v[92:95], v[128:131], v[192:195], v[92:95]
	v_mfma_f32_16x16x32_bf16 v[88:91], v[136:139], v[192:195], v[88:91]
	v_mfma_f32_16x16x32_bf16 v[76:79], v[128:131], v[200:203], v[76:79]
	v_mfma_f32_16x16x32_bf16 v[72:75], v[136:139], v[200:203], v[72:75]
	v_mfma_f32_16x16x32_bf16 v[124:127], v[132:135], v[164:167], v[124:127]
	v_mfma_f32_16x16x32_bf16 v[120:123], v[140:143], v[164:167], v[120:123]
	v_mfma_f32_16x16x32_bf16 v[108:111], v[132:135], v[172:175], v[108:111]
	v_mfma_f32_16x16x32_bf16 v[104:107], v[140:143], v[172:175], v[104:107]
	v_mfma_f32_16x16x32_bf16 v[92:95], v[132:135], v[196:199], v[92:95]
	v_mfma_f32_16x16x32_bf16 v[88:91], v[140:143], v[196:199], v[88:91]
	v_mfma_f32_16x16x32_bf16 v[76:79], v[132:135], v[212:215], v[76:79]
	v_mfma_f32_16x16x32_bf16 v[72:75], v[140:143], v[212:215], v[72:75]
	s_setprio 0
	s_setprio 1
	v_mfma_f32_16x16x32_bf16 v[116:119], v[144:147], v[160:163], v[116:119]
	v_mfma_f32_16x16x32_bf16 v[112:115], v[152:155], v[160:163], v[112:115]
	v_mfma_f32_16x16x32_bf16 v[100:103], v[144:147], v[168:171], v[100:103]
	v_mfma_f32_16x16x32_bf16 v[96:99], v[152:155], v[168:171], v[96:99]
	v_mfma_f32_16x16x32_bf16 v[84:87], v[144:147], v[192:195], v[84:87]
	v_mfma_f32_16x16x32_bf16 v[80:83], v[152:155], v[192:195], v[80:83]
	v_mfma_f32_16x16x32_bf16 v[68:71], v[144:147], v[200:203], v[68:71]
	v_mfma_f32_16x16x32_bf16 v[64:67], v[152:155], v[200:203], v[64:67]
	v_mfma_f32_16x16x32_bf16 v[116:119], v[148:151], v[164:167], v[116:119]
	v_mfma_f32_16x16x32_bf16 v[112:115], v[156:159], v[164:167], v[112:115]
	v_mfma_f32_16x16x32_bf16 v[100:103], v[148:151], v[172:175], v[100:103]
	v_mfma_f32_16x16x32_bf16 v[96:99], v[156:159], v[172:175], v[96:99]
	v_mfma_f32_16x16x32_bf16 v[84:87], v[148:151], v[196:199], v[84:87]
	v_mfma_f32_16x16x32_bf16 v[80:83], v[156:159], v[196:199], v[80:83]
	v_mfma_f32_16x16x32_bf16 v[68:71], v[148:151], v[212:215], v[68:71]
	v_mfma_f32_16x16x32_bf16 v[64:67], v[156:159], v[212:215], v[64:67]
	s_setprio 0
	s_barrier
; #define PG8_STAGE(bufoff, gbase, voff) do { _Pragma("unroll") for (int _i = 0; _i < 2; ++_i) \
;         __builtin_amdgcn_global_load_lds((const unsigned*)((const char*)(gbase) + (voff)[_i]), (PG8_LAS unsigned*)(lds + (bufoff) + ldsw + _i * 8192), 16, 0, 0); } while (0)
; #define PG8_LDA(dst, b, h) do { _Pragma("unroll") for (int m = 0; m < 4; ++m) _Pragma("unroll") for (int k = 0; k < 2; ++k) dst[m][k] = *(const PG8_LAS bf16x8*)(lds + PG8_SA(b, h) + aoff + m * 2048 + k * 1024); } while (0)
; #define PG8_MMA(ai, bj, At, Bt) do { __builtin_amdgcn_s_setprio(1); _Pragma("unroll") for (int m = 0; m < 4; ++m) _Pragma("unroll") for (int n = 0; n < 2; ++n) _Pragma("unroll") for (int k = 0; k < 2; ++k) \
;         acc[ai][bj][m][n] = __builtin_amdgcn_mfma_f32_16x16x32_bf16(Bt[n][k], At[m][k], acc[ai][bj][m][n], 0, 0, 0); __builtin_amdgcn_s_setprio(0); } while (0)
; #define PG8_WAIT_V(n) asm volatile("s_waitcnt vmcnt(" #n ")" ::: "memory")
; #define PG8_WAIT_L(n) asm volatile("s_waitcnt lgkmcnt(" #n ")" ::: "memory")
; #define PG8_BAR __builtin_amdgcn_s_barrier()
; #define PG8_SCHED __builtin_amdgcn_sched_barrier(0)
; template <class Epi, class Sched, bool ALIGN_EPI = false, bool SP2 = false>
; __device__ __forceinline__ void gemm_phase(PG8_LAS unsigned char* lds, const Gemm g, const Sched& S, const Epi& E) {
;     ...
;         for (int t = 0; t < nt; t += 2) {
;             const bool last = (t == nt - 2);
;     ...
;             PG8_LDA(At, 1, 1); PG8_STAGE(PG8_SB(1, 0), b3, voffB); PG8_STAGE(PG8_SB(1, 1), b3 + hstep, voffB); PG8_STAGE(PG8_SA(1, 0), a3, voffA);
;             PG8_WAIT_V(8); PG8_WAIT_L(0); PG8_BAR; PG8_MMA(1, 0, At, B0); PG8_MMA(1, 1, At, B1); PG8_BAR; PG8_SCHED;
	s_add_i32 s30, s69, s56
	v_lshl_add_u64 v[216:217], v[216:217], 0, s[18:19]
	s_mov_b32 m0, s30
	ds_read_b128 v[160:163], v209 offset:49152
	ds_read_b128 v[164:167], v209 offset:50176
	ds_read_b128 v[168:171], v209 offset:51200
	ds_read_b128 v[172:175], v209 offset:52224
	ds_read_b128 v[192:195], v209 offset:53248
	ds_read_b128 v[196:199], v209 offset:54272
	ds_read_b128 v[200:203], v209 offset:55296
	ds_read_b128 v[212:215], v209 offset:56320
	global_load_lds_dwordx4 v[216:217], off
	s_add_i32 m0, s30, 0x2000
	s_add_u32 s30, s52, 0x40080
	v_lshl_add_u64 v[216:217], v[218:219], 0, s[18:19]
	s_addc_u32 s31, s53, 0
	s_add_i32 s52, s70, s56
	global_load_lds_dwordx4 v[216:217], off
	v_lshl_add_u64 v[216:217], s[30:31], 0, v[178:179]
	s_mov_b32 m0, s52
	s_nop 0
	global_load_lds_dwordx4 v[216:217], off
	v_lshl_add_u64 v[216:217], s[30:31], 0, v[182:183]
	s_add_i32 m0, s52, 0x2000
	s_nop 0
	global_load_lds_dwordx4 v[216:217], off
	v_lshl_add_u64 v[216:217], v[220:221], 0, s[18:19]
	s_mov_b32 m0, s61
	s_nop 0
	global_load_lds_dwordx4 v[216:217], off
	v_lshl_add_u64 v[216:217], v[222:223], 0, s[18:19]
	s_mov_b32 m0, s62
	s_nop 0
	global_load_lds_dwordx4 v[216:217], off
	s_waitcnt vmcnt(8)
	s_waitcnt lgkmcnt(0)
	s_barrier
	s_setprio 1
	s_waitcnt lgkmcnt(0)
	v_mfma_f32_16x16x32_bf16 v[60:63], v[128:131], v[160:163], v[60:63]
	v_mfma_f32_16x16x32_bf16 v[56:59], v[136:139], v[160:163], v[56:59]
	v_mfma_f32_16x16x32_bf16 v[44:47], v[128:131], v[168:171], v[44:47]
	v_mfma_f32_16x16x32_bf16 v[40:43], v[136:139], v[168:171], v[40:43]
	v_mfma_f32_16x16x32_bf16 v[28:31], v[128:131], v[192:195], v[28:31]
	v_mfma_f32_16x16x32_bf16 v[24:27], v[136:139], v[192:195], v[24:27]
	v_mfma_f32_16x16x32_bf16 v[12:15], v[128:131], v[200:203], v[12:15]
	v_mfma_f32_16x16x32_bf16 v[8:11], v[136:139], v[200:203], v[8:11]
	v_mfma_f32_16x16x32_bf16 v[60:63], v[132:135], v[164:167], v[60:63]
	v_mfma_f32_16x16x32_bf16 v[56:59], v[140:143], v[164:167], v[56:59]
	v_mfma_f32_16x16x32_bf16 v[44:47], v[132:135], v[172:175], v[44:47]
	v_mfma_f32_16x16x32_bf16 v[40:43], v[140:143], v[172:175], v[40:43]
	v_mfma_f32_16x16x32_bf16 v[28:31], v[132:135], v[196:199], v[28:31]
	v_mfma_f32_16x16x32_bf16 v[24:27], v[140:143], v[196:199], v[24:27]
	v_mfma_f32_16x16x32_bf16 v[12:15], v[132:135], v[212:215], v[12:15]
	v_mfma_f32_16x16x32_bf16 v[8:11], v[140:143], v[212:215], v[8:11]
	s_setprio 0
	s_setprio 1
	v_mfma_f32_16x16x32_bf16 v[52:55], v[144:147], v[160:163], v[52:55]
	v_mfma_f32_16x16x32_bf16 v[48:51], v[152:155], v[160:163], v[48:51]
	v_mfma_f32_16x16x32_bf16 v[36:39], v[144:147], v[168:171], v[36:39]
	v_mfma_f32_16x16x32_bf16 v[32:35], v[152:155], v[168:171], v[32:35]
	v_mfma_f32_16x16x32_bf16 v[20:23], v[144:147], v[192:195], v[20:23]
	v_mfma_f32_16x16x32_bf16 v[16:19], v[152:155], v[192:195], v[16:19]
	v_mfma_f32_16x16x32_bf16 v[4:7], v[144:147], v[200:203], v[4:7]
	v_mfma_f32_16x16x32_bf16 v[0:3], v[152:155], v[200:203], v[0:3]
	v_mfma_f32_16x16x32_bf16 v[52:55], v[148:151], v[164:167], v[52:55]
	v_mfma_f32_16x16x32_bf16 v[48:51], v[156:159], v[164:167], v[48:51]
	v_mfma_f32_16x16x32_bf16 v[36:39], v[148:151], v[172:175], v[36:39]
	v_mfma_f32_16x16x32_bf16 v[32:35], v[156:159], v[172:175], v[32:35]
	v_mfma_f32_16x16x32_bf16 v[20:23], v[148:151], v[196:199], v[20:23]
	v_mfma_f32_16x16x32_bf16 v[16:19], v[156:159], v[196:199], v[16:19]
	v_mfma_f32_16x16x32_bf16 v[4:7], v[148:151], v[212:215], v[4:7]
	v_mfma_f32_16x16x32_bf16 v[0:3], v[156:159], v[212:215], v[0:3]
	s_setprio 0
	s_barrier
	s_add_i32 s68, s68, 2
	s_add_u32 s50, s50, 0x100
	s_addc_u32 s51, s51, 0
	s_add_u32 s66, s66, 0x100
	s_addc_u32 s67, s67, 0
	s_cmp_gt_u32 s68, 13
	s_cbranch_scc0 .LBB0_1062
	s_branch .Lgx_g4

; #define PG8_BAR __builtin_amdgcn_s_barrier()
; template <class Epi, class Sched, bool ALIGN_EPI = false, bool SP2 = false>
; __device__ __forceinline__ void gemm_phase(PG8_LAS unsigned char* lds, const Gemm g, const Sched& S, const Epi& E) {
;     ...
;         if constexpr (ALIGN_EPI) { if (wr == 0) PG8_BAR; }
.Lgx_g4:
	s_and_b64 vcc, exec, s[20:21]
	s_cbranch_vccz .LBB0_1065
	s_barrier

; #define PG8_STAGE(bufoff, gbase, voff) do { _Pragma("unroll") for (int _i = 0; _i < 2; ++_i) \
;         __builtin_amdgcn_global_load_lds((const unsigned*)((const char*)(gbase) + (voff)[_i]), (PG8_LAS unsigned*)(lds + (bufoff) + ldsw + _i * 8192), 16, 0, 0); } while (0)
; #define PG8_LDA(dst, b, h) do { _Pragma("unroll") for (int m = 0; m < 4; ++m) _Pragma("unroll") for (int k = 0; k < 2; ++k) dst[m][k] = *(const PG8_LAS bf16x8*)(lds + PG8_SA(b, h) + aoff + m * 2048 + k * 1024); } while (0)
; #define PG8_LDB(dst, b, h) do { _Pragma("unroll") for (int n = 0; n < 2; ++n) _Pragma("unroll") for (int k = 0; k < 2; ++k) dst[n][k] = *(const PG8_LAS bf16x8*)(lds + PG8_SB(b, h) + boff + n * 2048 + k * 1024); } while (0)
; #define PG8_MMA(ai, bj, At, Bt) do { __builtin_amdgcn_s_setprio(1); _Pragma("unroll") for (int m = 0; m < 4; ++m) _Pragma("unroll") for (int n = 0; n < 2; ++n) _Pragma("unroll") for (int k = 0; k < 2; ++k) \
;         acc[ai][bj][m][n] = __builtin_amdgcn_mfma_f32_16x16x32_bf16(Bt[n][k], At[m][k], acc[ai][bj][m][n], 0, 0, 0); __builtin_amdgcn_s_setprio(0); } while (0)
; #define PG8_WAIT_V(n) asm volatile("s_waitcnt vmcnt(" #n ")" ::: "memory")
; #define PG8_WAIT_L(n) asm volatile("s_waitcnt lgkmcnt(" #n ")" ::: "memory")
; #define PG8_BAR __builtin_amdgcn_s_barrier()
; #define PG8_SCHED __builtin_amdgcn_sched_barrier(0)
; template <class Epi, class Sched, bool ALIGN_EPI = false, bool SP2 = false>
; __device__ __forceinline__ void gemm_phase(PG8_LAS unsigned char* lds, const Gemm g, const Sched& S, const Epi& E) {
;     ...
;             const bool last = (t == nt - 2);
;             const char* a1 = cA + (size_t)(t + 1) * kstep;
;             const char* a2 = last ? nA : cA + (size_t)(t + 2) * kstep; const char* b2 = last ? nB : cB + (size_t)(t + 2) * kstep;
;             const char* a3 = a2 + kstep; const char* b3 = b2 + kstep;
;             if (last && has_next) S.a_ready(nxt);
;             if constexpr (SP2) {
;             PG8_LDB(B0, 0, 0); PG8_LDB(B1, 0, 1); PG8_SCHED; PG8_LDA(At, 0, 0); PG8_STAGE(PG8_SA(1, 1), a1 + hstep, voffA);
;             PG8_WAIT_V(8); PG8_WAIT_L(0); PG8_BAR; PG8_MMA(0, 0, At, B0); PG8_MMA(0, 1, At, B1); PG8_BAR; PG8_SCHED;
;             PG8_LDA(At, 0, 1); PG8_STAGE(PG8_SB(0, 0), b2, voffB); PG8_STAGE(PG8_SB(0, 1), b2 + hstep, voffB); PG8_STAGE(PG8_SA(0, 0), a2, voffA);
.LBB0_1154:
	s_ashr_i32 s45, s44, 31
	s_lshl_b64 s[30:31], s[44:45], 19
	s_add_u32 s46, s10, s30
	s_addc_u32 s47, s11, s31
	s_and_b64 s[30:31], s[4:5], exec
	s_cselect_b32 s45, s47, s53
	s_cselect_b32 s74, s46, s52
	s_ashr_i32 s43, s42, 31
	s_lshl_b64 s[30:31], s[42:43], 19
	s_add_u32 s48, s0, s30
	s_addc_u32 s49, s1, s31
	s_and_b64 s[30:31], s[4:5], exec
	s_cselect_b32 s43, s49, s55
	s_cselect_b32 s75, s48, s54
	s_add_u32 s52, s52, 0x40080
	s_addc_u32 s53, s53, 0
	s_add_u32 s76, s54, 0x100
	v_mov_b32_e32 v0, 0
	s_addc_u32 s77, s55, 0
	s_mov_b32 s80, -2
	ds_read_b128 v[144:147], v151
	ds_read_b128 v[156:159], v151 offset:1024
	ds_read_b128 v[160:163], v151 offset:2048
	ds_read_b128 v[164:167], v151 offset:3072
	ds_read_b128 v[168:171], v152
	ds_read_b128 v[172:175], v152 offset:1024
	ds_read_b128 v[176:179], v152 offset:2048
	ds_read_b128 v[180:183], v152 offset:3072
	s_add_u32 s30, s52, 0xfffc0080
	s_addc_u32 s31, s53, -1
	s_cmp_eq_u32 s80, 12
	s_cselect_b32 s57, s45, s31
	s_cselect_b32 s56, s74, s30
	s_cselect_b32 s55, s43, s77
	s_cselect_b32 s54, s75, s76
	v_lshl_add_u64 v[216:217], s[52:53], 0, v[136:137]
	s_add_i32 m0, s51, 0xc000
	ds_read_b128 v[184:187], v153
	ds_read_b128 v[188:191], v153 offset:1024
	ds_read_b128 v[192:195], v153 offset:2048
	ds_read_b128 v[196:199], v153 offset:3072
	ds_read_b128 v[200:203], v153 offset:4096
	ds_read_b128 v[204:207], v153 offset:5120
	ds_read_b128 v[208:211], v153 offset:6144
	ds_read_b128 v[212:215], v153 offset:7168
	global_load_lds_dwordx4 v[216:217], off
	v_lshl_add_u64 v[216:217], s[52:53], 0, v[138:139]
	s_add_i32 m0, s51, 0xe000
	s_nop 0
	global_load_lds_dwordx4 v[216:217], off
	s_waitcnt vmcnt(8)
	s_waitcnt lgkmcnt(0)
	s_barrier
	s_setprio 1
	s_waitcnt lgkmcnt(0)
	v_mfma_f32_16x16x32_bf16 v[124:127], v[144:147], v[184:187], 0
	v_mfma_f32_16x16x32_bf16 v[120:123], v[160:163], v[184:187], 0
	v_mfma_f32_16x16x32_bf16 v[108:111], v[144:147], v[192:195], 0
	v_mfma_f32_16x16x32_bf16 v[104:107], v[160:163], v[192:195], 0
	v_mfma_f32_16x16x32_bf16 v[92:95], v[144:147], v[200:203], 0
	v_mfma_f32_16x16x32_bf16 v[88:91], v[160:163], v[200:203], 0
	v_mfma_f32_16x16x32_bf16 v[76:79], v[144:147], v[208:211], 0
	v_mfma_f32_16x16x32_bf16 v[72:75], v[160:163], v[208:211], 0
	v_mfma_f32_16x16x32_bf16 v[124:127], v[156:159], v[188:191], v[124:127]
	v_mfma_f32_16x16x32_bf16 v[120:123], v[164:167], v[188:191], v[120:123]
	v_mfma_f32_16x16x32_bf16 v[108:111], v[156:159], v[196:199], v[108:111]
	v_mfma_f32_16x16x32_bf16 v[104:107], v[164:167], v[196:199], v[104:107]
	v_mfma_f32_16x16x32_bf16 v[92:95], v[156:159], v[204:207], v[92:95]
	v_mfma_f32_16x16x32_bf16 v[88:91], v[164:167], v[204:207], v[88:91]
	v_mfma_f32_16x16x32_bf16 v[76:79], v[156:159], v[212:215], v[76:79]
	v_mfma_f32_16x16x32_bf16 v[72:75], v[164:167], v[212:215], v[72:75]
	s_setprio 0
	s_setprio 1
	v_mfma_f32_16x16x32_bf16 v[116:119], v[168:171], v[184:187], 0
	v_mfma_f32_16x16x32_bf16 v[112:115], v[176:179], v[184:187], 0
	v_mfma_f32_16x16x32_bf16 v[100:103], v[168:171], v[192:195], 0
	v_mfma_f32_16x16x32_bf16 v[96:99], v[176:179], v[192:195], 0
	v_mfma_f32_16x16x32_bf16 v[84:87], v[168:171], v[200:203], 0
	v_mfma_f32_16x16x32_bf16 v[80:83], v[176:179], v[200:203], 0
	v_mfma_f32_16x16x32_bf16 v[68:71], v[168:171], v[208:211], 0
	v_mfma_f32_16x16x32_bf16 v[64:67], v[176:179], v[208:211], 0
	v_mfma_f32_16x16x32_bf16 v[116:119], v[172:175], v[188:191], v[116:119]
	v_mfma_f32_16x16x32_bf16 v[112:115], v[180:183], v[188:191], v[112:115]
	v_mfma_f32_16x16x32_bf16 v[100:103], v[172:175], v[196:199], v[100:103]
	v_mfma_f32_16x16x32_bf16 v[96:99], v[180:183], v[196:199], v[96:99]
	v_mfma_f32_16x16x32_bf16 v[84:87], v[172:175], v[204:207], v[84:87]
	v_mfma_f32_16x16x32_bf16 v[80:83], v[180:183], v[204:207], v[80:83]
	v_mfma_f32_16x16x32_bf16 v[68:71], v[172:175], v[212:215], v[68:71]
	v_mfma_f32_16x16x32_bf16 v[64:67], v[180:183], v[212:215], v[64:67]
	s_setprio 0
	s_barrier
	s_add_i32 s30, s65, s58
	v_lshl_add_u64 v[216:217], s[54:55], 0, v[130:131]
	s_mov_b32 m0, s30
	ds_read_b128 v[184:187], v153 offset:16384
	ds_read_b128 v[188:191], v153 offset:17408
	ds_read_b128 v[192:195], v153 offset:18432
	ds_read_b128 v[196:199], v153 offset:19456
	ds_read_b128 v[200:203], v153 offset:20480
	ds_read_b128 v[204:207], v153 offset:21504
	ds_read_b128 v[208:211], v153 offset:22528
	ds_read_b128 v[212:215], v153 offset:23552
	global_load_lds_dwordx4 v[216:217], off
	s_add_i32 m0, s30, 0x2000
	s_add_u32 s30, s54, 0x40000
	v_lshl_add_u64 v[218:219], s[54:55], 0, v[134:135]
	s_addc_u32 s31, s55, 0
	s_add_i32 s81, s66, s58
	global_load_lds_dwordx4 v[218:219], off
	v_lshl_add_u64 v[220:221], s[30:31], 0, v[130:131]
	s_mov_b32 m0, s81
	v_lshl_add_u64 v[222:223], s[56:57], 0, v[132:133]
	global_load_lds_dwordx4 v[220:221], off
	v_lshl_add_u64 v[220:221], s[30:31], 0, v[134:135]
	s_add_i32 m0, s81, 0x2000
	s_nop 0
	global_load_lds_dwordx4 v[220:221], off
	v_lshl_add_u64 v[220:221], s[56:57], 0, v[128:129]
	s_mov_b32 m0, s51
	s_nop 0
	global_load_lds_dwordx4 v[220:221], off
	s_mov_b32 m0, s59
	s_nop 0
	global_load_lds_dwordx4 v[222:223], off
	s_waitcnt vmcnt(8)
	s_waitcnt lgkmcnt(0)
	s_barrier
; #define PG8_STAGE(bufoff, gbase, voff) do { _Pragma("unroll") for (int _i = 0; _i < 2; ++_i) \
;         __builtin_amdgcn_global_load_lds((const unsigned*)((const char*)(gbase) + (voff)[_i]), (PG8_LAS unsigned*)(lds + (bufoff) + ldsw + _i * 8192), 16, 0, 0); } while (0)
; #define PG8_LDA(dst, b, h) do { _Pragma("unroll") for (int m = 0; m < 4; ++m) _Pragma("unroll") for (int k = 0; k < 2; ++k) dst[m][k] = *(const PG8_LAS bf16x8*)(lds + PG8_SA(b, h) + aoff + m * 2048 + k * 1024); } while (0)
; #define PG8_LDB(dst, b, h) do { _Pragma("unroll") for (int n = 0; n < 2; ++n) _Pragma("unroll") for (int k = 0; k < 2; ++k) dst[n][k] = *(const PG8_LAS bf16x8*)(lds + PG8_SB(b, h) + boff + n * 2048 + k * 1024); } while (0)
; #define PG8_MMA(ai, bj, At, Bt) do { __builtin_amdgcn_s_setprio(1); _Pragma("unroll") for (int m = 0; m < 4; ++m) _Pragma("unroll") for (int n = 0; n < 2; ++n) _Pragma("unroll") for (int k = 0; k < 2; ++k) \
;         acc[ai][bj][m][n] = __builtin_amdgcn_mfma_f32_16x16x32_bf16(Bt[n][k], At[m][k], acc[ai][bj][m][n], 0, 0, 0); __builtin_amdgcn_s_setprio(0); } while (0)
; #define PG8_WAIT_V(n) asm volatile("s_waitcnt vmcnt(" #n ")" ::: "memory")
; #define PG8_WAIT_L(n) asm volatile("s_waitcnt lgkmcnt(" #n ")" ::: "memory")
; #define PG8_BAR __builtin_amdgcn_s_barrier()
; #define PG8_SCHED __builtin_amdgcn_sched_barrier(0)
; template <class Epi, class Sched, bool ALIGN_EPI = false, bool SP2 = false>
; __device__ __forceinline__ void gemm_phase(PG8_LAS unsigned char* lds, const Gemm g, const Sched& S, const Epi& E) {
;     ...
;             PG8_WAIT_V(8); PG8_WAIT_L(0); PG8_BAR; PG8_MMA(1, 0, At, B0); PG8_MMA(1, 1, At, B1); PG8_BAR; PG8_SCHED;
;             PG8_LDB(B0, 1, 0); PG8_LDB(B1, 1, 1); PG8_SCHED; PG8_LDA(At, 1, 0); PG8_STAGE(PG8_SA(0, 1), a2 + hstep, voffA);
;             PG8_WAIT_V(8); PG8_WAIT_L(0); PG8_BAR; PG8_MMA(0, 0, At, B0); PG8_MMA(0, 1, At, B1); PG8_BAR; PG8_SCHED;
	s_setprio 1
	s_waitcnt lgkmcnt(0)
	v_mfma_f32_16x16x32_bf16 v[60:63], v[144:147], v[184:187], 0
	v_mfma_f32_16x16x32_bf16 v[56:59], v[160:163], v[184:187], 0
	v_mfma_f32_16x16x32_bf16 v[44:47], v[144:147], v[192:195], 0
	v_mfma_f32_16x16x32_bf16 v[40:43], v[160:163], v[192:195], 0
	v_mfma_f32_16x16x32_bf16 v[28:31], v[144:147], v[200:203], 0
	v_mfma_f32_16x16x32_bf16 v[24:27], v[160:163], v[200:203], 0
	v_mfma_f32_16x16x32_bf16 v[12:15], v[144:147], v[208:211], 0
	v_mfma_f32_16x16x32_bf16 v[8:11], v[160:163], v[208:211], 0
	v_mfma_f32_16x16x32_bf16 v[60:63], v[156:159], v[188:191], v[60:63]
	v_mfma_f32_16x16x32_bf16 v[56:59], v[164:167], v[188:191], v[56:59]
	v_mfma_f32_16x16x32_bf16 v[44:47], v[156:159], v[196:199], v[44:47]
	v_mfma_f32_16x16x32_bf16 v[40:43], v[164:167], v[196:199], v[40:43]
	v_mfma_f32_16x16x32_bf16 v[28:31], v[156:159], v[204:207], v[28:31]
	v_mfma_f32_16x16x32_bf16 v[24:27], v[164:167], v[204:207], v[24:27]
	v_mfma_f32_16x16x32_bf16 v[12:15], v[156:159], v[212:215], v[12:15]
	v_mfma_f32_16x16x32_bf16 v[8:11], v[164:167], v[212:215], v[8:11]
	s_setprio 0
	s_setprio 1
	v_mfma_f32_16x16x32_bf16 v[52:55], v[168:171], v[184:187], 0
	v_mfma_f32_16x16x32_bf16 v[48:51], v[176:179], v[184:187], 0
	v_mfma_f32_16x16x32_bf16 v[36:39], v[168:171], v[192:195], 0
	v_mfma_f32_16x16x32_bf16 v[32:35], v[176:179], v[192:195], 0
	v_mfma_f32_16x16x32_bf16 v[20:23], v[168:171], v[200:203], 0
	v_mfma_f32_16x16x32_bf16 v[16:19], v[176:179], v[200:203], 0
	v_mfma_f32_16x16x32_bf16 v[4:7], v[168:171], v[208:211], 0
	v_mfma_f32_16x16x32_bf16 v[0:3], v[176:179], v[208:211], 0
	v_mfma_f32_16x16x32_bf16 v[52:55], v[172:175], v[188:191], v[52:55]
	v_mfma_f32_16x16x32_bf16 v[48:51], v[180:183], v[188:191], v[48:51]
	v_mfma_f32_16x16x32_bf16 v[36:39], v[172:175], v[196:199], v[36:39]
	v_mfma_f32_16x16x32_bf16 v[32:35], v[180:183], v[196:199], v[32:35]
	v_mfma_f32_16x16x32_bf16 v[20:23], v[172:175], v[204:207], v[20:23]
	v_mfma_f32_16x16x32_bf16 v[16:19], v[180:183], v[204:207], v[16:19]
	v_mfma_f32_16x16x32_bf16 v[4:7], v[172:175], v[212:215], v[4:7]
	v_mfma_f32_16x16x32_bf16 v[0:3], v[180:183], v[212:215], v[0:3]
	s_setprio 0
	s_barrier
	s_add_i32 s81, 0, 0x18000
	v_add_u32_e32 v155, s81, v149
	s_add_i32 s82, 0, 0x1c000
	ds_read_b128 v[144:147], v155
	ds_read_b128 v[156:159], v155 offset:1024
	ds_read_b128 v[160:163], v155 offset:2048
	ds_read_b128 v[164:167], v155 offset:3072
	v_add_u32_e32 v155, s82, v149
	ds_read_b128 v[168:171], v155
	ds_read_b128 v[172:175], v155 offset:1024
	ds_read_b128 v[176:179], v155 offset:2048
	ds_read_b128 v[180:183], v155 offset:3072
	s_add_u32 s30, s56, 0x40000
	s_addc_u32 s31, s57, 0
	s_mov_b32 m0, s60
	v_lshl_add_u64 v[224:225], s[30:31], 0, v[128:129]
	ds_read_b128 v[184:187], v153 offset:32768
	ds_read_b128 v[188:191], v153 offset:33792
	ds_read_b128 v[192:195], v153 offset:34816
	ds_read_b128 v[196:199], v153 offset:35840
	ds_read_b128 v[200:203], v153 offset:36864
	ds_read_b128 v[204:207], v153 offset:37888
	ds_read_b128 v[208:211], v153 offset:38912
	ds_read_b128 v[212:215], v153 offset:39936
	global_load_lds_dwordx4 v[224:225], off
	v_lshl_add_u64 v[224:225], s[30:31], 0, v[132:133]
	s_mov_b32 m0, s61
	s_nop 0
	global_load_lds_dwordx4 v[224:225], off
	s_waitcnt vmcnt(8)
	s_waitcnt lgkmcnt(0)
	s_barrier
	s_setprio 1
	s_waitcnt lgkmcnt(0)
	v_mfma_f32_16x16x32_bf16 v[124:127], v[144:147], v[184:187], v[124:127]
	v_mfma_f32_16x16x32_bf16 v[120:123], v[160:163], v[184:187], v[120:123]
	v_mfma_f32_16x16x32_bf16 v[108:111], v[144:147], v[192:195], v[108:111]
	v_mfma_f32_16x16x32_bf16 v[104:107], v[160:163], v[192:195], v[104:107]
	v_mfma_f32_16x16x32_bf16 v[92:95], v[144:147], v[200:203], v[92:95]
	v_mfma_f32_16x16x32_bf16 v[88:91], v[160:163], v[200:203], v[88:91]
	v_mfma_f32_16x16x32_bf16 v[76:79], v[144:147], v[208:211], v[76:79]
	v_mfma_f32_16x16x32_bf16 v[72:75], v[160:163], v[208:211], v[72:75]
	v_mfma_f32_16x16x32_bf16 v[124:127], v[156:159], v[188:191], v[124:127]
	v_mfma_f32_16x16x32_bf16 v[120:123], v[164:167], v[188:191], v[120:123]
	v_mfma_f32_16x16x32_bf16 v[108:111], v[156:159], v[196:199], v[108:111]
	v_mfma_f32_16x16x32_bf16 v[104:107], v[164:167], v[196:199], v[104:107]
	v_mfma_f32_16x16x32_bf16 v[92:95], v[156:159], v[204:207], v[92:95]
	v_mfma_f32_16x16x32_bf16 v[88:91], v[164:167], v[204:207], v[88:91]
	v_mfma_f32_16x16x32_bf16 v[76:79], v[156:159], v[212:215], v[76:79]
	v_mfma_f32_16x16x32_bf16 v[72:75], v[164:167], v[212:215], v[72:75]
	s_setprio 0
	s_setprio 1
	v_mfma_f32_16x16x32_bf16 v[116:119], v[168:171], v[184:187], v[116:119]
	v_mfma_f32_16x16x32_bf16 v[112:115], v[176:179], v[184:187], v[112:115]
	v_mfma_f32_16x16x32_bf16 v[100:103], v[168:171], v[192:195], v[100:103]
	v_mfma_f32_16x16x32_bf16 v[96:99], v[176:179], v[192:195], v[96:99]
	v_mfma_f32_16x16x32_bf16 v[84:87], v[168:171], v[200:203], v[84:87]
	v_mfma_f32_16x16x32_bf16 v[80:83], v[176:179], v[200:203], v[80:83]
	v_mfma_f32_16x16x32_bf16 v[68:71], v[168:171], v[208:211], v[68:71]
	v_mfma_f32_16x16x32_bf16 v[64:67], v[176:179], v[208:211], v[64:67]
	v_mfma_f32_16x16x32_bf16 v[116:119], v[172:175], v[188:191], v[116:119]
	v_mfma_f32_16x16x32_bf16 v[112:115], v[180:183], v[188:191], v[112:115]
	v_mfma_f32_16x16x32_bf16 v[100:103], v[172:175], v[196:199], v[100:103]
	v_mfma_f32_16x16x32_bf16 v[96:99], v[180:183], v[196:199], v[96:99]
	v_mfma_f32_16x16x32_bf16 v[84:87], v[172:175], v[204:207], v[84:87]
	v_mfma_f32_16x16x32_bf16 v[80:83], v[180:183], v[204:207], v[80:83]
	v_mfma_f32_16x16x32_bf16 v[68:71], v[172:175], v[212:215], v[68:71]
	v_mfma_f32_16x16x32_bf16 v[64:67], v[180:183], v[212:215], v[64:67]
	s_setprio 0
	s_barrier
; #define PG8_STAGE(bufoff, gbase, voff) do { _Pragma("unroll") for (int _i = 0; _i < 2; ++_i) \
;         __builtin_amdgcn_global_load_lds((const unsigned*)((const char*)(gbase) + (voff)[_i]), (PG8_LAS unsigned*)(lds + (bufoff) + ldsw + _i * 8192), 16, 0, 0); } while (0)
; #define PG8_LDA(dst, b, h) do { _Pragma("unroll") for (int m = 0; m < 4; ++m) _Pragma("unroll") for (int k = 0; k < 2; ++k) dst[m][k] = *(const PG8_LAS bf16x8*)(lds + PG8_SA(b, h) + aoff + m * 2048 + k * 1024); } while (0)
; #define PG8_MMA(ai, bj, At, Bt) do { __builtin_amdgcn_s_setprio(1); _Pragma("unroll") for (int m = 0; m < 4; ++m) _Pragma("unroll") for (int n = 0; n < 2; ++n) _Pragma("unroll") for (int k = 0; k < 2; ++k) \
;         acc[ai][bj][m][n] = __builtin_amdgcn_mfma_f32_16x16x32_bf16(Bt[n][k], At[m][k], acc[ai][bj][m][n], 0, 0, 0); __builtin_amdgcn_s_setprio(0); } while (0)
; #define PG8_WAIT_V(n) asm volatile("s_waitcnt vmcnt(" #n ")" ::: "memory")
; #define PG8_WAIT_L(n) asm volatile("s_waitcnt lgkmcnt(" #n ")" ::: "memory")
; #define PG8_BAR __builtin_amdgcn_s_barrier()
; #define PG8_SCHED __builtin_amdgcn_sched_barrier(0)
; template <class Epi, class Sched, bool ALIGN_EPI = false, bool SP2 = false>
; __device__ __forceinline__ void gemm_phase(PG8_LAS unsigned char* lds, const Gemm g, const Sched& S, const Epi& E) {
;     ...
;         for (int t = 0; t < nt; t += 2) {
;     ...
;             PG8_LDA(At, 1, 1); PG8_STAGE(PG8_SB(1, 0), b3, voffB); PG8_STAGE(PG8_SB(1, 1), b3 + hstep, voffB); PG8_STAGE(PG8_SA(1, 0), a3, voffA);
;             PG8_WAIT_V(8); PG8_WAIT_L(0); PG8_BAR; PG8_MMA(1, 0, At, B0); PG8_MMA(1, 1, At, B1); PG8_BAR; PG8_SCHED;
	s_add_i32 s30, s81, s58
	v_lshl_add_u64 v[216:217], v[216:217], 0, s[16:17]
	s_mov_b32 m0, s30
	ds_read_b128 v[184:187], v153 offset:49152
	ds_read_b128 v[188:191], v153 offset:50176
	ds_read_b128 v[192:195], v153 offset:51200
	ds_read_b128 v[196:199], v153 offset:52224
	ds_read_b128 v[200:203], v153 offset:53248
	ds_read_b128 v[204:207], v153 offset:54272
	ds_read_b128 v[208:211], v153 offset:55296
	ds_read_b128 v[212:215], v153 offset:56320
	global_load_lds_dwordx4 v[216:217], off
	s_add_i32 m0, s30, 0x2000
	s_add_u32 s30, s54, 0x40080
	v_lshl_add_u64 v[216:217], v[218:219], 0, s[16:17]
	s_addc_u32 s31, s55, 0
	s_add_i32 s54, s82, s58
	global_load_lds_dwordx4 v[216:217], off
	v_lshl_add_u64 v[216:217], s[30:31], 0, v[130:131]
	s_mov_b32 m0, s54
	s_nop 0
	global_load_lds_dwordx4 v[216:217], off
	v_lshl_add_u64 v[216:217], s[30:31], 0, v[134:135]
	s_add_i32 m0, s54, 0x2000
	s_nop 0
	global_load_lds_dwordx4 v[216:217], off
	v_lshl_add_u64 v[216:217], v[220:221], 0, s[16:17]
	s_mov_b32 m0, s63
	s_nop 0
	global_load_lds_dwordx4 v[216:217], off
	v_lshl_add_u64 v[216:217], v[222:223], 0, s[16:17]
	s_mov_b32 m0, s64
	s_nop 0
	global_load_lds_dwordx4 v[216:217], off
	s_waitcnt vmcnt(8)
	s_waitcnt lgkmcnt(0)
	s_barrier
	s_setprio 1
	s_waitcnt lgkmcnt(0)
	v_mfma_f32_16x16x32_bf16 v[60:63], v[144:147], v[184:187], v[60:63]
	v_mfma_f32_16x16x32_bf16 v[56:59], v[160:163], v[184:187], v[56:59]
	v_mfma_f32_16x16x32_bf16 v[44:47], v[144:147], v[192:195], v[44:47]
	v_mfma_f32_16x16x32_bf16 v[40:43], v[160:163], v[192:195], v[40:43]
	v_mfma_f32_16x16x32_bf16 v[28:31], v[144:147], v[200:203], v[28:31]
	v_mfma_f32_16x16x32_bf16 v[24:27], v[160:163], v[200:203], v[24:27]
	v_mfma_f32_16x16x32_bf16 v[12:15], v[144:147], v[208:211], v[12:15]
	v_mfma_f32_16x16x32_bf16 v[8:11], v[160:163], v[208:211], v[8:11]
	v_mfma_f32_16x16x32_bf16 v[60:63], v[156:159], v[188:191], v[60:63]
	v_mfma_f32_16x16x32_bf16 v[56:59], v[164:167], v[188:191], v[56:59]
	v_mfma_f32_16x16x32_bf16 v[44:47], v[156:159], v[196:199], v[44:47]
	v_mfma_f32_16x16x32_bf16 v[40:43], v[164:167], v[196:199], v[40:43]
	v_mfma_f32_16x16x32_bf16 v[28:31], v[156:159], v[204:207], v[28:31]
	v_mfma_f32_16x16x32_bf16 v[24:27], v[164:167], v[204:207], v[24:27]
	v_mfma_f32_16x16x32_bf16 v[12:15], v[156:159], v[212:215], v[12:15]
	v_mfma_f32_16x16x32_bf16 v[8:11], v[164:167], v[212:215], v[8:11]
	s_setprio 0
	s_setprio 1
	v_mfma_f32_16x16x32_bf16 v[52:55], v[168:171], v[184:187], v[52:55]
	v_mfma_f32_16x16x32_bf16 v[48:51], v[176:179], v[184:187], v[48:51]
	v_mfma_f32_16x16x32_bf16 v[36:39], v[168:171], v[192:195], v[36:39]
	v_mfma_f32_16x16x32_bf16 v[32:35], v[176:179], v[192:195], v[32:35]
	v_mfma_f32_16x16x32_bf16 v[20:23], v[168:171], v[200:203], v[20:23]
	v_mfma_f32_16x16x32_bf16 v[16:19], v[176:179], v[200:203], v[16:19]
	v_mfma_f32_16x16x32_bf16 v[4:7], v[168:171], v[208:211], v[4:7]
	v_mfma_f32_16x16x32_bf16 v[0:3], v[176:179], v[208:211], v[0:3]
	v_mfma_f32_16x16x32_bf16 v[52:55], v[172:175], v[188:191], v[52:55]
	v_mfma_f32_16x16x32_bf16 v[48:51], v[180:183], v[188:191], v[48:51]
	v_mfma_f32_16x16x32_bf16 v[36:39], v[172:175], v[196:199], v[36:39]
	v_mfma_f32_16x16x32_bf16 v[32:35], v[180:183], v[196:199], v[32:35]
	v_mfma_f32_16x16x32_bf16 v[20:23], v[172:175], v[204:207], v[20:23]
	v_mfma_f32_16x16x32_bf16 v[16:19], v[180:183], v[204:207], v[16:19]
	v_mfma_f32_16x16x32_bf16 v[4:7], v[172:175], v[212:215], v[4:7]
	v_mfma_f32_16x16x32_bf16 v[0:3], v[180:183], v[212:215], v[0:3]
	s_setprio 0
	s_barrier
	s_add_i32 s80, s80, 2
	s_add_u32 s52, s52, 0x100
	s_addc_u32 s53, s53, 0
	s_add_u32 s76, s76, 0x100
	s_addc_u32 s77, s77, 0
	s_cmp_gt_u32 s80, 13
	s_cbranch_scc0 .LBB0_1155
	s_branch .Lgx_g5

; #define PG8_STAGE(bufoff, gbase, voff) do { _Pragma("unroll") for (int _i = 0; _i < 2; ++_i) \
;         __builtin_amdgcn_global_load_lds((const unsigned*)((const char*)(gbase) + (voff)[_i]), (PG8_LAS unsigned*)(lds + (bufoff) + ldsw + _i * 8192), 16, 0, 0); } while (0)
; #define PG8_LDA(dst, b, h) do { _Pragma("unroll") for (int m = 0; m < 4; ++m) _Pragma("unroll") for (int k = 0; k < 2; ++k) dst[m][k] = *(const PG8_LAS bf16x8*)(lds + PG8_SA(b, h) + aoff + m * 2048 + k * 1024); } while (0)
; #define PG8_LDB(dst, b, h) do { _Pragma("unroll") for (int n = 0; n < 2; ++n) _Pragma("unroll") for (int k = 0; k < 2; ++k) dst[n][k] = *(const PG8_LAS bf16x8*)(lds + PG8_SB(b, h) + boff + n * 2048 + k * 1024); } while (0)
; #define PG8_MMA(ai, bj, At, Bt) do { __builtin_amdgcn_s_setprio(1); _Pragma("unroll") for (int m = 0; m < 4; ++m) _Pragma("unroll") for (int n = 0; n < 2; ++n) _Pragma("unroll") for (int k = 0; k < 2; ++k) \
;         acc[ai][bj][m][n] = __builtin_amdgcn_mfma_f32_16x16x32_bf16(Bt[n][k], At[m][k], acc[ai][bj][m][n], 0, 0, 0); __builtin_amdgcn_s_setprio(0); } while (0)
; template <class Epi, class Sched, bool ALIGN_EPI = false, bool SP2 = false>
; __device__ __forceinline__ void gemm_phase(PG8_LAS unsigned char* lds, const Gemm g, const Sched& S, const Epi& E) {
;     ...
;         const bool has_next = S.next(ui + 1, nxt);
;         const char* nA = has_next ? (const char*)g.A + (size_t)nxt.pm * tstep : cA; const char* nB = has_next ? (const char*)g.Bt + (size_t)nxt.pn * tstep : cB;
; #pragma unroll 1
;         for (int t = 0; t < nt; t += 2) {
;             const bool last = (t == nt - 2);
;             const char* a1 = cA + (size_t)(t + 1) * kstep;
;             const char* a2 = last ? nA : cA + (size_t)(t + 2) * kstep; const char* b2 = last ? nB : cB + (size_t)(t + 2) * kstep;
;             const char* a3 = a2 + kstep; const char* b3 = b2 + kstep;
;             if (last && has_next) S.a_ready(nxt);
;             if constexpr (SP2) {
;             PG8_LDB(B0, 0, 0); PG8_LDB(B1, 0, 1); PG8_SCHED; PG8_LDA(At, 0, 0); PG8_STAGE(PG8_SA(1, 1), a1 + hstep, voffA);
;             PG8_WAIT_V(8); PG8_WAIT_L(0); PG8_BAR; PG8_MMA(0, 0, At, B0); PG8_MMA(0, 1, At, B1); PG8_BAR; PG8_SCHED;
;             PG8_LDA(At, 0, 1); PG8_STAGE(PG8_SB(0, 0), b2, voffB); PG8_STAGE(PG8_SB(0, 1), b2 + hstep, voffB); PG8_STAGE(PG8_SA(0, 0), a2, voffA);
.LBB0_1299:
	s_ashr_i32 s41, s40, 31
	s_lshl_b64 s[30:31], s[40:41], 18
	s_add_u32 s42, s10, s30
	s_addc_u32 s43, s11, s31
	s_and_b64 s[30:31], s[6:7], exec
	s_cselect_b32 s41, s43, s51
	s_cselect_b32 s47, s42, s50
	s_ashr_i32 s39, s38, 31
	s_lshl_b64 s[30:31], s[38:39], 18
	s_add_u32 s44, s0, s30
	s_addc_u32 s45, s1, s31
	s_and_b64 s[30:31], s[6:7], exec
	s_cselect_b32 s39, s45, s53
	s_cselect_b32 s65, s44, s52
	s_add_u32 s50, s50, 0x20080
	s_addc_u32 s51, s51, 0
	s_add_u32 s66, s52, 0x100
	v_mov_b32_e32 v0, 0
	s_addc_u32 s67, s53, 0
	s_mov_b32 s68, -2
	ds_read_b128 v[112:115], v246
	ds_read_b128 v[116:119], v246 offset:1024
	ds_read_b128 v[128:131], v246 offset:2048
	ds_read_b128 v[132:135], v246 offset:3072
	ds_read_b128 v[136:139], v247
	ds_read_b128 v[140:143], v247 offset:1024
	ds_read_b128 v[144:147], v247 offset:2048
	ds_read_b128 v[156:159], v247 offset:3072
	s_add_u32 s30, s50, 0xfffe0080
	s_addc_u32 s31, s51, -1
	s_cmp_eq_u32 s68, 4
	s_cselect_b32 s55, s41, s31
	s_cselect_b32 s54, s47, s30
	s_cselect_b32 s53, s39, s67
	s_cselect_b32 s52, s65, s66
	v_lshl_add_u64 v[206:207], s[50:51], 0, v[200:201]
	s_add_i32 m0, s49, 0xc000
	ds_read_b128 v[160:163], v248
	ds_read_b128 v[164:167], v248 offset:1024
	ds_read_b128 v[168:171], v248 offset:2048
	ds_read_b128 v[172:175], v248 offset:3072
	ds_read_b128 v[176:179], v248 offset:4096
	ds_read_b128 v[180:183], v248 offset:5120
	ds_read_b128 v[184:187], v248 offset:6144
	ds_read_b128 v[188:191], v248 offset:7168
	global_load_lds_dwordx4 v[206:207], off
	v_lshl_add_u64 v[206:207], s[50:51], 0, v[202:203]
	s_add_i32 m0, s49, 0xe000
	s_nop 0
	global_load_lds_dwordx4 v[206:207], off
	s_waitcnt vmcnt(8)
	s_waitcnt lgkmcnt(0)
	s_barrier
	s_setprio 1
	s_waitcnt lgkmcnt(0)
	v_mfma_f32_16x16x32_bf16 v[152:155], v[112:115], v[160:163], 0
	v_mfma_f32_16x16x32_bf16 v[148:151], v[128:131], v[160:163], 0
	v_mfma_f32_16x16x32_bf16 v[108:111], v[112:115], v[168:171], 0
	v_mfma_f32_16x16x32_bf16 v[104:107], v[128:131], v[168:171], 0
	v_mfma_f32_16x16x32_bf16 v[92:95], v[112:115], v[176:179], 0
	v_mfma_f32_16x16x32_bf16 v[88:91], v[128:131], v[176:179], 0
	v_mfma_f32_16x16x32_bf16 v[76:79], v[112:115], v[184:187], 0
	v_mfma_f32_16x16x32_bf16 v[72:75], v[128:131], v[184:187], 0
	v_mfma_f32_16x16x32_bf16 v[152:155], v[116:119], v[164:167], v[152:155]
	v_mfma_f32_16x16x32_bf16 v[148:151], v[132:135], v[164:167], v[148:151]
	v_mfma_f32_16x16x32_bf16 v[108:111], v[116:119], v[172:175], v[108:111]
	v_mfma_f32_16x16x32_bf16 v[104:107], v[132:135], v[172:175], v[104:107]
	v_mfma_f32_16x16x32_bf16 v[92:95], v[116:119], v[180:183], v[92:95]
	v_mfma_f32_16x16x32_bf16 v[88:91], v[132:135], v[180:183], v[88:91]
	v_mfma_f32_16x16x32_bf16 v[76:79], v[116:119], v[188:191], v[76:79]
	v_mfma_f32_16x16x32_bf16 v[72:75], v[132:135], v[188:191], v[72:75]
	s_setprio 0
	s_setprio 1
	v_mfma_f32_16x16x32_bf16 v[124:127], v[136:139], v[160:163], 0
	v_mfma_f32_16x16x32_bf16 v[120:123], v[144:147], v[160:163], 0
	v_mfma_f32_16x16x32_bf16 v[100:103], v[136:139], v[168:171], 0
	v_mfma_f32_16x16x32_bf16 v[96:99], v[144:147], v[168:171], 0
	v_mfma_f32_16x16x32_bf16 v[84:87], v[136:139], v[176:179], 0
	v_mfma_f32_16x16x32_bf16 v[80:83], v[144:147], v[176:179], 0
	v_mfma_f32_16x16x32_bf16 v[68:71], v[136:139], v[184:187], 0
	v_mfma_f32_16x16x32_bf16 v[64:67], v[144:147], v[184:187], 0
	v_mfma_f32_16x16x32_bf16 v[124:127], v[140:143], v[164:167], v[124:127]
	v_mfma_f32_16x16x32_bf16 v[120:123], v[156:159], v[164:167], v[120:123]
	v_mfma_f32_16x16x32_bf16 v[100:103], v[140:143], v[172:175], v[100:103]
	v_mfma_f32_16x16x32_bf16 v[96:99], v[156:159], v[172:175], v[96:99]
	v_mfma_f32_16x16x32_bf16 v[84:87], v[140:143], v[180:183], v[84:87]
	v_mfma_f32_16x16x32_bf16 v[80:83], v[156:159], v[180:183], v[80:83]
	v_mfma_f32_16x16x32_bf16 v[68:71], v[140:143], v[188:191], v[68:71]
	v_mfma_f32_16x16x32_bf16 v[64:67], v[156:159], v[188:191], v[64:67]
	s_setprio 0
	s_barrier
	s_add_i32 s30, s63, s56
	v_lshl_add_u64 v[206:207], s[52:53], 0, v[194:195]
	s_mov_b32 m0, s30
	ds_read_b128 v[160:163], v248 offset:16384
	ds_read_b128 v[164:167], v248 offset:17408
	ds_read_b128 v[168:171], v248 offset:18432
	ds_read_b128 v[172:175], v248 offset:19456
	ds_read_b128 v[176:179], v248 offset:20480
	ds_read_b128 v[180:183], v248 offset:21504
	ds_read_b128 v[184:187], v248 offset:22528
	ds_read_b128 v[188:191], v248 offset:23552
	global_load_lds_dwordx4 v[206:207], off
	s_add_i32 m0, s30, 0x2000
	s_add_u32 s30, s52, 0x20000
	v_lshl_add_u64 v[208:209], s[52:53], 0, v[198:199]
	s_addc_u32 s31, s53, 0
	s_add_i32 s69, s64, s56
	global_load_lds_dwordx4 v[208:209], off
	v_lshl_add_u64 v[210:211], s[30:31], 0, v[194:195]
	s_mov_b32 m0, s69
	v_lshl_add_u64 v[212:213], s[54:55], 0, v[196:197]
	global_load_lds_dwordx4 v[210:211], off
	v_lshl_add_u64 v[210:211], s[30:31], 0, v[198:199]
	s_add_i32 m0, s69, 0x2000
	s_nop 0
	global_load_lds_dwordx4 v[210:211], off
	v_lshl_add_u64 v[210:211], s[54:55], 0, v[192:193]
	s_mov_b32 m0, s49
	s_nop 0
	global_load_lds_dwordx4 v[210:211], off
	s_mov_b32 m0, s57
	s_nop 0
	global_load_lds_dwordx4 v[212:213], off
	s_waitcnt vmcnt(8)
	s_waitcnt lgkmcnt(0)
	s_barrier
; #define PG8_STAGE(bufoff, gbase, voff) do { _Pragma("unroll") for (int _i = 0; _i < 2; ++_i) \
;         __builtin_amdgcn_global_load_lds((const unsigned*)((const char*)(gbase) + (voff)[_i]), (PG8_LAS unsigned*)(lds + (bufoff) + ldsw + _i * 8192), 16, 0, 0); } while (0)
; #define PG8_LDA(dst, b, h) do { _Pragma("unroll") for (int m = 0; m < 4; ++m) _Pragma("unroll") for (int k = 0; k < 2; ++k) dst[m][k] = *(const PG8_LAS bf16x8*)(lds + PG8_SA(b, h) + aoff + m * 2048 + k * 1024); } while (0)
; #define PG8_LDB(dst, b, h) do { _Pragma("unroll") for (int n = 0; n < 2; ++n) _Pragma("unroll") for (int k = 0; k < 2; ++k) dst[n][k] = *(const PG8_LAS bf16x8*)(lds + PG8_SB(b, h) + boff + n * 2048 + k * 1024); } while (0)
; #define PG8_MMA(ai, bj, At, Bt) do { __builtin_amdgcn_s_setprio(1); _Pragma("unroll") for (int m = 0; m < 4; ++m) _Pragma("unroll") for (int n = 0; n < 2; ++n) _Pragma("unroll") for (int k = 0; k < 2; ++k) \
;         acc[ai][bj][m][n] = __builtin_amdgcn_mfma_f32_16x16x32_bf16(Bt[n][k], At[m][k], acc[ai][bj][m][n], 0, 0, 0); __builtin_amdgcn_s_setprio(0); } while (0)
; #define PG8_WAIT_V(n) asm volatile("s_waitcnt vmcnt(" #n ")" ::: "memory")
; #define PG8_WAIT_L(n) asm volatile("s_waitcnt lgkmcnt(" #n ")" ::: "memory")
; #define PG8_BAR __builtin_amdgcn_s_barrier()
; #define PG8_SCHED __builtin_amdgcn_sched_barrier(0)
; template <class Epi, class Sched, bool ALIGN_EPI = false, bool SP2 = false>
; __device__ __forceinline__ void gemm_phase(PG8_LAS unsigned char* lds, const Gemm g, const Sched& S, const Epi& E) {
;     ...
;             PG8_WAIT_V(8); PG8_WAIT_L(0); PG8_BAR; PG8_MMA(1, 0, At, B0); PG8_MMA(1, 1, At, B1); PG8_BAR; PG8_SCHED;
;             PG8_LDB(B0, 1, 0); PG8_LDB(B1, 1, 1); PG8_SCHED; PG8_LDA(At, 1, 0); PG8_STAGE(PG8_SA(0, 1), a2 + hstep, voffA);
;             PG8_WAIT_V(8); PG8_WAIT_L(0); PG8_BAR; PG8_MMA(0, 0, At, B0); PG8_MMA(0, 1, At, B1); PG8_BAR; PG8_SCHED;
	s_setprio 1
	s_waitcnt lgkmcnt(0)
	v_mfma_f32_16x16x32_bf16 v[60:63], v[112:115], v[160:163], 0
	v_mfma_f32_16x16x32_bf16 v[56:59], v[128:131], v[160:163], 0
	v_mfma_f32_16x16x32_bf16 v[44:47], v[112:115], v[168:171], 0
	v_mfma_f32_16x16x32_bf16 v[40:43], v[128:131], v[168:171], 0
	v_mfma_f32_16x16x32_bf16 v[28:31], v[112:115], v[176:179], 0
	v_mfma_f32_16x16x32_bf16 v[24:27], v[128:131], v[176:179], 0
	v_mfma_f32_16x16x32_bf16 v[12:15], v[112:115], v[184:187], 0
	v_mfma_f32_16x16x32_bf16 v[8:11], v[128:131], v[184:187], 0
	v_mfma_f32_16x16x32_bf16 v[60:63], v[116:119], v[164:167], v[60:63]
	v_mfma_f32_16x16x32_bf16 v[56:59], v[132:135], v[164:167], v[56:59]
	v_mfma_f32_16x16x32_bf16 v[44:47], v[116:119], v[172:175], v[44:47]
	v_mfma_f32_16x16x32_bf16 v[40:43], v[132:135], v[172:175], v[40:43]
	v_mfma_f32_16x16x32_bf16 v[28:31], v[116:119], v[180:183], v[28:31]
	v_mfma_f32_16x16x32_bf16 v[24:27], v[132:135], v[180:183], v[24:27]
	v_mfma_f32_16x16x32_bf16 v[12:15], v[116:119], v[188:191], v[12:15]
	v_mfma_f32_16x16x32_bf16 v[8:11], v[132:135], v[188:191], v[8:11]
	s_setprio 0
	s_setprio 1
	v_mfma_f32_16x16x32_bf16 v[52:55], v[136:139], v[160:163], 0
	v_mfma_f32_16x16x32_bf16 v[48:51], v[144:147], v[160:163], 0
	v_mfma_f32_16x16x32_bf16 v[36:39], v[136:139], v[168:171], 0
	v_mfma_f32_16x16x32_bf16 v[32:35], v[144:147], v[168:171], 0
	v_mfma_f32_16x16x32_bf16 v[20:23], v[136:139], v[176:179], 0
	v_mfma_f32_16x16x32_bf16 v[16:19], v[144:147], v[176:179], 0
	v_mfma_f32_16x16x32_bf16 v[4:7], v[136:139], v[184:187], 0
	v_mfma_f32_16x16x32_bf16 v[0:3], v[144:147], v[184:187], 0
	v_mfma_f32_16x16x32_bf16 v[52:55], v[140:143], v[164:167], v[52:55]
	v_mfma_f32_16x16x32_bf16 v[48:51], v[156:159], v[164:167], v[48:51]
	v_mfma_f32_16x16x32_bf16 v[36:39], v[140:143], v[172:175], v[36:39]
	v_mfma_f32_16x16x32_bf16 v[32:35], v[156:159], v[172:175], v[32:35]
	v_mfma_f32_16x16x32_bf16 v[20:23], v[140:143], v[180:183], v[20:23]
	v_mfma_f32_16x16x32_bf16 v[16:19], v[156:159], v[180:183], v[16:19]
	v_mfma_f32_16x16x32_bf16 v[4:7], v[140:143], v[188:191], v[4:7]
	v_mfma_f32_16x16x32_bf16 v[0:3], v[156:159], v[188:191], v[0:3]
	s_setprio 0
	s_barrier
	s_add_i32 s69, 0, 0x18000
	s_add_i32 s70, 0, 0x1c000
	v_add_u32_e32 v132, s69, v244
	v_add_u32_e32 v156, s70, v244
	ds_read_b128 v[112:115], v132
	ds_read_b128 v[116:119], v132 offset:1024
	ds_read_b128 v[128:131], v132 offset:2048
	ds_read_b128 v[132:135], v132 offset:3072
	ds_read_b128 v[136:139], v156
	ds_read_b128 v[140:143], v156 offset:1024
	ds_read_b128 v[144:147], v156 offset:2048
	ds_read_b128 v[156:159], v156 offset:3072
	s_add_u32 s30, s54, 0x20000
	s_addc_u32 s31, s55, 0
	s_mov_b32 m0, s58
	v_lshl_add_u64 v[214:215], s[30:31], 0, v[192:193]
	ds_read_b128 v[160:163], v248 offset:32768
	ds_read_b128 v[164:167], v248 offset:33792
	ds_read_b128 v[168:171], v248 offset:34816
	ds_read_b128 v[172:175], v248 offset:35840
	ds_read_b128 v[176:179], v248 offset:36864
	ds_read_b128 v[180:183], v248 offset:37888
	ds_read_b128 v[184:187], v248 offset:38912
	ds_read_b128 v[188:191], v248 offset:39936
	global_load_lds_dwordx4 v[214:215], off
	v_lshl_add_u64 v[214:215], s[30:31], 0, v[196:197]
	s_mov_b32 m0, s59
	s_nop 0
	global_load_lds_dwordx4 v[214:215], off
	s_waitcnt vmcnt(8)
	s_waitcnt lgkmcnt(0)
	s_barrier
	s_setprio 1
	s_waitcnt lgkmcnt(0)
	v_mfma_f32_16x16x32_bf16 v[152:155], v[112:115], v[160:163], v[152:155]
	v_mfma_f32_16x16x32_bf16 v[148:151], v[128:131], v[160:163], v[148:151]
	v_mfma_f32_16x16x32_bf16 v[108:111], v[112:115], v[168:171], v[108:111]
	v_mfma_f32_16x16x32_bf16 v[104:107], v[128:131], v[168:171], v[104:107]
	v_mfma_f32_16x16x32_bf16 v[92:95], v[112:115], v[176:179], v[92:95]
	v_mfma_f32_16x16x32_bf16 v[88:91], v[128:131], v[176:179], v[88:91]
	v_mfma_f32_16x16x32_bf16 v[76:79], v[112:115], v[184:187], v[76:79]
	v_mfma_f32_16x16x32_bf16 v[72:75], v[128:131], v[184:187], v[72:75]
	v_mfma_f32_16x16x32_bf16 v[152:155], v[116:119], v[164:167], v[152:155]
	v_mfma_f32_16x16x32_bf16 v[148:151], v[132:135], v[164:167], v[148:151]
	v_mfma_f32_16x16x32_bf16 v[108:111], v[116:119], v[172:175], v[108:111]
	v_mfma_f32_16x16x32_bf16 v[104:107], v[132:135], v[172:175], v[104:107]
	v_mfma_f32_16x16x32_bf16 v[92:95], v[116:119], v[180:183], v[92:95]
	v_mfma_f32_16x16x32_bf16 v[88:91], v[132:135], v[180:183], v[88:91]
	v_mfma_f32_16x16x32_bf16 v[76:79], v[116:119], v[188:191], v[76:79]
	v_mfma_f32_16x16x32_bf16 v[72:75], v[132:135], v[188:191], v[72:75]
	s_setprio 0
	s_setprio 1
	v_mfma_f32_16x16x32_bf16 v[124:127], v[136:139], v[160:163], v[124:127]
	v_mfma_f32_16x16x32_bf16 v[120:123], v[144:147], v[160:163], v[120:123]
	v_mfma_f32_16x16x32_bf16 v[100:103], v[136:139], v[168:171], v[100:103]
	v_mfma_f32_16x16x32_bf16 v[96:99], v[144:147], v[168:171], v[96:99]
	v_mfma_f32_16x16x32_bf16 v[84:87], v[136:139], v[176:179], v[84:87]
	v_mfma_f32_16x16x32_bf16 v[80:83], v[144:147], v[176:179], v[80:83]
	v_mfma_f32_16x16x32_bf16 v[68:71], v[136:139], v[184:187], v[68:71]
	v_mfma_f32_16x16x32_bf16 v[64:67], v[144:147], v[184:187], v[64:67]
	v_mfma_f32_16x16x32_bf16 v[124:127], v[140:143], v[164:167], v[124:127]
	v_mfma_f32_16x16x32_bf16 v[120:123], v[156:159], v[164:167], v[120:123]
	v_mfma_f32_16x16x32_bf16 v[100:103], v[140:143], v[172:175], v[100:103]
	v_mfma_f32_16x16x32_bf16 v[96:99], v[156:159], v[172:175], v[96:99]
	v_mfma_f32_16x16x32_bf16 v[84:87], v[140:143], v[180:183], v[84:87]
	v_mfma_f32_16x16x32_bf16 v[80:83], v[156:159], v[180:183], v[80:83]
	v_mfma_f32_16x16x32_bf16 v[68:71], v[140:143], v[188:191], v[68:71]
	v_mfma_f32_16x16x32_bf16 v[64:67], v[156:159], v[188:191], v[64:67]
	s_setprio 0
	s_barrier
; #define PG8_STAGE(bufoff, gbase, voff) do { _Pragma("unroll") for (int _i = 0; _i < 2; ++_i) \
;         __builtin_amdgcn_global_load_lds((const unsigned*)((const char*)(gbase) + (voff)[_i]), (PG8_LAS unsigned*)(lds + (bufoff) + ldsw + _i * 8192), 16, 0, 0); } while (0)
; #define PG8_LDA(dst, b, h) do { _Pragma("unroll") for (int m = 0; m < 4; ++m) _Pragma("unroll") for (int k = 0; k < 2; ++k) dst[m][k] = *(const PG8_LAS bf16x8*)(lds + PG8_SA(b, h) + aoff + m * 2048 + k * 1024); } while (0)
; #define PG8_MMA(ai, bj, At, Bt) do { __builtin_amdgcn_s_setprio(1); _Pragma("unroll") for (int m = 0; m < 4; ++m) _Pragma("unroll") for (int n = 0; n < 2; ++n) _Pragma("unroll") for (int k = 0; k < 2; ++k) \
;         acc[ai][bj][m][n] = __builtin_amdgcn_mfma_f32_16x16x32_bf16(Bt[n][k], At[m][k], acc[ai][bj][m][n], 0, 0, 0); __builtin_amdgcn_s_setprio(0); } while (0)
; #define PG8_WAIT_V(n) asm volatile("s_waitcnt vmcnt(" #n ")" ::: "memory")
; #define PG8_WAIT_L(n) asm volatile("s_waitcnt lgkmcnt(" #n ")" ::: "memory")
; #define PG8_BAR __builtin_amdgcn_s_barrier()
; #define PG8_SCHED __builtin_amdgcn_sched_barrier(0)
; template <class Epi, class Sched, bool ALIGN_EPI = false, bool SP2 = false>
; __device__ __forceinline__ void gemm_phase(PG8_LAS unsigned char* lds, const Gemm g, const Sched& S, const Epi& E) {
;     ...
;         for (int t = 0; t < nt; t += 2) {
;     ...
;             PG8_LDA(At, 1, 1); PG8_STAGE(PG8_SB(1, 0), b3, voffB); PG8_STAGE(PG8_SB(1, 1), b3 + hstep, voffB); PG8_STAGE(PG8_SA(1, 0), a3, voffA);
;             PG8_WAIT_V(8); PG8_WAIT_L(0); PG8_BAR; PG8_MMA(1, 0, At, B0); PG8_MMA(1, 1, At, B1); PG8_BAR; PG8_SCHED;
	s_add_i32 s30, s69, s56
	v_lshl_add_u64 v[206:207], v[206:207], 0, s[20:21]
	s_mov_b32 m0, s30
	ds_read_b128 v[160:163], v248 offset:49152
	ds_read_b128 v[164:167], v248 offset:50176
	ds_read_b128 v[168:171], v248 offset:51200
	ds_read_b128 v[172:175], v248 offset:52224
	ds_read_b128 v[176:179], v248 offset:53248
	ds_read_b128 v[180:183], v248 offset:54272
	ds_read_b128 v[184:187], v248 offset:55296
	ds_read_b128 v[188:191], v248 offset:56320
	global_load_lds_dwordx4 v[206:207], off
	s_add_i32 m0, s30, 0x2000
	s_add_u32 s30, s52, 0x20080
	v_lshl_add_u64 v[206:207], v[208:209], 0, s[20:21]
	s_addc_u32 s31, s53, 0
	s_add_i32 s52, s70, s56
	global_load_lds_dwordx4 v[206:207], off
	v_lshl_add_u64 v[206:207], s[30:31], 0, v[194:195]
	s_mov_b32 m0, s52
	s_nop 0
	global_load_lds_dwordx4 v[206:207], off
	v_lshl_add_u64 v[206:207], s[30:31], 0, v[198:199]
	s_add_i32 m0, s52, 0x2000
	s_nop 0
	global_load_lds_dwordx4 v[206:207], off
	v_lshl_add_u64 v[206:207], v[210:211], 0, s[20:21]
	s_mov_b32 m0, s61
	s_nop 0
	global_load_lds_dwordx4 v[206:207], off
	v_lshl_add_u64 v[206:207], v[212:213], 0, s[20:21]
	s_mov_b32 m0, s62
	s_nop 0
	global_load_lds_dwordx4 v[206:207], off
	s_waitcnt vmcnt(8)
	s_waitcnt lgkmcnt(0)
	s_barrier
	s_setprio 1
	s_waitcnt lgkmcnt(0)
	v_mfma_f32_16x16x32_bf16 v[60:63], v[112:115], v[160:163], v[60:63]
	v_mfma_f32_16x16x32_bf16 v[56:59], v[128:131], v[160:163], v[56:59]
	v_mfma_f32_16x16x32_bf16 v[44:47], v[112:115], v[168:171], v[44:47]
	v_mfma_f32_16x16x32_bf16 v[40:43], v[128:131], v[168:171], v[40:43]
	v_mfma_f32_16x16x32_bf16 v[28:31], v[112:115], v[176:179], v[28:31]
	v_mfma_f32_16x16x32_bf16 v[24:27], v[128:131], v[176:179], v[24:27]
	v_mfma_f32_16x16x32_bf16 v[12:15], v[112:115], v[184:187], v[12:15]
	v_mfma_f32_16x16x32_bf16 v[8:11], v[128:131], v[184:187], v[8:11]
	v_mfma_f32_16x16x32_bf16 v[60:63], v[116:119], v[164:167], v[60:63]
	v_mfma_f32_16x16x32_bf16 v[56:59], v[132:135], v[164:167], v[56:59]
	v_mfma_f32_16x16x32_bf16 v[44:47], v[116:119], v[172:175], v[44:47]
	v_mfma_f32_16x16x32_bf16 v[40:43], v[132:135], v[172:175], v[40:43]
	v_mfma_f32_16x16x32_bf16 v[28:31], v[116:119], v[180:183], v[28:31]
	v_mfma_f32_16x16x32_bf16 v[24:27], v[132:135], v[180:183], v[24:27]
	v_mfma_f32_16x16x32_bf16 v[12:15], v[116:119], v[188:191], v[12:15]
	v_mfma_f32_16x16x32_bf16 v[8:11], v[132:135], v[188:191], v[8:11]
	s_setprio 0
	s_setprio 1
	v_mfma_f32_16x16x32_bf16 v[52:55], v[136:139], v[160:163], v[52:55]
	v_mfma_f32_16x16x32_bf16 v[48:51], v[144:147], v[160:163], v[48:51]
	v_mfma_f32_16x16x32_bf16 v[36:39], v[136:139], v[168:171], v[36:39]
	v_mfma_f32_16x16x32_bf16 v[32:35], v[144:147], v[168:171], v[32:35]
	v_mfma_f32_16x16x32_bf16 v[20:23], v[136:139], v[176:179], v[20:23]
	v_mfma_f32_16x16x32_bf16 v[16:19], v[144:147], v[176:179], v[16:19]
	v_mfma_f32_16x16x32_bf16 v[4:7], v[136:139], v[184:187], v[4:7]
	v_mfma_f32_16x16x32_bf16 v[0:3], v[144:147], v[184:187], v[0:3]
	v_mfma_f32_16x16x32_bf16 v[52:55], v[140:143], v[164:167], v[52:55]
	v_mfma_f32_16x16x32_bf16 v[48:51], v[156:159], v[164:167], v[48:51]
	v_mfma_f32_16x16x32_bf16 v[36:39], v[140:143], v[172:175], v[36:39]
	v_mfma_f32_16x16x32_bf16 v[32:35], v[156:159], v[172:175], v[32:35]
	v_mfma_f32_16x16x32_bf16 v[20:23], v[140:143], v[180:183], v[20:23]
	v_mfma_f32_16x16x32_bf16 v[16:19], v[156:159], v[180:183], v[16:19]
	v_mfma_f32_16x16x32_bf16 v[4:7], v[140:143], v[188:191], v[4:7]
	v_mfma_f32_16x16x32_bf16 v[0:3], v[156:159], v[188:191], v[0:3]
	s_setprio 0
	s_barrier
	s_add_i32 s68, s68, 2
	s_add_u32 s50, s50, 0x100
	s_addc_u32 s51, s51, 0
	s_add_u32 s66, s66, 0x100
	s_addc_u32 s67, s67, 0
	s_cmp_gt_u32 s68, 5
	s_cbranch_scc0 .LBB0_1300
	s_branch .Lgx_g6

; #define PG8_BAR __builtin_amdgcn_s_barrier()
; template <class Epi, class Sched, bool ALIGN_EPI = false, bool SP2 = false>
; __device__ __forceinline__ void gemm_phase(PG8_LAS unsigned char* lds, const Gemm g, const Sched& S, const Epi& E) {
;     ...
;         if constexpr (ALIGN_EPI) { if (wr == 0) PG8_BAR; }
.Lgx_g6:
	s_and_b64 vcc, exec, s[36:37]
	s_cbranch_vccz .LBB0_1303
	s_barrier

; #define PG8_STAGE(bufoff, gbase, voff) do { _Pragma("unroll") for (int _i = 0; _i < 2; ++_i) \
;         __builtin_amdgcn_global_load_lds((const unsigned*)((const char*)(gbase) + (voff)[_i]), (PG8_LAS unsigned*)(lds + (bufoff) + ldsw + _i * 8192), 16, 0, 0); } while (0)
; #define PG8_LDA(dst, b, h) do { _Pragma("unroll") for (int m = 0; m < 4; ++m) _Pragma("unroll") for (int k = 0; k < 2; ++k) dst[m][k] = *(const PG8_LAS bf16x8*)(lds + PG8_SA(b, h) + aoff + m * 2048 + k * 1024); } while (0)
; #define PG8_LDB(dst, b, h) do { _Pragma("unroll") for (int n = 0; n < 2; ++n) _Pragma("unroll") for (int k = 0; k < 2; ++k) dst[n][k] = *(const PG8_LAS bf16x8*)(lds + PG8_SB(b, h) + boff + n * 2048 + k * 1024); } while (0)
; #define PG8_MMA(ai, bj, At, Bt) do { __builtin_amdgcn_s_setprio(1); _Pragma("unroll") for (int m = 0; m < 4; ++m) _Pragma("unroll") for (int n = 0; n < 2; ++n) _Pragma("unroll") for (int k = 0; k < 2; ++k) \
;         acc[ai][bj][m][n] = __builtin_amdgcn_mfma_f32_16x16x32_bf16(Bt[n][k], At[m][k], acc[ai][bj][m][n], 0, 0, 0); __builtin_amdgcn_s_setprio(0); } while (0)
; template <class Epi, class Sched, bool ALIGN_EPI = false, bool SP2 = false>
; __device__ __forceinline__ void gemm_phase(PG8_LAS unsigned char* lds, const Gemm g, const Sched& S, const Epi& E) {
;     ...
;         const bool has_next = S.next(ui + 1, nxt);
;         const char* nA = has_next ? (const char*)g.A + (size_t)nxt.pm * tstep : cA; const char* nB = has_next ? (const char*)g.Bt + (size_t)nxt.pn * tstep : cB;
; #pragma unroll 1
;         for (int t = 0; t < nt; t += 2) {
;             const bool last = (t == nt - 2);
;             const char* a1 = cA + (size_t)(t + 1) * kstep;
;             const char* a2 = last ? nA : cA + (size_t)(t + 2) * kstep; const char* b2 = last ? nB : cB + (size_t)(t + 2) * kstep;
;             const char* a3 = a2 + kstep; const char* b3 = b2 + kstep;
;             if (last && has_next) S.a_ready(nxt);
;             if constexpr (SP2) {
;             PG8_LDB(B0, 0, 0); PG8_LDB(B1, 0, 1); PG8_SCHED; PG8_LDA(At, 0, 0); PG8_STAGE(PG8_SA(1, 1), a1 + hstep, voffA);
;             PG8_WAIT_V(8); PG8_WAIT_L(0); PG8_BAR; PG8_MMA(0, 0, At, B0); PG8_MMA(0, 1, At, B1); PG8_BAR; PG8_SCHED;
;             PG8_LDA(At, 0, 1); PG8_STAGE(PG8_SB(0, 0), b2, voffB); PG8_STAGE(PG8_SB(0, 1), b2 + hstep, voffB); PG8_STAGE(PG8_SA(0, 0), a2, voffA);
.LBB0_1384:
	s_ashr_i32 s37, s36, 31
	s_lshl_b64 s[30:31], s[36:37], 19
	s_add_u32 s38, s10, s30
	s_addc_u32 s39, s11, s31
	s_and_b64 s[30:31], s[4:5], exec
	s_cselect_b32 s37, s39, s45
	s_cselect_b32 s62, s38, s44
	s_ashr_i32 s21, s20, 31
	s_lshl_b64 s[30:31], s[20:21], 19
	s_add_u32 s40, s0, s30
	s_addc_u32 s41, s1, s31
	s_and_b64 s[30:31], s[4:5], exec
	s_cselect_b32 s21, s41, s47
	s_cselect_b32 s63, s40, s46
	s_add_u32 s44, s44, 0x40080
	s_addc_u32 s45, s45, 0
	s_add_u32 s64, s46, 0x100
	v_mov_b32_e32 v0, 0
	s_addc_u32 s65, s47, 0
	s_mov_b32 s66, -2
	ds_read_b128 v[154:157], v149
	ds_read_b128 v[158:161], v149 offset:1024
	ds_read_b128 v[162:165], v149 offset:2048
	ds_read_b128 v[166:169], v149 offset:3072
	ds_read_b128 v[170:173], v150
	ds_read_b128 v[174:177], v150 offset:1024
	ds_read_b128 v[178:181], v150 offset:2048
	ds_read_b128 v[182:185], v150 offset:3072
	s_add_u32 s30, s44, 0xfffc0080
	s_addc_u32 s31, s45, -1
	s_cmp_eq_u32 s66, 12
	s_cselect_b32 s49, s37, s31
	s_cselect_b32 s48, s62, s30
	s_cselect_b32 s47, s21, s65
	s_cselect_b32 s46, s63, s64
	v_lshl_add_u64 v[144:145], s[44:45], 0, v[136:137]
	s_add_i32 m0, s43, 0xc000
	ds_read_b128 v[186:189], v151
	ds_read_b128 v[190:193], v151 offset:1024
	ds_read_b128 v[194:197], v151 offset:2048
	ds_read_b128 v[198:201], v151 offset:3072
	ds_read_b128 v[202:205], v151 offset:4096
	ds_read_b128 v[206:209], v151 offset:5120
	ds_read_b128 v[210:213], v151 offset:6144
	ds_read_b128 v[214:217], v151 offset:7168
	global_load_lds_dwordx4 v[144:145], off
	v_lshl_add_u64 v[144:145], s[44:45], 0, v[138:139]
	s_add_i32 m0, s43, 0xe000
	s_nop 0
	global_load_lds_dwordx4 v[144:145], off
	s_waitcnt vmcnt(8)
	s_waitcnt lgkmcnt(0)
	s_barrier
	s_setprio 1
	s_waitcnt lgkmcnt(0)
	v_mfma_f32_16x16x32_bf16 v[116:119], v[154:157], v[186:189], 0
	v_mfma_f32_16x16x32_bf16 v[112:115], v[162:165], v[186:189], 0
	v_mfma_f32_16x16x32_bf16 v[108:111], v[154:157], v[194:197], 0
	v_mfma_f32_16x16x32_bf16 v[100:103], v[162:165], v[194:197], 0
	v_mfma_f32_16x16x32_bf16 v[92:95], v[154:157], v[202:205], 0
	v_mfma_f32_16x16x32_bf16 v[84:87], v[162:165], v[202:205], 0
	v_mfma_f32_16x16x32_bf16 v[76:79], v[154:157], v[210:213], 0
	v_mfma_f32_16x16x32_bf16 v[68:71], v[162:165], v[210:213], 0
	v_mfma_f32_16x16x32_bf16 v[116:119], v[158:161], v[190:193], v[116:119]
	v_mfma_f32_16x16x32_bf16 v[112:115], v[166:169], v[190:193], v[112:115]
	v_mfma_f32_16x16x32_bf16 v[108:111], v[158:161], v[198:201], v[108:111]
	v_mfma_f32_16x16x32_bf16 v[100:103], v[166:169], v[198:201], v[100:103]
	v_mfma_f32_16x16x32_bf16 v[92:95], v[158:161], v[206:209], v[92:95]
	v_mfma_f32_16x16x32_bf16 v[84:87], v[166:169], v[206:209], v[84:87]
	v_mfma_f32_16x16x32_bf16 v[76:79], v[158:161], v[214:217], v[76:79]
	v_mfma_f32_16x16x32_bf16 v[68:71], v[166:169], v[214:217], v[68:71]
	s_setprio 0
	s_setprio 1
	v_mfma_f32_16x16x32_bf16 v[124:127], v[170:173], v[186:189], 0
	v_mfma_f32_16x16x32_bf16 v[120:123], v[178:181], v[186:189], 0
	v_mfma_f32_16x16x32_bf16 v[104:107], v[170:173], v[194:197], 0
	v_mfma_f32_16x16x32_bf16 v[96:99], v[178:181], v[194:197], 0
	v_mfma_f32_16x16x32_bf16 v[88:91], v[170:173], v[202:205], 0
	v_mfma_f32_16x16x32_bf16 v[80:83], v[178:181], v[202:205], 0
	v_mfma_f32_16x16x32_bf16 v[72:75], v[170:173], v[210:213], 0
	v_mfma_f32_16x16x32_bf16 v[64:67], v[178:181], v[210:213], 0
	v_mfma_f32_16x16x32_bf16 v[124:127], v[174:177], v[190:193], v[124:127]
	v_mfma_f32_16x16x32_bf16 v[120:123], v[182:185], v[190:193], v[120:123]
	v_mfma_f32_16x16x32_bf16 v[104:107], v[174:177], v[198:201], v[104:107]
	v_mfma_f32_16x16x32_bf16 v[96:99], v[182:185], v[198:201], v[96:99]
	v_mfma_f32_16x16x32_bf16 v[88:91], v[174:177], v[206:209], v[88:91]
	v_mfma_f32_16x16x32_bf16 v[80:83], v[182:185], v[206:209], v[80:83]
	v_mfma_f32_16x16x32_bf16 v[72:75], v[174:177], v[214:217], v[72:75]
	v_mfma_f32_16x16x32_bf16 v[64:67], v[182:185], v[214:217], v[64:67]
	s_setprio 0
	s_barrier
	s_add_i32 s30, s58, s50
	v_lshl_add_u64 v[144:145], s[46:47], 0, v[132:133]
	s_mov_b32 m0, s30
	ds_read_b128 v[186:189], v151 offset:16384
	ds_read_b128 v[190:193], v151 offset:17408
	ds_read_b128 v[194:197], v151 offset:18432
	ds_read_b128 v[198:201], v151 offset:19456
	ds_read_b128 v[202:205], v151 offset:20480
	ds_read_b128 v[206:209], v151 offset:21504
	ds_read_b128 v[210:213], v151 offset:22528
	ds_read_b128 v[214:217], v151 offset:23552
	global_load_lds_dwordx4 v[144:145], off
	s_add_i32 m0, s30, 0x2000
	s_add_u32 s30, s46, 0x40000
	v_lshl_add_u64 v[218:219], s[46:47], 0, v[128:129]
	s_addc_u32 s31, s47, 0
	s_add_i32 s67, s59, s50
	global_load_lds_dwordx4 v[218:219], off
	v_lshl_add_u64 v[220:221], s[30:31], 0, v[132:133]
	s_mov_b32 m0, s67
	v_lshl_add_u64 v[222:223], s[48:49], 0, v[130:131]
	global_load_lds_dwordx4 v[220:221], off
	v_lshl_add_u64 v[220:221], s[30:31], 0, v[128:129]
	s_add_i32 m0, s67, 0x2000
	s_nop 0
	global_load_lds_dwordx4 v[220:221], off
	v_lshl_add_u64 v[220:221], s[48:49], 0, v[134:135]
	s_mov_b32 m0, s43
	s_nop 0
	global_load_lds_dwordx4 v[220:221], off
	s_mov_b32 m0, s52
	s_nop 0
	global_load_lds_dwordx4 v[222:223], off
	s_waitcnt vmcnt(8)
	s_waitcnt lgkmcnt(0)
	s_barrier
; #define PG8_STAGE(bufoff, gbase, voff) do { _Pragma("unroll") for (int _i = 0; _i < 2; ++_i) \
;         __builtin_amdgcn_global_load_lds((const unsigned*)((const char*)(gbase) + (voff)[_i]), (PG8_LAS unsigned*)(lds + (bufoff) + ldsw + _i * 8192), 16, 0, 0); } while (0)
; #define PG8_LDA(dst, b, h) do { _Pragma("unroll") for (int m = 0; m < 4; ++m) _Pragma("unroll") for (int k = 0; k < 2; ++k) dst[m][k] = *(const PG8_LAS bf16x8*)(lds + PG8_SA(b, h) + aoff + m * 2048 + k * 1024); } while (0)
; #define PG8_LDB(dst, b, h) do { _Pragma("unroll") for (int n = 0; n < 2; ++n) _Pragma("unroll") for (int k = 0; k < 2; ++k) dst[n][k] = *(const PG8_LAS bf16x8*)(lds + PG8_SB(b, h) + boff + n * 2048 + k * 1024); } while (0)
; #define PG8_MMA(ai, bj, At, Bt) do { __builtin_amdgcn_s_setprio(1); _Pragma("unroll") for (int m = 0; m < 4; ++m) _Pragma("unroll") for (int n = 0; n < 2; ++n) _Pragma("unroll") for (int k = 0; k < 2; ++k) \
;         acc[ai][bj][m][n] = __builtin_amdgcn_mfma_f32_16x16x32_bf16(Bt[n][k], At[m][k], acc[ai][bj][m][n], 0, 0, 0); __builtin_amdgcn_s_setprio(0); } while (0)
; #define PG8_WAIT_V(n) asm volatile("s_waitcnt vmcnt(" #n ")" ::: "memory")
; #define PG8_WAIT_L(n) asm volatile("s_waitcnt lgkmcnt(" #n ")" ::: "memory")
; #define PG8_BAR __builtin_amdgcn_s_barrier()
; #define PG8_SCHED __builtin_amdgcn_sched_barrier(0)
; template <class Epi, class Sched, bool ALIGN_EPI = false, bool SP2 = false>
; __device__ __forceinline__ void gemm_phase(PG8_LAS unsigned char* lds, const Gemm g, const Sched& S, const Epi& E) {
;     ...
;             PG8_WAIT_V(8); PG8_WAIT_L(0); PG8_BAR; PG8_MMA(1, 0, At, B0); PG8_MMA(1, 1, At, B1); PG8_BAR; PG8_SCHED;
;             PG8_LDB(B0, 1, 0); PG8_LDB(B1, 1, 1); PG8_SCHED; PG8_LDA(At, 1, 0); PG8_STAGE(PG8_SA(0, 1), a2 + hstep, voffA);
;             PG8_WAIT_V(8); PG8_WAIT_L(0); PG8_BAR; PG8_MMA(0, 0, At, B0); PG8_MMA(0, 1, At, B1); PG8_BAR; PG8_SCHED;
	s_setprio 1
	s_waitcnt lgkmcnt(0)
	v_mfma_f32_16x16x32_bf16 v[60:63], v[154:157], v[186:189], 0
	v_mfma_f32_16x16x32_bf16 v[52:55], v[162:165], v[186:189], 0
	v_mfma_f32_16x16x32_bf16 v[44:47], v[154:157], v[194:197], 0
	v_mfma_f32_16x16x32_bf16 v[36:39], v[162:165], v[194:197], 0
	v_mfma_f32_16x16x32_bf16 v[28:31], v[154:157], v[202:205], 0
	v_mfma_f32_16x16x32_bf16 v[20:23], v[162:165], v[202:205], 0
	v_mfma_f32_16x16x32_bf16 v[12:15], v[154:157], v[210:213], 0
	v_mfma_f32_16x16x32_bf16 v[4:7], v[162:165], v[210:213], 0
	v_mfma_f32_16x16x32_bf16 v[60:63], v[158:161], v[190:193], v[60:63]
	v_mfma_f32_16x16x32_bf16 v[52:55], v[166:169], v[190:193], v[52:55]
	v_mfma_f32_16x16x32_bf16 v[44:47], v[158:161], v[198:201], v[44:47]
	v_mfma_f32_16x16x32_bf16 v[36:39], v[166:169], v[198:201], v[36:39]
	v_mfma_f32_16x16x32_bf16 v[28:31], v[158:161], v[206:209], v[28:31]
	v_mfma_f32_16x16x32_bf16 v[20:23], v[166:169], v[206:209], v[20:23]
	v_mfma_f32_16x16x32_bf16 v[12:15], v[158:161], v[214:217], v[12:15]
	v_mfma_f32_16x16x32_bf16 v[4:7], v[166:169], v[214:217], v[4:7]
	s_setprio 0
	s_setprio 1
	v_mfma_f32_16x16x32_bf16 v[56:59], v[170:173], v[186:189], 0
	v_mfma_f32_16x16x32_bf16 v[48:51], v[178:181], v[186:189], 0
	v_mfma_f32_16x16x32_bf16 v[40:43], v[170:173], v[194:197], 0
	v_mfma_f32_16x16x32_bf16 v[32:35], v[178:181], v[194:197], 0
	v_mfma_f32_16x16x32_bf16 v[24:27], v[170:173], v[202:205], 0
	v_mfma_f32_16x16x32_bf16 v[16:19], v[178:181], v[202:205], 0
	v_mfma_f32_16x16x32_bf16 v[8:11], v[170:173], v[210:213], 0
	v_mfma_f32_16x16x32_bf16 v[0:3], v[178:181], v[210:213], 0
	v_mfma_f32_16x16x32_bf16 v[56:59], v[174:177], v[190:193], v[56:59]
	v_mfma_f32_16x16x32_bf16 v[48:51], v[182:185], v[190:193], v[48:51]
	v_mfma_f32_16x16x32_bf16 v[40:43], v[174:177], v[198:201], v[40:43]
	v_mfma_f32_16x16x32_bf16 v[32:35], v[182:185], v[198:201], v[32:35]
	v_mfma_f32_16x16x32_bf16 v[24:27], v[174:177], v[206:209], v[24:27]
	v_mfma_f32_16x16x32_bf16 v[16:19], v[182:185], v[206:209], v[16:19]
	v_mfma_f32_16x16x32_bf16 v[8:11], v[174:177], v[214:217], v[8:11]
	v_mfma_f32_16x16x32_bf16 v[0:3], v[182:185], v[214:217], v[0:3]
	s_setprio 0
	s_barrier
	s_add_i32 s67, 0, 0x18000
	v_add_u32_e32 v153, s67, v147
	s_add_i32 s68, 0, 0x1c000
	ds_read_b128 v[154:157], v153
	ds_read_b128 v[158:161], v153 offset:1024
	ds_read_b128 v[162:165], v153 offset:2048
	ds_read_b128 v[166:169], v153 offset:3072
	v_add_u32_e32 v153, s68, v147
	ds_read_b128 v[170:173], v153
	ds_read_b128 v[174:177], v153 offset:1024
	ds_read_b128 v[178:181], v153 offset:2048
	ds_read_b128 v[182:185], v153 offset:3072
	s_add_u32 s30, s48, 0x40000
	s_addc_u32 s31, s49, 0
	s_mov_b32 m0, s53
	v_lshl_add_u64 v[224:225], s[30:31], 0, v[134:135]
	ds_read_b128 v[186:189], v151 offset:32768
	ds_read_b128 v[190:193], v151 offset:33792
	ds_read_b128 v[194:197], v151 offset:34816
	ds_read_b128 v[198:201], v151 offset:35840
	ds_read_b128 v[202:205], v151 offset:36864
	ds_read_b128 v[206:209], v151 offset:37888
	ds_read_b128 v[210:213], v151 offset:38912
	ds_read_b128 v[214:217], v151 offset:39936
	global_load_lds_dwordx4 v[224:225], off
	v_lshl_add_u64 v[224:225], s[30:31], 0, v[130:131]
	s_mov_b32 m0, s54
	s_nop 0
	global_load_lds_dwordx4 v[224:225], off
	s_waitcnt vmcnt(8)
	s_waitcnt lgkmcnt(0)
	s_barrier
	s_setprio 1
	s_waitcnt lgkmcnt(0)
	v_mfma_f32_16x16x32_bf16 v[116:119], v[154:157], v[186:189], v[116:119]
	v_mfma_f32_16x16x32_bf16 v[112:115], v[162:165], v[186:189], v[112:115]
	v_mfma_f32_16x16x32_bf16 v[108:111], v[154:157], v[194:197], v[108:111]
	v_mfma_f32_16x16x32_bf16 v[100:103], v[162:165], v[194:197], v[100:103]
	v_mfma_f32_16x16x32_bf16 v[92:95], v[154:157], v[202:205], v[92:95]
	v_mfma_f32_16x16x32_bf16 v[84:87], v[162:165], v[202:205], v[84:87]
	v_mfma_f32_16x16x32_bf16 v[76:79], v[154:157], v[210:213], v[76:79]
	v_mfma_f32_16x16x32_bf16 v[68:71], v[162:165], v[210:213], v[68:71]
	v_mfma_f32_16x16x32_bf16 v[116:119], v[158:161], v[190:193], v[116:119]
	v_mfma_f32_16x16x32_bf16 v[112:115], v[166:169], v[190:193], v[112:115]
	v_mfma_f32_16x16x32_bf16 v[108:111], v[158:161], v[198:201], v[108:111]
	v_mfma_f32_16x16x32_bf16 v[100:103], v[166:169], v[198:201], v[100:103]
	v_mfma_f32_16x16x32_bf16 v[92:95], v[158:161], v[206:209], v[92:95]
	v_mfma_f32_16x16x32_bf16 v[84:87], v[166:169], v[206:209], v[84:87]
	v_mfma_f32_16x16x32_bf16 v[76:79], v[158:161], v[214:217], v[76:79]
	v_mfma_f32_16x16x32_bf16 v[68:71], v[166:169], v[214:217], v[68:71]
	s_setprio 0
	s_setprio 1
	v_mfma_f32_16x16x32_bf16 v[124:127], v[170:173], v[186:189], v[124:127]
	v_mfma_f32_16x16x32_bf16 v[120:123], v[178:181], v[186:189], v[120:123]
	v_mfma_f32_16x16x32_bf16 v[104:107], v[170:173], v[194:197], v[104:107]
	v_mfma_f32_16x16x32_bf16 v[96:99], v[178:181], v[194:197], v[96:99]
	v_mfma_f32_16x16x32_bf16 v[88:91], v[170:173], v[202:205], v[88:91]
	v_mfma_f32_16x16x32_bf16 v[80:83], v[178:181], v[202:205], v[80:83]
	v_mfma_f32_16x16x32_bf16 v[72:75], v[170:173], v[210:213], v[72:75]
	v_mfma_f32_16x16x32_bf16 v[64:67], v[178:181], v[210:213], v[64:67]
	v_mfma_f32_16x16x32_bf16 v[124:127], v[174:177], v[190:193], v[124:127]
	v_mfma_f32_16x16x32_bf16 v[120:123], v[182:185], v[190:193], v[120:123]
	v_mfma_f32_16x16x32_bf16 v[104:107], v[174:177], v[198:201], v[104:107]
	v_mfma_f32_16x16x32_bf16 v[96:99], v[182:185], v[198:201], v[96:99]
	v_mfma_f32_16x16x32_bf16 v[88:91], v[174:177], v[206:209], v[88:91]
	v_mfma_f32_16x16x32_bf16 v[80:83], v[182:185], v[206:209], v[80:83]
	v_mfma_f32_16x16x32_bf16 v[72:75], v[174:177], v[214:217], v[72:75]
	v_mfma_f32_16x16x32_bf16 v[64:67], v[182:185], v[214:217], v[64:67]
	s_setprio 0
	s_barrier
; #define PG8_STAGE(bufoff, gbase, voff) do { _Pragma("unroll") for (int _i = 0; _i < 2; ++_i) \
;         __builtin_amdgcn_global_load_lds((const unsigned*)((const char*)(gbase) + (voff)[_i]), (PG8_LAS unsigned*)(lds + (bufoff) + ldsw + _i * 8192), 16, 0, 0); } while (0)
; #define PG8_LDA(dst, b, h) do { _Pragma("unroll") for (int m = 0; m < 4; ++m) _Pragma("unroll") for (int k = 0; k < 2; ++k) dst[m][k] = *(const PG8_LAS bf16x8*)(lds + PG8_SA(b, h) + aoff + m * 2048 + k * 1024); } while (0)
; #define PG8_MMA(ai, bj, At, Bt) do { __builtin_amdgcn_s_setprio(1); _Pragma("unroll") for (int m = 0; m < 4; ++m) _Pragma("unroll") for (int n = 0; n < 2; ++n) _Pragma("unroll") for (int k = 0; k < 2; ++k) \
;         acc[ai][bj][m][n] = __builtin_amdgcn_mfma_f32_16x16x32_bf16(Bt[n][k], At[m][k], acc[ai][bj][m][n], 0, 0, 0); __builtin_amdgcn_s_setprio(0); } while (0)
; #define PG8_WAIT_V(n) asm volatile("s_waitcnt vmcnt(" #n ")" ::: "memory")
; #define PG8_WAIT_L(n) asm volatile("s_waitcnt lgkmcnt(" #n ")" ::: "memory")
; #define PG8_BAR __builtin_amdgcn_s_barrier()
; #define PG8_SCHED __builtin_amdgcn_sched_barrier(0)
; template <class Epi, class Sched, bool ALIGN_EPI = false, bool SP2 = false>
; __device__ __forceinline__ void gemm_phase(PG8_LAS unsigned char* lds, const Gemm g, const Sched& S, const Epi& E) {
;     ...
;         for (int t = 0; t < nt; t += 2) {
;     ...
;             PG8_LDA(At, 1, 1); PG8_STAGE(PG8_SB(1, 0), b3, voffB); PG8_STAGE(PG8_SB(1, 1), b3 + hstep, voffB); PG8_STAGE(PG8_SA(1, 0), a3, voffA);
;             PG8_WAIT_V(8); PG8_WAIT_L(0); PG8_BAR; PG8_MMA(1, 0, At, B0); PG8_MMA(1, 1, At, B1); PG8_BAR; PG8_SCHED;
	s_add_i32 s30, s67, s50
	v_lshl_add_u64 v[144:145], v[144:145], 0, s[16:17]
	s_mov_b32 m0, s30
	ds_read_b128 v[186:189], v151 offset:49152
	ds_read_b128 v[190:193], v151 offset:50176
	ds_read_b128 v[194:197], v151 offset:51200
	ds_read_b128 v[198:201], v151 offset:52224
	ds_read_b128 v[202:205], v151 offset:53248
	ds_read_b128 v[206:209], v151 offset:54272
	ds_read_b128 v[210:213], v151 offset:55296
	ds_read_b128 v[214:217], v151 offset:56320
	global_load_lds_dwordx4 v[144:145], off
	s_add_i32 m0, s30, 0x2000
	s_add_u32 s30, s46, 0x40080
	v_lshl_add_u64 v[144:145], v[218:219], 0, s[16:17]
	s_addc_u32 s31, s47, 0
	s_add_i32 s46, s68, s50
	global_load_lds_dwordx4 v[144:145], off
	v_lshl_add_u64 v[144:145], s[30:31], 0, v[132:133]
	s_mov_b32 m0, s46
	s_nop 0
	global_load_lds_dwordx4 v[144:145], off
	v_lshl_add_u64 v[144:145], s[30:31], 0, v[128:129]
	s_add_i32 m0, s46, 0x2000
	s_nop 0
	global_load_lds_dwordx4 v[144:145], off
	v_lshl_add_u64 v[144:145], v[220:221], 0, s[16:17]
	s_mov_b32 m0, s56
	s_nop 0
	global_load_lds_dwordx4 v[144:145], off
	v_lshl_add_u64 v[144:145], v[222:223], 0, s[16:17]
	s_mov_b32 m0, s57
	s_nop 0
	global_load_lds_dwordx4 v[144:145], off
	s_waitcnt vmcnt(8)
	s_waitcnt lgkmcnt(0)
	s_barrier
	s_setprio 1
	s_waitcnt lgkmcnt(0)
	v_mfma_f32_16x16x32_bf16 v[60:63], v[154:157], v[186:189], v[60:63]
	v_mfma_f32_16x16x32_bf16 v[52:55], v[162:165], v[186:189], v[52:55]
	v_mfma_f32_16x16x32_bf16 v[44:47], v[154:157], v[194:197], v[44:47]
	v_mfma_f32_16x16x32_bf16 v[36:39], v[162:165], v[194:197], v[36:39]
	v_mfma_f32_16x16x32_bf16 v[28:31], v[154:157], v[202:205], v[28:31]
	v_mfma_f32_16x16x32_bf16 v[20:23], v[162:165], v[202:205], v[20:23]
	v_mfma_f32_16x16x32_bf16 v[12:15], v[154:157], v[210:213], v[12:15]
	v_mfma_f32_16x16x32_bf16 v[4:7], v[162:165], v[210:213], v[4:7]
	v_mfma_f32_16x16x32_bf16 v[60:63], v[158:161], v[190:193], v[60:63]
	v_mfma_f32_16x16x32_bf16 v[52:55], v[166:169], v[190:193], v[52:55]
	v_mfma_f32_16x16x32_bf16 v[44:47], v[158:161], v[198:201], v[44:47]
	v_mfma_f32_16x16x32_bf16 v[36:39], v[166:169], v[198:201], v[36:39]
	v_mfma_f32_16x16x32_bf16 v[28:31], v[158:161], v[206:209], v[28:31]
	v_mfma_f32_16x16x32_bf16 v[20:23], v[166:169], v[206:209], v[20:23]
	v_mfma_f32_16x16x32_bf16 v[12:15], v[158:161], v[214:217], v[12:15]
	v_mfma_f32_16x16x32_bf16 v[4:7], v[166:169], v[214:217], v[4:7]
	s_setprio 0
	s_setprio 1
	v_mfma_f32_16x16x32_bf16 v[56:59], v[170:173], v[186:189], v[56:59]
	v_mfma_f32_16x16x32_bf16 v[48:51], v[178:181], v[186:189], v[48:51]
	v_mfma_f32_16x16x32_bf16 v[40:43], v[170:173], v[194:197], v[40:43]
	v_mfma_f32_16x16x32_bf16 v[32:35], v[178:181], v[194:197], v[32:35]
	v_mfma_f32_16x16x32_bf16 v[24:27], v[170:173], v[202:205], v[24:27]
	v_mfma_f32_16x16x32_bf16 v[16:19], v[178:181], v[202:205], v[16:19]
	v_mfma_f32_16x16x32_bf16 v[8:11], v[170:173], v[210:213], v[8:11]
	v_mfma_f32_16x16x32_bf16 v[0:3], v[178:181], v[210:213], v[0:3]
	v_mfma_f32_16x16x32_bf16 v[56:59], v[174:177], v[190:193], v[56:59]
	v_mfma_f32_16x16x32_bf16 v[48:51], v[182:185], v[190:193], v[48:51]
	v_mfma_f32_16x16x32_bf16 v[40:43], v[174:177], v[198:201], v[40:43]
	v_mfma_f32_16x16x32_bf16 v[32:35], v[182:185], v[198:201], v[32:35]
	v_mfma_f32_16x16x32_bf16 v[24:27], v[174:177], v[206:209], v[24:27]
	v_mfma_f32_16x16x32_bf16 v[16:19], v[182:185], v[206:209], v[16:19]
	v_mfma_f32_16x16x32_bf16 v[8:11], v[174:177], v[214:217], v[8:11]
	v_mfma_f32_16x16x32_bf16 v[0:3], v[182:185], v[214:217], v[0:3]
	s_setprio 0
	s_barrier
	s_add_i32 s66, s66, 2
	s_add_u32 s44, s44, 0x100
	s_addc_u32 s45, s45, 0
	s_add_u32 s64, s64, 0x100
	s_addc_u32 s65, s65, 0
	s_cmp_gt_u32 s66, 13
	s_cbranch_scc0 .LBB0_1385
	s_branch .Lgx_g7

; #define PG8_STAGE(bufoff, gbase, voff) do { _Pragma("unroll") for (int _i = 0; _i < 2; ++_i) \
;         __builtin_amdgcn_global_load_lds((const unsigned*)((const char*)(gbase) + (voff)[_i]), (PG8_LAS unsigned*)(lds + (bufoff) + ldsw + _i * 8192), 16, 0, 0); } while (0)
; #define PG8_LDA(dst, b, h) do { _Pragma("unroll") for (int m = 0; m < 4; ++m) _Pragma("unroll") for (int k = 0; k < 2; ++k) dst[m][k] = *(const PG8_LAS bf16x8*)(lds + PG8_SA(b, h) + aoff + m * 2048 + k * 1024); } while (0)
; #define PG8_LDB(dst, b, h) do { _Pragma("unroll") for (int n = 0; n < 2; ++n) _Pragma("unroll") for (int k = 0; k < 2; ++k) dst[n][k] = *(const PG8_LAS bf16x8*)(lds + PG8_SB(b, h) + boff + n * 2048 + k * 1024); } while (0)
; #define PG8_MMA(ai, bj, At, Bt) do { __builtin_amdgcn_s_setprio(1); _Pragma("unroll") for (int m = 0; m < 4; ++m) _Pragma("unroll") for (int n = 0; n < 2; ++n) _Pragma("unroll") for (int k = 0; k < 2; ++k) \
;         acc[ai][bj][m][n] = __builtin_amdgcn_mfma_f32_16x16x32_bf16(Bt[n][k], At[m][k], acc[ai][bj][m][n], 0, 0, 0); __builtin_amdgcn_s_setprio(0); } while (0)
; template <class Epi, class Sched, bool ALIGN_EPI = false, bool SP2 = false>
; __device__ __forceinline__ void gemm_phase(PG8_LAS unsigned char* lds, const Gemm g, const Sched& S, const Epi& E) {
;     ...
;         const bool has_next = S.next(ui + 1, nxt);
;         const char* nA = has_next ? (const char*)g.A + (size_t)nxt.pm * tstep : cA; const char* nB = has_next ? (const char*)g.Bt + (size_t)nxt.pn * tstep : cB;
; #pragma unroll 1
;         for (int t = 0; t < nt; t += 2) {
;             const bool last = (t == nt - 2);
;             const char* a1 = cA + (size_t)(t + 1) * kstep;
;             const char* a2 = last ? nA : cA + (size_t)(t + 2) * kstep; const char* b2 = last ? nB : cB + (size_t)(t + 2) * kstep;
;             const char* a3 = a2 + kstep; const char* b3 = b2 + kstep;
;             if (last && has_next) S.a_ready(nxt);
;             if constexpr (SP2) {
;             PG8_LDB(B0, 0, 0); PG8_LDB(B1, 0, 1); PG8_SCHED; PG8_LDA(At, 0, 0); PG8_STAGE(PG8_SA(1, 1), a1 + hstep, voffA);
;             PG8_WAIT_V(8); PG8_WAIT_L(0); PG8_BAR; PG8_MMA(0, 0, At, B0); PG8_MMA(0, 1, At, B1); PG8_BAR; PG8_SCHED;
;             PG8_LDA(At, 0, 1); PG8_STAGE(PG8_SB(0, 0), b2, voffB); PG8_STAGE(PG8_SB(0, 1), b2 + hstep, voffB); PG8_STAGE(PG8_SA(0, 0), a2, voffA);
.LBB0_1468:
	s_add_u32 s68, s46, 0x100
	v_mov_b32_e32 v0, 0
	s_addc_u32 s69, s47, 0
	s_mov_b32 s70, -2
	ds_read_b128 v[112:115], v246
	ds_read_b128 v[120:123], v246 offset:1024
	ds_read_b128 v[124:127], v246 offset:2048
	ds_read_b128 v[128:131], v246 offset:3072
	ds_read_b128 v[136:139], v247
	ds_read_b128 v[140:143], v247 offset:1024
	ds_read_b128 v[144:147], v247 offset:2048
	ds_read_b128 v[156:159], v247 offset:3072
	s_add_u32 s46, s44, 0x100
	s_addc_u32 s47, s45, 0
	s_cmp_eq_u32 s70, 40
	s_cselect_b32 s51, s9, s47
	s_cselect_b32 s50, s8, s46
	s_cselect_b32 s49, s43, s69
	s_cselect_b32 s48, s42, s68
	v_lshl_add_u64 v[206:207], s[44:45], 0, v[200:201]
	s_add_i32 m0, s1, 0xc000
	ds_read_b128 v[160:163], v248
	ds_read_b128 v[164:167], v248 offset:1024
	ds_read_b128 v[168:171], v248 offset:2048
	ds_read_b128 v[172:175], v248 offset:3072
	ds_read_b128 v[176:179], v248 offset:4096
	ds_read_b128 v[180:183], v248 offset:5120
	ds_read_b128 v[184:187], v248 offset:6144
	ds_read_b128 v[188:191], v248 offset:7168
	global_load_lds_dwordx4 v[206:207], off
	v_lshl_add_u64 v[206:207], s[44:45], 0, v[202:203]
	s_add_i32 m0, s1, 0xe000
	s_nop 0
	global_load_lds_dwordx4 v[206:207], off
	s_waitcnt vmcnt(8)
	s_waitcnt lgkmcnt(0)
	s_barrier
	s_setprio 1
	s_waitcnt lgkmcnt(0)
	v_mfma_f32_16x16x32_bf16 v[152:155], v[112:115], v[160:163], 0
	v_mfma_f32_16x16x32_bf16 v[148:151], v[124:127], v[160:163], 0
	v_mfma_f32_16x16x32_bf16 v[108:111], v[112:115], v[168:171], 0
	v_mfma_f32_16x16x32_bf16 v[104:107], v[124:127], v[168:171], 0
	v_mfma_f32_16x16x32_bf16 v[92:95], v[112:115], v[176:179], 0
	v_mfma_f32_16x16x32_bf16 v[88:91], v[124:127], v[176:179], 0
	v_mfma_f32_16x16x32_bf16 v[76:79], v[112:115], v[184:187], 0
	v_mfma_f32_16x16x32_bf16 v[72:75], v[124:127], v[184:187], 0
	v_mfma_f32_16x16x32_bf16 v[152:155], v[120:123], v[164:167], v[152:155]
	v_mfma_f32_16x16x32_bf16 v[148:151], v[128:131], v[164:167], v[148:151]
	v_mfma_f32_16x16x32_bf16 v[108:111], v[120:123], v[172:175], v[108:111]
	v_mfma_f32_16x16x32_bf16 v[104:107], v[128:131], v[172:175], v[104:107]
	v_mfma_f32_16x16x32_bf16 v[92:95], v[120:123], v[180:183], v[92:95]
	v_mfma_f32_16x16x32_bf16 v[88:91], v[128:131], v[180:183], v[88:91]
	v_mfma_f32_16x16x32_bf16 v[76:79], v[120:123], v[188:191], v[76:79]
	v_mfma_f32_16x16x32_bf16 v[72:75], v[128:131], v[188:191], v[72:75]
	s_setprio 0
	s_setprio 1
	v_mfma_f32_16x16x32_bf16 v[132:135], v[136:139], v[160:163], 0
	v_mfma_f32_16x16x32_bf16 v[116:119], v[144:147], v[160:163], 0
	v_mfma_f32_16x16x32_bf16 v[100:103], v[136:139], v[168:171], 0
	v_mfma_f32_16x16x32_bf16 v[96:99], v[144:147], v[168:171], 0
	v_mfma_f32_16x16x32_bf16 v[84:87], v[136:139], v[176:179], 0
	v_mfma_f32_16x16x32_bf16 v[80:83], v[144:147], v[176:179], 0
	v_mfma_f32_16x16x32_bf16 v[68:71], v[136:139], v[184:187], 0
	v_mfma_f32_16x16x32_bf16 v[64:67], v[144:147], v[184:187], 0
	v_mfma_f32_16x16x32_bf16 v[132:135], v[140:143], v[164:167], v[132:135]
	v_mfma_f32_16x16x32_bf16 v[116:119], v[156:159], v[164:167], v[116:119]
	v_mfma_f32_16x16x32_bf16 v[100:103], v[140:143], v[172:175], v[100:103]
	v_mfma_f32_16x16x32_bf16 v[96:99], v[156:159], v[172:175], v[96:99]
	v_mfma_f32_16x16x32_bf16 v[84:87], v[140:143], v[180:183], v[84:87]
	v_mfma_f32_16x16x32_bf16 v[80:83], v[156:159], v[180:183], v[80:83]
	v_mfma_f32_16x16x32_bf16 v[68:71], v[140:143], v[188:191], v[68:71]
	v_mfma_f32_16x16x32_bf16 v[64:67], v[156:159], v[188:191], v[64:67]
	s_setprio 0
	s_barrier
	s_add_i32 s30, s62, s0
	v_lshl_add_u64 v[206:207], s[48:49], 0, v[194:195]
	s_mov_b32 m0, s30
	ds_read_b128 v[160:163], v248 offset:16384
	ds_read_b128 v[164:167], v248 offset:17408
	ds_read_b128 v[168:171], v248 offset:18432
	ds_read_b128 v[172:175], v248 offset:19456
	ds_read_b128 v[176:179], v248 offset:20480
	ds_read_b128 v[180:183], v248 offset:21504
	ds_read_b128 v[184:187], v248 offset:22528
	ds_read_b128 v[188:191], v248 offset:23552
	global_load_lds_dwordx4 v[206:207], off
	s_add_i32 m0, s30, 0x2000
	s_add_u32 s30, s48, 0xb0000
	v_lshl_add_u64 v[208:209], s[48:49], 0, v[198:199]
	s_addc_u32 s31, s49, 0
	s_add_i32 s44, s63, s0
	global_load_lds_dwordx4 v[208:209], off
	v_lshl_add_u64 v[210:211], s[30:31], 0, v[194:195]
	s_mov_b32 m0, s44
	v_lshl_add_u64 v[212:213], s[50:51], 0, v[196:197]
	global_load_lds_dwordx4 v[210:211], off
	v_lshl_add_u64 v[210:211], s[30:31], 0, v[198:199]
	s_add_i32 m0, s44, 0x2000
	s_nop 0
	global_load_lds_dwordx4 v[210:211], off
	v_lshl_add_u64 v[210:211], s[50:51], 0, v[192:193]
	s_mov_b32 m0, s1
	s_nop 0
	global_load_lds_dwordx4 v[210:211], off
	s_mov_b32 m0, s56
	s_nop 0
	global_load_lds_dwordx4 v[212:213], off
	s_waitcnt vmcnt(8)
	s_waitcnt lgkmcnt(0)
	s_barrier
; #define PG8_STAGE(bufoff, gbase, voff) do { _Pragma("unroll") for (int _i = 0; _i < 2; ++_i) \
;         __builtin_amdgcn_global_load_lds((const unsigned*)((const char*)(gbase) + (voff)[_i]), (PG8_LAS unsigned*)(lds + (bufoff) + ldsw + _i * 8192), 16, 0, 0); } while (0)
; #define PG8_LDA(dst, b, h) do { _Pragma("unroll") for (int m = 0; m < 4; ++m) _Pragma("unroll") for (int k = 0; k < 2; ++k) dst[m][k] = *(const PG8_LAS bf16x8*)(lds + PG8_SA(b, h) + aoff + m * 2048 + k * 1024); } while (0)
; #define PG8_LDB(dst, b, h) do { _Pragma("unroll") for (int n = 0; n < 2; ++n) _Pragma("unroll") for (int k = 0; k < 2; ++k) dst[n][k] = *(const PG8_LAS bf16x8*)(lds + PG8_SB(b, h) + boff + n * 2048 + k * 1024); } while (0)
; #define PG8_MMA(ai, bj, At, Bt) do { __builtin_amdgcn_s_setprio(1); _Pragma("unroll") for (int m = 0; m < 4; ++m) _Pragma("unroll") for (int n = 0; n < 2; ++n) _Pragma("unroll") for (int k = 0; k < 2; ++k) \
;         acc[ai][bj][m][n] = __builtin_amdgcn_mfma_f32_16x16x32_bf16(Bt[n][k], At[m][k], acc[ai][bj][m][n], 0, 0, 0); __builtin_amdgcn_s_setprio(0); } while (0)
; #define PG8_WAIT_V(n) asm volatile("s_waitcnt vmcnt(" #n ")" ::: "memory")
; #define PG8_WAIT_L(n) asm volatile("s_waitcnt lgkmcnt(" #n ")" ::: "memory")
; #define PG8_BAR __builtin_amdgcn_s_barrier()
; #define PG8_SCHED __builtin_amdgcn_sched_barrier(0)
; template <class Epi, class Sched, bool ALIGN_EPI = false, bool SP2 = false>
; __device__ __forceinline__ void gemm_phase(PG8_LAS unsigned char* lds, const Gemm g, const Sched& S, const Epi& E) {
;     ...
;             PG8_WAIT_V(8); PG8_WAIT_L(0); PG8_BAR; PG8_MMA(1, 0, At, B0); PG8_MMA(1, 1, At, B1); PG8_BAR; PG8_SCHED;
;             PG8_LDB(B0, 1, 0); PG8_LDB(B1, 1, 1); PG8_SCHED; PG8_LDA(At, 1, 0); PG8_STAGE(PG8_SA(0, 1), a2 + hstep, voffA);
;             PG8_WAIT_V(8); PG8_WAIT_L(0); PG8_BAR; PG8_MMA(0, 0, At, B0); PG8_MMA(0, 1, At, B1); PG8_BAR; PG8_SCHED;
	s_setprio 1
	s_waitcnt lgkmcnt(0)
	v_mfma_f32_16x16x32_bf16 v[60:63], v[112:115], v[160:163], 0
	v_mfma_f32_16x16x32_bf16 v[56:59], v[124:127], v[160:163], 0
	v_mfma_f32_16x16x32_bf16 v[44:47], v[112:115], v[168:171], 0
	v_mfma_f32_16x16x32_bf16 v[40:43], v[124:127], v[168:171], 0
	v_mfma_f32_16x16x32_bf16 v[28:31], v[112:115], v[176:179], 0
	v_mfma_f32_16x16x32_bf16 v[24:27], v[124:127], v[176:179], 0
	v_mfma_f32_16x16x32_bf16 v[12:15], v[112:115], v[184:187], 0
	v_mfma_f32_16x16x32_bf16 v[8:11], v[124:127], v[184:187], 0
	v_mfma_f32_16x16x32_bf16 v[60:63], v[120:123], v[164:167], v[60:63]
	v_mfma_f32_16x16x32_bf16 v[56:59], v[128:131], v[164:167], v[56:59]
	v_mfma_f32_16x16x32_bf16 v[44:47], v[120:123], v[172:175], v[44:47]
	v_mfma_f32_16x16x32_bf16 v[40:43], v[128:131], v[172:175], v[40:43]
	v_mfma_f32_16x16x32_bf16 v[28:31], v[120:123], v[180:183], v[28:31]
	v_mfma_f32_16x16x32_bf16 v[24:27], v[128:131], v[180:183], v[24:27]
	v_mfma_f32_16x16x32_bf16 v[12:15], v[120:123], v[188:191], v[12:15]
	v_mfma_f32_16x16x32_bf16 v[8:11], v[128:131], v[188:191], v[8:11]
	s_setprio 0
	s_setprio 1
	v_mfma_f32_16x16x32_bf16 v[52:55], v[136:139], v[160:163], 0
	v_mfma_f32_16x16x32_bf16 v[48:51], v[144:147], v[160:163], 0
	v_mfma_f32_16x16x32_bf16 v[36:39], v[136:139], v[168:171], 0
	v_mfma_f32_16x16x32_bf16 v[32:35], v[144:147], v[168:171], 0
	v_mfma_f32_16x16x32_bf16 v[20:23], v[136:139], v[176:179], 0
	v_mfma_f32_16x16x32_bf16 v[16:19], v[144:147], v[176:179], 0
	v_mfma_f32_16x16x32_bf16 v[4:7], v[136:139], v[184:187], 0
	v_mfma_f32_16x16x32_bf16 v[0:3], v[144:147], v[184:187], 0
	v_mfma_f32_16x16x32_bf16 v[52:55], v[140:143], v[164:167], v[52:55]
	v_mfma_f32_16x16x32_bf16 v[48:51], v[156:159], v[164:167], v[48:51]
	v_mfma_f32_16x16x32_bf16 v[36:39], v[140:143], v[172:175], v[36:39]
	v_mfma_f32_16x16x32_bf16 v[32:35], v[156:159], v[172:175], v[32:35]
	v_mfma_f32_16x16x32_bf16 v[20:23], v[140:143], v[180:183], v[20:23]
	v_mfma_f32_16x16x32_bf16 v[16:19], v[156:159], v[180:183], v[16:19]
	v_mfma_f32_16x16x32_bf16 v[4:7], v[140:143], v[188:191], v[4:7]
	v_mfma_f32_16x16x32_bf16 v[0:3], v[156:159], v[188:191], v[0:3]
	s_setprio 0
	s_barrier
	s_add_i32 s44, 0, 0x18000
	s_add_i32 s45, 0, 0x1c000
	v_add_u32_e32 v128, s44, v244
	v_add_u32_e32 v156, s45, v244
	ds_read_b128 v[112:115], v128
	ds_read_b128 v[120:123], v128 offset:1024
	ds_read_b128 v[124:127], v128 offset:2048
	ds_read_b128 v[128:131], v128 offset:3072
	ds_read_b128 v[136:139], v156
	ds_read_b128 v[140:143], v156 offset:1024
	ds_read_b128 v[144:147], v156 offset:2048
	ds_read_b128 v[156:159], v156 offset:3072
	s_add_u32 s30, s50, 0xb0000
	s_addc_u32 s31, s51, 0
	s_mov_b32 m0, s57
	v_lshl_add_u64 v[214:215], s[30:31], 0, v[192:193]
	ds_read_b128 v[160:163], v248 offset:32768
	ds_read_b128 v[164:167], v248 offset:33792
	ds_read_b128 v[168:171], v248 offset:34816
	ds_read_b128 v[172:175], v248 offset:35840
	ds_read_b128 v[176:179], v248 offset:36864
	ds_read_b128 v[180:183], v248 offset:37888
	ds_read_b128 v[184:187], v248 offset:38912
	ds_read_b128 v[188:191], v248 offset:39936
	global_load_lds_dwordx4 v[214:215], off
	v_lshl_add_u64 v[214:215], s[30:31], 0, v[196:197]
	s_mov_b32 m0, s58
	s_nop 0
	global_load_lds_dwordx4 v[214:215], off
	s_waitcnt vmcnt(8)
	s_waitcnt lgkmcnt(0)
	s_barrier
	s_setprio 1
	s_waitcnt lgkmcnt(0)
	v_mfma_f32_16x16x32_bf16 v[152:155], v[112:115], v[160:163], v[152:155]
	v_mfma_f32_16x16x32_bf16 v[148:151], v[124:127], v[160:163], v[148:151]
	v_mfma_f32_16x16x32_bf16 v[108:111], v[112:115], v[168:171], v[108:111]
	v_mfma_f32_16x16x32_bf16 v[104:107], v[124:127], v[168:171], v[104:107]
	v_mfma_f32_16x16x32_bf16 v[92:95], v[112:115], v[176:179], v[92:95]
	v_mfma_f32_16x16x32_bf16 v[88:91], v[124:127], v[176:179], v[88:91]
	v_mfma_f32_16x16x32_bf16 v[76:79], v[112:115], v[184:187], v[76:79]
	v_mfma_f32_16x16x32_bf16 v[72:75], v[124:127], v[184:187], v[72:75]
	v_mfma_f32_16x16x32_bf16 v[152:155], v[120:123], v[164:167], v[152:155]
	v_mfma_f32_16x16x32_bf16 v[148:151], v[128:131], v[164:167], v[148:151]
	v_mfma_f32_16x16x32_bf16 v[108:111], v[120:123], v[172:175], v[108:111]
	v_mfma_f32_16x16x32_bf16 v[104:107], v[128:131], v[172:175], v[104:107]
	v_mfma_f32_16x16x32_bf16 v[92:95], v[120:123], v[180:183], v[92:95]
	v_mfma_f32_16x16x32_bf16 v[88:91], v[128:131], v[180:183], v[88:91]
	v_mfma_f32_16x16x32_bf16 v[76:79], v[120:123], v[188:191], v[76:79]
	v_mfma_f32_16x16x32_bf16 v[72:75], v[128:131], v[188:191], v[72:75]
	s_setprio 0
	s_setprio 1
	v_mfma_f32_16x16x32_bf16 v[132:135], v[136:139], v[160:163], v[132:135]
	v_mfma_f32_16x16x32_bf16 v[116:119], v[144:147], v[160:163], v[116:119]
	v_mfma_f32_16x16x32_bf16 v[100:103], v[136:139], v[168:171], v[100:103]
	v_mfma_f32_16x16x32_bf16 v[96:99], v[144:147], v[168:171], v[96:99]
	v_mfma_f32_16x16x32_bf16 v[84:87], v[136:139], v[176:179], v[84:87]
	v_mfma_f32_16x16x32_bf16 v[80:83], v[144:147], v[176:179], v[80:83]
	v_mfma_f32_16x16x32_bf16 v[68:71], v[136:139], v[184:187], v[68:71]
	v_mfma_f32_16x16x32_bf16 v[64:67], v[144:147], v[184:187], v[64:67]
	v_mfma_f32_16x16x32_bf16 v[132:135], v[140:143], v[164:167], v[132:135]
	v_mfma_f32_16x16x32_bf16 v[116:119], v[156:159], v[164:167], v[116:119]
	v_mfma_f32_16x16x32_bf16 v[100:103], v[140:143], v[172:175], v[100:103]
	v_mfma_f32_16x16x32_bf16 v[96:99], v[156:159], v[172:175], v[96:99]
	v_mfma_f32_16x16x32_bf16 v[84:87], v[140:143], v[180:183], v[84:87]
	v_mfma_f32_16x16x32_bf16 v[80:83], v[156:159], v[180:183], v[80:83]
	v_mfma_f32_16x16x32_bf16 v[68:71], v[140:143], v[188:191], v[68:71]
	v_mfma_f32_16x16x32_bf16 v[64:67], v[156:159], v[188:191], v[64:67]
	s_setprio 0
	s_barrier
; #define PG8_STAGE(bufoff, gbase, voff) do { _Pragma("unroll") for (int _i = 0; _i < 2; ++_i) \
;         __builtin_amdgcn_global_load_lds((const unsigned*)((const char*)(gbase) + (voff)[_i]), (PG8_LAS unsigned*)(lds + (bufoff) + ldsw + _i * 8192), 16, 0, 0); } while (0)
; #define PG8_LDA(dst, b, h) do { _Pragma("unroll") for (int m = 0; m < 4; ++m) _Pragma("unroll") for (int k = 0; k < 2; ++k) dst[m][k] = *(const PG8_LAS bf16x8*)(lds + PG8_SA(b, h) + aoff + m * 2048 + k * 1024); } while (0)
; #define PG8_MMA(ai, bj, At, Bt) do { __builtin_amdgcn_s_setprio(1); _Pragma("unroll") for (int m = 0; m < 4; ++m) _Pragma("unroll") for (int n = 0; n < 2; ++n) _Pragma("unroll") for (int k = 0; k < 2; ++k) \
;         acc[ai][bj][m][n] = __builtin_amdgcn_mfma_f32_16x16x32_bf16(Bt[n][k], At[m][k], acc[ai][bj][m][n], 0, 0, 0); __builtin_amdgcn_s_setprio(0); } while (0)
; #define PG8_WAIT_V(n) asm volatile("s_waitcnt vmcnt(" #n ")" ::: "memory")
; #define PG8_WAIT_L(n) asm volatile("s_waitcnt lgkmcnt(" #n ")" ::: "memory")
; #define PG8_BAR __builtin_amdgcn_s_barrier()
; #define PG8_SCHED __builtin_amdgcn_sched_barrier(0)
; template <class Epi, class Sched, bool ALIGN_EPI = false, bool SP2 = false>
; __device__ __forceinline__ void gemm_phase(PG8_LAS unsigned char* lds, const Gemm g, const Sched& S, const Epi& E) {
;     ...
;         for (int t = 0; t < nt; t += 2) {
;     ...
;             PG8_LDA(At, 1, 1); PG8_STAGE(PG8_SB(1, 0), b3, voffB); PG8_STAGE(PG8_SB(1, 1), b3 + hstep, voffB); PG8_STAGE(PG8_SA(1, 0), a3, voffA);
;             PG8_WAIT_V(8); PG8_WAIT_L(0); PG8_BAR; PG8_MMA(1, 0, At, B0); PG8_MMA(1, 1, At, B1); PG8_BAR; PG8_SCHED;
	s_add_i32 s30, s44, s0
	v_lshl_add_u64 v[206:207], v[206:207], 0, s[38:39]
	s_mov_b32 m0, s30
	ds_read_b128 v[160:163], v248 offset:49152
	ds_read_b128 v[164:167], v248 offset:50176
	ds_read_b128 v[168:171], v248 offset:51200
	ds_read_b128 v[172:175], v248 offset:52224
	ds_read_b128 v[176:179], v248 offset:53248
	ds_read_b128 v[180:183], v248 offset:54272
	ds_read_b128 v[184:187], v248 offset:55296
	ds_read_b128 v[188:191], v248 offset:56320
	global_load_lds_dwordx4 v[206:207], off
	s_add_i32 m0, s30, 0x2000
	s_add_u32 s30, s48, 0xb0080
	v_lshl_add_u64 v[206:207], v[208:209], 0, s[38:39]
	s_addc_u32 s31, s49, 0
	s_add_i32 s44, s45, s0
	global_load_lds_dwordx4 v[206:207], off
	v_lshl_add_u64 v[206:207], s[30:31], 0, v[194:195]
	s_mov_b32 m0, s44
	s_nop 0
	global_load_lds_dwordx4 v[206:207], off
	v_lshl_add_u64 v[206:207], s[30:31], 0, v[198:199]
	s_add_i32 m0, s44, 0x2000
	s_nop 0
	global_load_lds_dwordx4 v[206:207], off
	v_lshl_add_u64 v[206:207], v[210:211], 0, s[38:39]
	s_mov_b32 m0, s60
	s_nop 0
	global_load_lds_dwordx4 v[206:207], off
	v_lshl_add_u64 v[206:207], v[212:213], 0, s[38:39]
	s_mov_b32 m0, s61
	s_nop 0
	global_load_lds_dwordx4 v[206:207], off
	s_waitcnt vmcnt(8)
	s_waitcnt lgkmcnt(0)
	s_barrier
	s_setprio 1
	s_waitcnt lgkmcnt(0)
	v_mfma_f32_16x16x32_bf16 v[60:63], v[112:115], v[160:163], v[60:63]
	v_mfma_f32_16x16x32_bf16 v[56:59], v[124:127], v[160:163], v[56:59]
	v_mfma_f32_16x16x32_bf16 v[44:47], v[112:115], v[168:171], v[44:47]
	v_mfma_f32_16x16x32_bf16 v[40:43], v[124:127], v[168:171], v[40:43]
	v_mfma_f32_16x16x32_bf16 v[28:31], v[112:115], v[176:179], v[28:31]
	v_mfma_f32_16x16x32_bf16 v[24:27], v[124:127], v[176:179], v[24:27]
	v_mfma_f32_16x16x32_bf16 v[12:15], v[112:115], v[184:187], v[12:15]
	v_mfma_f32_16x16x32_bf16 v[8:11], v[124:127], v[184:187], v[8:11]
	v_mfma_f32_16x16x32_bf16 v[60:63], v[120:123], v[164:167], v[60:63]
	v_mfma_f32_16x16x32_bf16 v[56:59], v[128:131], v[164:167], v[56:59]
	v_mfma_f32_16x16x32_bf16 v[44:47], v[120:123], v[172:175], v[44:47]
	v_mfma_f32_16x16x32_bf16 v[40:43], v[128:131], v[172:175], v[40:43]
	v_mfma_f32_16x16x32_bf16 v[28:31], v[120:123], v[180:183], v[28:31]
	v_mfma_f32_16x16x32_bf16 v[24:27], v[128:131], v[180:183], v[24:27]
	v_mfma_f32_16x16x32_bf16 v[12:15], v[120:123], v[188:191], v[12:15]
	v_mfma_f32_16x16x32_bf16 v[8:11], v[128:131], v[188:191], v[8:11]
	s_setprio 0
	s_setprio 1
	v_mfma_f32_16x16x32_bf16 v[52:55], v[136:139], v[160:163], v[52:55]
	v_mfma_f32_16x16x32_bf16 v[48:51], v[144:147], v[160:163], v[48:51]
	v_mfma_f32_16x16x32_bf16 v[36:39], v[136:139], v[168:171], v[36:39]
	v_mfma_f32_16x16x32_bf16 v[32:35], v[144:147], v[168:171], v[32:35]
	v_mfma_f32_16x16x32_bf16 v[20:23], v[136:139], v[176:179], v[20:23]
	v_mfma_f32_16x16x32_bf16 v[16:19], v[144:147], v[176:179], v[16:19]
	v_mfma_f32_16x16x32_bf16 v[4:7], v[136:139], v[184:187], v[4:7]
	v_mfma_f32_16x16x32_bf16 v[0:3], v[144:147], v[184:187], v[0:3]
	v_mfma_f32_16x16x32_bf16 v[52:55], v[140:143], v[164:167], v[52:55]
	v_mfma_f32_16x16x32_bf16 v[48:51], v[156:159], v[164:167], v[48:51]
	v_mfma_f32_16x16x32_bf16 v[36:39], v[140:143], v[172:175], v[36:39]
	v_mfma_f32_16x16x32_bf16 v[32:35], v[156:159], v[172:175], v[32:35]
	v_mfma_f32_16x16x32_bf16 v[20:23], v[140:143], v[180:183], v[20:23]
	v_mfma_f32_16x16x32_bf16 v[16:19], v[156:159], v[180:183], v[16:19]
	v_mfma_f32_16x16x32_bf16 v[4:7], v[140:143], v[188:191], v[4:7]
	v_mfma_f32_16x16x32_bf16 v[0:3], v[156:159], v[188:191], v[0:3]
	s_setprio 0
	s_barrier
	s_add_i32 s70, s70, 2
	s_add_u32 s68, s68, 0x100
	s_addc_u32 s69, s69, 0
	s_cmp_gt_u32 s70, 41
	s_mov_b64 s[44:45], s[46:47]
	s_cbranch_scc0 .LBB0_1469
	s_branch .Lgx_g8

; #define PG8_BAR __builtin_amdgcn_s_barrier()
; template <class Epi, class Sched, bool ALIGN_EPI = false, bool SP2 = false>
; __device__ __forceinline__ void gemm_phase(PG8_LAS unsigned char* lds, const Gemm g, const Sched& S, const Epi& E) {
;     ...
;         if constexpr (ALIGN_EPI) { if (wr == 0) PG8_BAR; }
.Lgx_g8:
	s_and_b64 vcc, exec, s[40:41]
	s_cbranch_vccz .LBB0_1472
	s_barrier
